# K-loops unrolled by 6 steps with constant ring-slot offsets, uniform setprio 2, exit check once per 2 steps (less scalar overhead per K-step)
# speedup vs baseline: 1.0076x; 1.0076x over previous
; __device__ __forceinline__ f32x4 mfma16(bf16x8 a, bf16x8 b, f32x4 c) { return __builtin_amdgcn_mfma_f32_16x16x32_bf16(a, b, c, 0, 0, 0); }
; template <int MI, bool SWAP, class Epi> ...
;     ...
;     if (!prefetched) {
;         __syncthreads();
;         RING_STAGE(0, 0);
;         RING_STAGE(1, 32);
;     }
;     int cur = 0;
;     for (int kt = 0; kt < nk; ++kt) {
;         if (kt + 1 < nk && !(prefetched && kt == 0)) { if (MI == 8) asm volatile("s_waitcnt vmcnt(6)\n\ts_barrier" ::: "memory"); else if (MI == 4) asm volatile("s_waitcnt vmcnt(4)\n\ts_barrier" ::: "memory"); else asm volatile("s_waitcnt vmcnt(3)\n\ts_barrier" ::: "memory"); }
;         else asm volatile("s_waitcnt vmcnt(0)\n\ts_barrier" ::: "memory");
;         if (kt + 2 < nk) { const int nx = (cur == 0) ? 2 : cur - 1; RING_STAGE(nx, (kt + 2) * 32); }
;         const int so = cur * STAGEB;
;         bf16x8 bf[4], af[MI];
; #pragma unroll
;         for (int j = 0; j < 4; ++j) bf[j] = *(const bf16x8*)(brdb + so + j * 1024);
; #pragma unroll
;         for (int i = 0; i < MI; ++i) af[i] = *(const bf16x8*)(ardb + so + i * 1024);
;         if (blockIdx.x & 256) __builtin_amdgcn_s_setprio(2); else __builtin_amdgcn_s_setprio(1);
; #pragma unroll
;         for (int i = 0; i < MI; ++i) {
; #pragma unroll
;             for (int j = 0; j < 4; ++j) {
;                 if (SWAP) acc[i][j] = mfma16(bf[j], af[i], acc[i][j]);
;                 else acc[i][j] = mfma16(af[i], bf[j], acc[i][j]);
;             }
;         }
;         __builtin_amdgcn_s_setprio(0);
.LBB0_274:
	s_mul_i32 s8, s25, 0x6000
	s_add_i32 s9, s8, 0xffffa000
	s_cmp_lg_u32 s25, 0
	s_cselect_b32 s9, s9, 0xc000
	v_readlane_b32 vcc_lo, v248, 0
	s_nop 1
	s_bitcmp1_b32 vcc_lo, 3
	s_cbranch_scc0 .Lrp_nostag0_inA
	s_sleep 9
.Lrp_nostag0_inA:
	s_waitcnt vmcnt(6)
	s_barrier
	v_lshl_add_u64 v[128:129], v[178:179], 0, s[6:7]
	s_add_i32 s29, s9, s11
	s_mov_b32 s30, m0
	s_mov_b32 m0, s29
	s_nop 0
	global_load_lds_dwordx4 v[128:129], off
	s_mov_b32 m0, s30
	s_mov_b64 s[38:39], 0x8000
	v_lshl_add_u64 v[130:131], v[128:129], 0, s[38:39]
	s_add_i32 s30, s29, 0x400
	s_mov_b32 s31, m0
	s_mov_b32 m0, s30
	s_nop 0
	global_load_lds_dwordx4 v[130:131], off
	s_mov_b32 m0, s31
	s_mov_b64 s[30:31], 0x10000
	v_lshl_add_u64 v[130:131], v[128:129], 0, s[30:31]
	s_add_i32 s30, s29, 0x800
	s_mov_b32 s31, m0
	s_mov_b32 m0, s30
	s_nop 0
	global_load_lds_dwordx4 v[130:131], off
	s_mov_b32 m0, s31
	s_mov_b64 s[30:31], 0x18000
	v_lshl_add_u64 v[128:129], v[128:129], 0, s[30:31]
	s_addk_i32 s29, 0xc00
	s_mov_b32 s30, m0
	s_mov_b32 m0, s29
	s_nop 0
	global_load_lds_dwordx4 v[128:129], off
	s_mov_b32 m0, s30
	v_lshl_add_u64 v[128:129], v[176:177], 0, s[6:7]
	s_add_i32 s9, s9, s22
	s_mov_b32 s29, m0
	s_mov_b32 m0, s9
	s_nop 0
	global_load_lds_dwordx4 v[128:129], off
	s_mov_b32 m0, s29
	v_lshl_add_u64 v[128:129], v[128:129], 0, s[38:39]
	s_addk_i32 s9, 0x400
	s_mov_b32 s29, m0
	s_mov_b32 m0, s9
	s_nop 0
	global_load_lds_dwordx4 v[128:129], off
	s_mov_b32 m0, s29
	v_add_u32_e32 v140, s8, v223
	v_add_u32_e32 v144, s8, v222
	ds_read_b128 v[128:131], v140 offset:16384
	ds_read_b128 v[132:135], v140 offset:17408
	ds_read_b128 v[136:139], v140 offset:18432
	ds_read_b128 v[140:143], v140 offset:19456
	ds_read_b128 v[172:175], v144
	ds_read_b128 v[168:171], v144 offset:1024
	ds_read_b128 v[164:167], v144 offset:2048
	ds_read_b128 v[160:163], v144 offset:3072
	ds_read_b128 v[156:159], v144 offset:4096
	ds_read_b128 v[152:155], v144 offset:5120
	ds_read_b128 v[148:151], v144 offset:6144
	ds_read_b128 v[144:147], v144 offset:7168
	s_setprio 2
	s_waitcnt lgkmcnt(7)
	v_mfma_f32_16x16x32_bf16 v[124:127], v[128:131], v[172:175], v[124:127]
	v_mfma_f32_16x16x32_bf16 v[120:123], v[132:135], v[172:175], v[120:123]
	v_mfma_f32_16x16x32_bf16 v[116:119], v[136:139], v[172:175], v[116:119]
	v_mfma_f32_16x16x32_bf16 v[112:115], v[140:143], v[172:175], v[112:115]
	s_waitcnt lgkmcnt(6)
	v_mfma_f32_16x16x32_bf16 v[108:111], v[128:131], v[168:171], v[108:111]
	v_mfma_f32_16x16x32_bf16 v[104:107], v[132:135], v[168:171], v[104:107]
	v_mfma_f32_16x16x32_bf16 v[100:103], v[136:139], v[168:171], v[100:103]
	v_mfma_f32_16x16x32_bf16 v[96:99], v[140:143], v[168:171], v[96:99]
	s_waitcnt lgkmcnt(5)
	v_mfma_f32_16x16x32_bf16 v[92:95], v[128:131], v[164:167], v[92:95]
	v_mfma_f32_16x16x32_bf16 v[88:91], v[132:135], v[164:167], v[88:91]
	v_mfma_f32_16x16x32_bf16 v[84:87], v[136:139], v[164:167], v[84:87]
	v_mfma_f32_16x16x32_bf16 v[80:83], v[140:143], v[164:167], v[80:83]
	s_waitcnt lgkmcnt(4)
	v_mfma_f32_16x16x32_bf16 v[76:79], v[128:131], v[160:163], v[76:79]
	v_mfma_f32_16x16x32_bf16 v[72:75], v[132:135], v[160:163], v[72:75]
	v_mfma_f32_16x16x32_bf16 v[68:71], v[136:139], v[160:163], v[68:71]
	v_mfma_f32_16x16x32_bf16 v[64:67], v[140:143], v[160:163], v[64:67]
	s_waitcnt lgkmcnt(3)
	v_mfma_f32_16x16x32_bf16 v[60:63], v[128:131], v[156:159], v[60:63]
	v_mfma_f32_16x16x32_bf16 v[56:59], v[132:135], v[156:159], v[56:59]
	v_mfma_f32_16x16x32_bf16 v[52:55], v[136:139], v[156:159], v[52:55]
	v_mfma_f32_16x16x32_bf16 v[48:51], v[140:143], v[156:159], v[48:51]
	s_waitcnt lgkmcnt(2)
	v_mfma_f32_16x16x32_bf16 v[44:47], v[128:131], v[152:155], v[44:47]
	v_mfma_f32_16x16x32_bf16 v[40:43], v[132:135], v[152:155], v[40:43]
	v_mfma_f32_16x16x32_bf16 v[36:39], v[136:139], v[152:155], v[36:39]
	v_mfma_f32_16x16x32_bf16 v[32:35], v[140:143], v[152:155], v[32:35]
	s_waitcnt lgkmcnt(1)
	v_mfma_f32_16x16x32_bf16 v[28:31], v[128:131], v[148:151], v[28:31]
	v_mfma_f32_16x16x32_bf16 v[24:27], v[132:135], v[148:151], v[24:27]
	v_mfma_f32_16x16x32_bf16 v[20:23], v[136:139], v[148:151], v[20:23]
	v_mfma_f32_16x16x32_bf16 v[16:19], v[140:143], v[148:151], v[16:19]
	s_waitcnt lgkmcnt(0)
	v_mfma_f32_16x16x32_bf16 v[12:15], v[128:131], v[144:147], v[12:15]
	v_mfma_f32_16x16x32_bf16 v[8:11], v[132:135], v[144:147], v[8:11]
	v_mfma_f32_16x16x32_bf16 v[4:7], v[136:139], v[144:147], v[4:7]
	v_mfma_f32_16x16x32_bf16 v[0:3], v[140:143], v[144:147], v[0:3]
	s_setprio 0
	s_add_u32 s6, s6, 64
	s_addc_u32 s7, s7, 0
; __device__ __forceinline__ f32x4 mfma16(bf16x8 a, bf16x8 b, f32x4 c) { return __builtin_amdgcn_mfma_f32_16x16x32_bf16(a, b, c, 0, 0, 0); }
; template <int MI, bool SWAP, class Epi> ...
;     ...
;     for (int kt = 0; kt < nk; ++kt) {
;         if (kt + 1 < nk && !(prefetched && kt == 0)) { if (MI == 8) asm volatile("s_waitcnt vmcnt(6)\n\ts_barrier" ::: "memory"); else if (MI == 4) asm volatile("s_waitcnt vmcnt(4)\n\ts_barrier" ::: "memory"); else asm volatile("s_waitcnt vmcnt(3)\n\ts_barrier" ::: "memory"); }
;         else asm volatile("s_waitcnt vmcnt(0)\n\ts_barrier" ::: "memory");
;         if (kt + 2 < nk) { const int nx = (cur == 0) ? 2 : cur - 1; RING_STAGE(nx, (kt + 2) * 32); }
;         const int so = cur * STAGEB;
;         bf16x8 bf[4], af[MI];
; #pragma unroll
;         for (int j = 0; j < 4; ++j) bf[j] = *(const bf16x8*)(brdb + so + j * 1024);
; #pragma unroll
;         for (int i = 0; i < MI; ++i) af[i] = *(const bf16x8*)(ardb + so + i * 1024);
;         if (blockIdx.x & 256) __builtin_amdgcn_s_setprio(2); else __builtin_amdgcn_s_setprio(1);
; #pragma unroll
;         for (int i = 0; i < MI; ++i) {
; #pragma unroll
;             for (int j = 0; j < 4; ++j) {
;                 if (SWAP) acc[i][j] = mfma16(bf[j], af[i], acc[i][j]);
;                 else acc[i][j] = mfma16(af[i], bf[j], acc[i][j]);
;             }
;         }
;         __builtin_amdgcn_s_setprio(0);
;         cur = (cur == 2) ? 0 : cur + 1;
;     }
.Lru_loop_inA:
	s_mov_b32 s8, 0xc000
	s_mov_b32 s9, 0x6000
	s_waitcnt vmcnt(0)
	s_barrier
	v_add_u32_e32 v140, s8, v223
	v_add_u32_e32 v144, s8, v222
	ds_read_b128 v[128:131], v140 offset:16384
	ds_read_b128 v[132:135], v140 offset:17408
	ds_read_b128 v[136:139], v140 offset:18432
	ds_read_b128 v[140:143], v140 offset:19456
	ds_read_b128 v[172:175], v144
	ds_read_b128 v[168:171], v144 offset:1024
	ds_read_b128 v[164:167], v144 offset:2048
	ds_read_b128 v[160:163], v144 offset:3072
	ds_read_b128 v[156:159], v144 offset:4096
	ds_read_b128 v[152:155], v144 offset:5120
	ds_read_b128 v[148:151], v144 offset:6144
	ds_read_b128 v[144:147], v144 offset:7168
	s_waitcnt lgkmcnt(0)
	s_barrier
	s_setprio 2
	s_sub_i32 vcc_lo, s8, s9
	v_mfma_f32_16x16x32_bf16 v[124:127], v[128:131], v[172:175], v[124:127]
	v_mfma_f32_16x16x32_bf16 v[120:123], v[132:135], v[172:175], v[120:123]
	v_mfma_f32_16x16x32_bf16 v[116:119], v[136:139], v[172:175], v[116:119]
	v_mfma_f32_16x16x32_bf16 v[112:115], v[140:143], v[172:175], v[112:115]
	v_mfma_f32_16x16x32_bf16 v[108:111], v[128:131], v[168:171], v[108:111]
	v_mfma_f32_16x16x32_bf16 v[104:107], v[132:135], v[168:171], v[104:107]
	v_mfma_f32_16x16x32_bf16 v[100:103], v[136:139], v[168:171], v[100:103]
	v_mfma_f32_16x16x32_bf16 v[96:99], v[140:143], v[168:171], v[96:99]
	v_mfma_f32_16x16x32_bf16 v[92:95], v[128:131], v[164:167], v[92:95]
	v_mfma_f32_16x16x32_bf16 v[88:91], v[132:135], v[164:167], v[88:91]
	v_mfma_f32_16x16x32_bf16 v[84:87], v[136:139], v[164:167], v[84:87]
	v_mfma_f32_16x16x32_bf16 v[80:83], v[140:143], v[164:167], v[80:83]
	v_lshl_add_u64 v[172:173], v[178:179], 0, s[6:7]
	s_add_i32 s29, s9, s11
	s_mov_b32 m0, s29
	v_lshl_add_u64 v[168:169], v[172:173], 0, 64
	global_load_lds_dwordx4 v[172:173], off
	s_add_i32 m0, s29, vcc_lo
	s_nop 0
	global_load_lds_dwordx4 v[168:169], off
	s_mov_b64 s[38:39], 0x8000
	v_lshl_add_u64 v[174:175], v[172:173], 0, s[38:39]
	s_add_i32 s30, s29, 0x400
	s_mov_b32 m0, s30
	v_lshl_add_u64 v[168:169], v[174:175], 0, 64
	global_load_lds_dwordx4 v[174:175], off
	s_add_i32 m0, s30, vcc_lo
	s_nop 0
	global_load_lds_dwordx4 v[168:169], off
	s_mov_b64 s[30:31], 0x10000
	v_lshl_add_u64 v[174:175], v[172:173], 0, s[30:31]
	s_add_i32 s30, s29, 0x800
	s_mov_b32 m0, s30
	v_lshl_add_u64 v[168:169], v[174:175], 0, 64
	global_load_lds_dwordx4 v[174:175], off
	s_add_i32 m0, s30, vcc_lo
	s_nop 0
	global_load_lds_dwordx4 v[168:169], off
	s_mov_b64 s[30:31], 0x18000
	v_lshl_add_u64 v[172:173], v[172:173], 0, s[30:31]
	s_addk_i32 s29, 0xc00
	s_mov_b32 m0, s29
	v_lshl_add_u64 v[168:169], v[172:173], 0, 64
	global_load_lds_dwordx4 v[172:173], off
	s_add_i32 m0, s29, vcc_lo
	s_nop 0
	global_load_lds_dwordx4 v[168:169], off
	v_lshl_add_u64 v[172:173], v[176:177], 0, s[6:7]
	s_add_i32 s9, s9, s22
	s_mov_b32 m0, s9
	v_lshl_add_u64 v[168:169], v[172:173], 0, 64
	global_load_lds_dwordx4 v[172:173], off
	s_add_i32 m0, s9, vcc_lo
	s_nop 0
	global_load_lds_dwordx4 v[168:169], off
	v_lshl_add_u64 v[172:173], v[172:173], 0, s[38:39]
	s_addk_i32 s9, 0x400
	s_mov_b32 m0, s9
	v_lshl_add_u64 v[168:169], v[172:173], 0, 64
	global_load_lds_dwordx4 v[172:173], off
	s_add_i32 m0, s9, vcc_lo
	s_nop 0
	global_load_lds_dwordx4 v[168:169], off
	v_mfma_f32_16x16x32_bf16 v[76:79], v[128:131], v[160:163], v[76:79]
	v_mfma_f32_16x16x32_bf16 v[72:75], v[132:135], v[160:163], v[72:75]
	v_mfma_f32_16x16x32_bf16 v[68:71], v[136:139], v[160:163], v[68:71]
	v_mfma_f32_16x16x32_bf16 v[64:67], v[140:143], v[160:163], v[64:67]
	v_mfma_f32_16x16x32_bf16 v[60:63], v[128:131], v[156:159], v[60:63]
	v_mfma_f32_16x16x32_bf16 v[56:59], v[132:135], v[156:159], v[56:59]
	v_mfma_f32_16x16x32_bf16 v[52:55], v[136:139], v[156:159], v[52:55]
	v_mfma_f32_16x16x32_bf16 v[48:51], v[140:143], v[156:159], v[48:51]
	v_mfma_f32_16x16x32_bf16 v[44:47], v[128:131], v[152:155], v[44:47]
	v_mfma_f32_16x16x32_bf16 v[40:43], v[132:135], v[152:155], v[40:43]
	v_mfma_f32_16x16x32_bf16 v[36:39], v[136:139], v[152:155], v[36:39]
	v_mfma_f32_16x16x32_bf16 v[32:35], v[140:143], v[152:155], v[32:35]
	v_mfma_f32_16x16x32_bf16 v[28:31], v[128:131], v[148:151], v[28:31]
	v_mfma_f32_16x16x32_bf16 v[24:27], v[132:135], v[148:151], v[24:27]
	v_mfma_f32_16x16x32_bf16 v[20:23], v[136:139], v[148:151], v[20:23]
	v_mfma_f32_16x16x32_bf16 v[16:19], v[140:143], v[148:151], v[16:19]
	v_mfma_f32_16x16x32_bf16 v[12:15], v[128:131], v[144:147], v[12:15]
	v_mfma_f32_16x16x32_bf16 v[8:11], v[132:135], v[144:147], v[8:11]
	v_mfma_f32_16x16x32_bf16 v[4:7], v[136:139], v[144:147], v[4:7]
	v_mfma_f32_16x16x32_bf16 v[0:3], v[140:143], v[144:147], v[0:3]
	s_setprio 0
	s_add_u32 s6, s6, 64
	s_addc_u32 s7, s7, 0
	s_mov_b32 s8, 0x0
	v_add_u32_e32 v140, s8, v223
	v_add_u32_e32 v144, s8, v222
	ds_read_b128 v[128:131], v140 offset:16384
	ds_read_b128 v[132:135], v140 offset:17408
	ds_read_b128 v[136:139], v140 offset:18432
	ds_read_b128 v[140:143], v140 offset:19456
	ds_read_b128 v[172:175], v144
	ds_read_b128 v[168:171], v144 offset:1024
	ds_read_b128 v[164:167], v144 offset:2048
	ds_read_b128 v[160:163], v144 offset:3072
	ds_read_b128 v[156:159], v144 offset:4096
	ds_read_b128 v[152:155], v144 offset:5120
	ds_read_b128 v[148:151], v144 offset:6144
	ds_read_b128 v[144:147], v144 offset:7168
	s_setprio 2
	s_waitcnt lgkmcnt(7)
	v_mfma_f32_16x16x32_bf16 v[124:127], v[128:131], v[172:175], v[124:127]
	v_mfma_f32_16x16x32_bf16 v[120:123], v[132:135], v[172:175], v[120:123]
	v_mfma_f32_16x16x32_bf16 v[116:119], v[136:139], v[172:175], v[116:119]
	v_mfma_f32_16x16x32_bf16 v[112:115], v[140:143], v[172:175], v[112:115]
	s_waitcnt lgkmcnt(6)
; __device__ __forceinline__ f32x4 mfma16(bf16x8 a, bf16x8 b, f32x4 c) { return __builtin_amdgcn_mfma_f32_16x16x32_bf16(a, b, c, 0, 0, 0); }
; template <int MI, bool SWAP, class Epi> ...
;     ...
;     for (int kt = 0; kt < nk; ++kt) {
;         if (kt + 1 < nk && !(prefetched && kt == 0)) { if (MI == 8) asm volatile("s_waitcnt vmcnt(6)\n\ts_barrier" ::: "memory"); else if (MI == 4) asm volatile("s_waitcnt vmcnt(4)\n\ts_barrier" ::: "memory"); else asm volatile("s_waitcnt vmcnt(3)\n\ts_barrier" ::: "memory"); }
;         else asm volatile("s_waitcnt vmcnt(0)\n\ts_barrier" ::: "memory");
;         if (kt + 2 < nk) { const int nx = (cur == 0) ? 2 : cur - 1; RING_STAGE(nx, (kt + 2) * 32); }
;         const int so = cur * STAGEB;
;         bf16x8 bf[4], af[MI];
; #pragma unroll
;         for (int j = 0; j < 4; ++j) bf[j] = *(const bf16x8*)(brdb + so + j * 1024);
; #pragma unroll
;         for (int i = 0; i < MI; ++i) af[i] = *(const bf16x8*)(ardb + so + i * 1024);
;         if (blockIdx.x & 256) __builtin_amdgcn_s_setprio(2); else __builtin_amdgcn_s_setprio(1);
; #pragma unroll
;         for (int i = 0; i < MI; ++i) {
; #pragma unroll
;             for (int j = 0; j < 4; ++j) {
;                 if (SWAP) acc[i][j] = mfma16(bf[j], af[i], acc[i][j]);
;                 else acc[i][j] = mfma16(af[i], bf[j], acc[i][j]);
;             }
;         }
;         __builtin_amdgcn_s_setprio(0);
;         cur = (cur == 2) ? 0 : cur + 1;
;     }
	v_mfma_f32_16x16x32_bf16 v[108:111], v[128:131], v[168:171], v[108:111]
	v_mfma_f32_16x16x32_bf16 v[104:107], v[132:135], v[168:171], v[104:107]
	v_mfma_f32_16x16x32_bf16 v[100:103], v[136:139], v[168:171], v[100:103]
	v_mfma_f32_16x16x32_bf16 v[96:99], v[140:143], v[168:171], v[96:99]
	s_waitcnt lgkmcnt(5)
	v_mfma_f32_16x16x32_bf16 v[92:95], v[128:131], v[164:167], v[92:95]
	v_mfma_f32_16x16x32_bf16 v[88:91], v[132:135], v[164:167], v[88:91]
	v_mfma_f32_16x16x32_bf16 v[84:87], v[136:139], v[164:167], v[84:87]
	v_mfma_f32_16x16x32_bf16 v[80:83], v[140:143], v[164:167], v[80:83]
	s_waitcnt lgkmcnt(4)
	v_mfma_f32_16x16x32_bf16 v[76:79], v[128:131], v[160:163], v[76:79]
	v_mfma_f32_16x16x32_bf16 v[72:75], v[132:135], v[160:163], v[72:75]
	v_mfma_f32_16x16x32_bf16 v[68:71], v[136:139], v[160:163], v[68:71]
	v_mfma_f32_16x16x32_bf16 v[64:67], v[140:143], v[160:163], v[64:67]
	s_waitcnt lgkmcnt(3)
	v_mfma_f32_16x16x32_bf16 v[60:63], v[128:131], v[156:159], v[60:63]
	v_mfma_f32_16x16x32_bf16 v[56:59], v[132:135], v[156:159], v[56:59]
	v_mfma_f32_16x16x32_bf16 v[52:55], v[136:139], v[156:159], v[52:55]
	v_mfma_f32_16x16x32_bf16 v[48:51], v[140:143], v[156:159], v[48:51]
	s_waitcnt lgkmcnt(2)
	v_mfma_f32_16x16x32_bf16 v[44:47], v[128:131], v[152:155], v[44:47]
	v_mfma_f32_16x16x32_bf16 v[40:43], v[132:135], v[152:155], v[40:43]
	v_mfma_f32_16x16x32_bf16 v[36:39], v[136:139], v[152:155], v[36:39]
	v_mfma_f32_16x16x32_bf16 v[32:35], v[140:143], v[152:155], v[32:35]
	s_waitcnt lgkmcnt(1)
	v_mfma_f32_16x16x32_bf16 v[28:31], v[128:131], v[148:151], v[28:31]
	v_mfma_f32_16x16x32_bf16 v[24:27], v[132:135], v[148:151], v[24:27]
	v_mfma_f32_16x16x32_bf16 v[20:23], v[136:139], v[148:151], v[20:23]
	v_mfma_f32_16x16x32_bf16 v[16:19], v[140:143], v[148:151], v[16:19]
	s_waitcnt lgkmcnt(0)
	v_mfma_f32_16x16x32_bf16 v[12:15], v[128:131], v[144:147], v[12:15]
	v_mfma_f32_16x16x32_bf16 v[8:11], v[132:135], v[144:147], v[8:11]
	v_mfma_f32_16x16x32_bf16 v[4:7], v[136:139], v[144:147], v[4:7]
	v_mfma_f32_16x16x32_bf16 v[0:3], v[140:143], v[144:147], v[0:3]
	s_setprio 0
	s_add_u32 s6, s6, 64
	s_addc_u32 s7, s7, 0
	s_mov_b32 s25, 1
	s_cmpk_eq_i32 s6, 0x740
	s_cbranch_scc1 .LBB0_279
	s_mov_b32 s8, 0x6000
	s_mov_b32 s9, 0x0
	s_waitcnt vmcnt(0)
	s_barrier
	v_add_u32_e32 v140, s8, v223
	v_add_u32_e32 v144, s8, v222
	ds_read_b128 v[128:131], v140 offset:16384
	ds_read_b128 v[132:135], v140 offset:17408
	ds_read_b128 v[136:139], v140 offset:18432
	ds_read_b128 v[140:143], v140 offset:19456
	ds_read_b128 v[172:175], v144
	ds_read_b128 v[168:171], v144 offset:1024
	ds_read_b128 v[164:167], v144 offset:2048
	ds_read_b128 v[160:163], v144 offset:3072
	ds_read_b128 v[156:159], v144 offset:4096
	ds_read_b128 v[152:155], v144 offset:5120
	ds_read_b128 v[148:151], v144 offset:6144
	ds_read_b128 v[144:147], v144 offset:7168
	s_waitcnt lgkmcnt(0)
	s_barrier
	s_setprio 2
	s_sub_i32 vcc_lo, s8, s9
	v_mfma_f32_16x16x32_bf16 v[124:127], v[128:131], v[172:175], v[124:127]
	v_mfma_f32_16x16x32_bf16 v[120:123], v[132:135], v[172:175], v[120:123]
	v_mfma_f32_16x16x32_bf16 v[116:119], v[136:139], v[172:175], v[116:119]
	v_mfma_f32_16x16x32_bf16 v[112:115], v[140:143], v[172:175], v[112:115]
	v_mfma_f32_16x16x32_bf16 v[108:111], v[128:131], v[168:171], v[108:111]
	v_mfma_f32_16x16x32_bf16 v[104:107], v[132:135], v[168:171], v[104:107]
	v_mfma_f32_16x16x32_bf16 v[100:103], v[136:139], v[168:171], v[100:103]
	v_mfma_f32_16x16x32_bf16 v[96:99], v[140:143], v[168:171], v[96:99]
	v_mfma_f32_16x16x32_bf16 v[92:95], v[128:131], v[164:167], v[92:95]
	v_mfma_f32_16x16x32_bf16 v[88:91], v[132:135], v[164:167], v[88:91]
	v_mfma_f32_16x16x32_bf16 v[84:87], v[136:139], v[164:167], v[84:87]
	v_mfma_f32_16x16x32_bf16 v[80:83], v[140:143], v[164:167], v[80:83]
	v_lshl_add_u64 v[172:173], v[178:179], 0, s[6:7]
	s_add_i32 s29, s9, s11
	s_mov_b32 m0, s29
	v_lshl_add_u64 v[168:169], v[172:173], 0, 64
	global_load_lds_dwordx4 v[172:173], off
	s_add_i32 m0, s29, vcc_lo
	s_nop 0
	global_load_lds_dwordx4 v[168:169], off
	s_mov_b64 s[38:39], 0x8000
	v_lshl_add_u64 v[174:175], v[172:173], 0, s[38:39]
	s_add_i32 s30, s29, 0x400
	s_mov_b32 m0, s30
	v_lshl_add_u64 v[168:169], v[174:175], 0, 64
	global_load_lds_dwordx4 v[174:175], off
	s_add_i32 m0, s30, vcc_lo
	s_nop 0
	global_load_lds_dwordx4 v[168:169], off
	s_mov_b64 s[30:31], 0x10000
	v_lshl_add_u64 v[174:175], v[172:173], 0, s[30:31]
	s_add_i32 s30, s29, 0x800
	s_mov_b32 m0, s30
	v_lshl_add_u64 v[168:169], v[174:175], 0, 64
	global_load_lds_dwordx4 v[174:175], off
	s_add_i32 m0, s30, vcc_lo
	s_nop 0
	global_load_lds_dwordx4 v[168:169], off
	s_mov_b64 s[30:31], 0x18000
	v_lshl_add_u64 v[172:173], v[172:173], 0, s[30:31]
	s_addk_i32 s29, 0xc00
	s_mov_b32 m0, s29
	v_lshl_add_u64 v[168:169], v[172:173], 0, 64
	global_load_lds_dwordx4 v[172:173], off
	s_add_i32 m0, s29, vcc_lo
	s_nop 0
	global_load_lds_dwordx4 v[168:169], off
	v_lshl_add_u64 v[172:173], v[176:177], 0, s[6:7]
	s_add_i32 s9, s9, s22
	s_mov_b32 m0, s9
	v_lshl_add_u64 v[168:169], v[172:173], 0, 64
	global_load_lds_dwordx4 v[172:173], off
	s_add_i32 m0, s9, vcc_lo
	s_nop 0
	global_load_lds_dwordx4 v[168:169], off
	v_lshl_add_u64 v[172:173], v[172:173], 0, s[38:39]
	s_addk_i32 s9, 0x400
	s_mov_b32 m0, s9
	v_lshl_add_u64 v[168:169], v[172:173], 0, 64
	global_load_lds_dwordx4 v[172:173], off
	s_add_i32 m0, s9, vcc_lo
	s_nop 0
	global_load_lds_dwordx4 v[168:169], off
	v_mfma_f32_16x16x32_bf16 v[76:79], v[128:131], v[160:163], v[76:79]
	v_mfma_f32_16x16x32_bf16 v[72:75], v[132:135], v[160:163], v[72:75]
	v_mfma_f32_16x16x32_bf16 v[68:71], v[136:139], v[160:163], v[68:71]
	v_mfma_f32_16x16x32_bf16 v[64:67], v[140:143], v[160:163], v[64:67]
; __device__ __forceinline__ f32x4 mfma16(bf16x8 a, bf16x8 b, f32x4 c) { return __builtin_amdgcn_mfma_f32_16x16x32_bf16(a, b, c, 0, 0, 0); }
; template <int MI, bool SWAP, class Epi> ...
;     ...
;     for (int kt = 0; kt < nk; ++kt) {
;         if (kt + 1 < nk && !(prefetched && kt == 0)) { if (MI == 8) asm volatile("s_waitcnt vmcnt(6)\n\ts_barrier" ::: "memory"); else if (MI == 4) asm volatile("s_waitcnt vmcnt(4)\n\ts_barrier" ::: "memory"); else asm volatile("s_waitcnt vmcnt(3)\n\ts_barrier" ::: "memory"); }
;         else asm volatile("s_waitcnt vmcnt(0)\n\ts_barrier" ::: "memory");
;         if (kt + 2 < nk) { const int nx = (cur == 0) ? 2 : cur - 1; RING_STAGE(nx, (kt + 2) * 32); }
;         const int so = cur * STAGEB;
;         bf16x8 bf[4], af[MI];
; #pragma unroll
;         for (int j = 0; j < 4; ++j) bf[j] = *(const bf16x8*)(brdb + so + j * 1024);
; #pragma unroll
;         for (int i = 0; i < MI; ++i) af[i] = *(const bf16x8*)(ardb + so + i * 1024);
;         if (blockIdx.x & 256) __builtin_amdgcn_s_setprio(2); else __builtin_amdgcn_s_setprio(1);
; #pragma unroll
;         for (int i = 0; i < MI; ++i) {
; #pragma unroll
;             for (int j = 0; j < 4; ++j) {
;                 if (SWAP) acc[i][j] = mfma16(bf[j], af[i], acc[i][j]);
;                 else acc[i][j] = mfma16(af[i], bf[j], acc[i][j]);
;             }
;         }
;         __builtin_amdgcn_s_setprio(0);
;         cur = (cur == 2) ? 0 : cur + 1;
;     }
	v_mfma_f32_16x16x32_bf16 v[60:63], v[128:131], v[156:159], v[60:63]
	v_mfma_f32_16x16x32_bf16 v[56:59], v[132:135], v[156:159], v[56:59]
	v_mfma_f32_16x16x32_bf16 v[52:55], v[136:139], v[156:159], v[52:55]
	v_mfma_f32_16x16x32_bf16 v[48:51], v[140:143], v[156:159], v[48:51]
	v_mfma_f32_16x16x32_bf16 v[44:47], v[128:131], v[152:155], v[44:47]
	v_mfma_f32_16x16x32_bf16 v[40:43], v[132:135], v[152:155], v[40:43]
	v_mfma_f32_16x16x32_bf16 v[36:39], v[136:139], v[152:155], v[36:39]
	v_mfma_f32_16x16x32_bf16 v[32:35], v[140:143], v[152:155], v[32:35]
	v_mfma_f32_16x16x32_bf16 v[28:31], v[128:131], v[148:151], v[28:31]
	v_mfma_f32_16x16x32_bf16 v[24:27], v[132:135], v[148:151], v[24:27]
	v_mfma_f32_16x16x32_bf16 v[20:23], v[136:139], v[148:151], v[20:23]
	v_mfma_f32_16x16x32_bf16 v[16:19], v[140:143], v[148:151], v[16:19]
	v_mfma_f32_16x16x32_bf16 v[12:15], v[128:131], v[144:147], v[12:15]
	v_mfma_f32_16x16x32_bf16 v[8:11], v[132:135], v[144:147], v[8:11]
	v_mfma_f32_16x16x32_bf16 v[4:7], v[136:139], v[144:147], v[4:7]
	v_mfma_f32_16x16x32_bf16 v[0:3], v[140:143], v[144:147], v[0:3]
	s_setprio 0
	s_add_u32 s6, s6, 64
	s_addc_u32 s7, s7, 0
	s_mov_b32 s8, 0xc000
	v_add_u32_e32 v140, s8, v223
	v_add_u32_e32 v144, s8, v222
	ds_read_b128 v[128:131], v140 offset:16384
	ds_read_b128 v[132:135], v140 offset:17408
	ds_read_b128 v[136:139], v140 offset:18432
	ds_read_b128 v[140:143], v140 offset:19456
	ds_read_b128 v[172:175], v144
	ds_read_b128 v[168:171], v144 offset:1024
	ds_read_b128 v[164:167], v144 offset:2048
	ds_read_b128 v[160:163], v144 offset:3072
	ds_read_b128 v[156:159], v144 offset:4096
	ds_read_b128 v[152:155], v144 offset:5120
	ds_read_b128 v[148:151], v144 offset:6144
	ds_read_b128 v[144:147], v144 offset:7168
	s_setprio 2
	s_waitcnt lgkmcnt(7)
	v_mfma_f32_16x16x32_bf16 v[124:127], v[128:131], v[172:175], v[124:127]
	v_mfma_f32_16x16x32_bf16 v[120:123], v[132:135], v[172:175], v[120:123]
	v_mfma_f32_16x16x32_bf16 v[116:119], v[136:139], v[172:175], v[116:119]
	v_mfma_f32_16x16x32_bf16 v[112:115], v[140:143], v[172:175], v[112:115]
	s_waitcnt lgkmcnt(6)
	v_mfma_f32_16x16x32_bf16 v[108:111], v[128:131], v[168:171], v[108:111]
	v_mfma_f32_16x16x32_bf16 v[104:107], v[132:135], v[168:171], v[104:107]
	v_mfma_f32_16x16x32_bf16 v[100:103], v[136:139], v[168:171], v[100:103]
	v_mfma_f32_16x16x32_bf16 v[96:99], v[140:143], v[168:171], v[96:99]
	s_waitcnt lgkmcnt(5)
	v_mfma_f32_16x16x32_bf16 v[92:95], v[128:131], v[164:167], v[92:95]
	v_mfma_f32_16x16x32_bf16 v[88:91], v[132:135], v[164:167], v[88:91]
	v_mfma_f32_16x16x32_bf16 v[84:87], v[136:139], v[164:167], v[84:87]
	v_mfma_f32_16x16x32_bf16 v[80:83], v[140:143], v[164:167], v[80:83]
	s_waitcnt lgkmcnt(4)
	v_mfma_f32_16x16x32_bf16 v[76:79], v[128:131], v[160:163], v[76:79]
	v_mfma_f32_16x16x32_bf16 v[72:75], v[132:135], v[160:163], v[72:75]
	v_mfma_f32_16x16x32_bf16 v[68:71], v[136:139], v[160:163], v[68:71]
	v_mfma_f32_16x16x32_bf16 v[64:67], v[140:143], v[160:163], v[64:67]
	s_waitcnt lgkmcnt(3)
	v_mfma_f32_16x16x32_bf16 v[60:63], v[128:131], v[156:159], v[60:63]
	v_mfma_f32_16x16x32_bf16 v[56:59], v[132:135], v[156:159], v[56:59]
	v_mfma_f32_16x16x32_bf16 v[52:55], v[136:139], v[156:159], v[52:55]
	v_mfma_f32_16x16x32_bf16 v[48:51], v[140:143], v[156:159], v[48:51]
	s_waitcnt lgkmcnt(2)
	v_mfma_f32_16x16x32_bf16 v[44:47], v[128:131], v[152:155], v[44:47]
	v_mfma_f32_16x16x32_bf16 v[40:43], v[132:135], v[152:155], v[40:43]
	v_mfma_f32_16x16x32_bf16 v[36:39], v[136:139], v[152:155], v[36:39]
	v_mfma_f32_16x16x32_bf16 v[32:35], v[140:143], v[152:155], v[32:35]
	s_waitcnt lgkmcnt(1)
	v_mfma_f32_16x16x32_bf16 v[28:31], v[128:131], v[148:151], v[28:31]
	v_mfma_f32_16x16x32_bf16 v[24:27], v[132:135], v[148:151], v[24:27]
	v_mfma_f32_16x16x32_bf16 v[20:23], v[136:139], v[148:151], v[20:23]
	v_mfma_f32_16x16x32_bf16 v[16:19], v[140:143], v[148:151], v[16:19]
	s_waitcnt lgkmcnt(0)
	v_mfma_f32_16x16x32_bf16 v[12:15], v[128:131], v[144:147], v[12:15]
	v_mfma_f32_16x16x32_bf16 v[8:11], v[132:135], v[144:147], v[8:11]
	v_mfma_f32_16x16x32_bf16 v[4:7], v[136:139], v[144:147], v[4:7]
	v_mfma_f32_16x16x32_bf16 v[0:3], v[140:143], v[144:147], v[0:3]
	s_setprio 0
	s_add_u32 s6, s6, 64
	s_addc_u32 s7, s7, 0
	s_mov_b32 s25, 0
	s_cmpk_eq_i32 s6, 0x740
	s_cbranch_scc1 .LBB0_279
	s_mov_b32 s8, 0x0
	s_mov_b32 s9, 0xc000
	s_waitcnt vmcnt(0)
	s_barrier
	v_add_u32_e32 v140, s8, v223
	v_add_u32_e32 v144, s8, v222
	ds_read_b128 v[128:131], v140 offset:16384
	ds_read_b128 v[132:135], v140 offset:17408
	ds_read_b128 v[136:139], v140 offset:18432
	ds_read_b128 v[140:143], v140 offset:19456
	ds_read_b128 v[172:175], v144
	ds_read_b128 v[168:171], v144 offset:1024
	ds_read_b128 v[164:167], v144 offset:2048
	ds_read_b128 v[160:163], v144 offset:3072
	ds_read_b128 v[156:159], v144 offset:4096
	ds_read_b128 v[152:155], v144 offset:5120
	ds_read_b128 v[148:151], v144 offset:6144
	ds_read_b128 v[144:147], v144 offset:7168
	s_waitcnt lgkmcnt(0)
	s_barrier
; __device__ __forceinline__ f32x4 mfma16(bf16x8 a, bf16x8 b, f32x4 c) { return __builtin_amdgcn_mfma_f32_16x16x32_bf16(a, b, c, 0, 0, 0); }
; template <int MI, bool SWAP, class Epi> ...
;     ...
;     for (int kt = 0; kt < nk; ++kt) {
;         if (kt + 1 < nk && !(prefetched && kt == 0)) { if (MI == 8) asm volatile("s_waitcnt vmcnt(6)\n\ts_barrier" ::: "memory"); else if (MI == 4) asm volatile("s_waitcnt vmcnt(4)\n\ts_barrier" ::: "memory"); else asm volatile("s_waitcnt vmcnt(3)\n\ts_barrier" ::: "memory"); }
;         else asm volatile("s_waitcnt vmcnt(0)\n\ts_barrier" ::: "memory");
;         if (kt + 2 < nk) { const int nx = (cur == 0) ? 2 : cur - 1; RING_STAGE(nx, (kt + 2) * 32); }
;         const int so = cur * STAGEB;
;         bf16x8 bf[4], af[MI];
; #pragma unroll
;         for (int j = 0; j < 4; ++j) bf[j] = *(const bf16x8*)(brdb + so + j * 1024);
; #pragma unroll
;         for (int i = 0; i < MI; ++i) af[i] = *(const bf16x8*)(ardb + so + i * 1024);
;         if (blockIdx.x & 256) __builtin_amdgcn_s_setprio(2); else __builtin_amdgcn_s_setprio(1);
; #pragma unroll
;         for (int i = 0; i < MI; ++i) {
; #pragma unroll
;             for (int j = 0; j < 4; ++j) {
;                 if (SWAP) acc[i][j] = mfma16(bf[j], af[i], acc[i][j]);
;                 else acc[i][j] = mfma16(af[i], bf[j], acc[i][j]);
;             }
;         }
;         __builtin_amdgcn_s_setprio(0);
;         cur = (cur == 2) ? 0 : cur + 1;
;     }
	s_setprio 2
	s_sub_i32 vcc_lo, s8, s9
	v_mfma_f32_16x16x32_bf16 v[124:127], v[128:131], v[172:175], v[124:127]
	v_mfma_f32_16x16x32_bf16 v[120:123], v[132:135], v[172:175], v[120:123]
	v_mfma_f32_16x16x32_bf16 v[116:119], v[136:139], v[172:175], v[116:119]
	v_mfma_f32_16x16x32_bf16 v[112:115], v[140:143], v[172:175], v[112:115]
	v_mfma_f32_16x16x32_bf16 v[108:111], v[128:131], v[168:171], v[108:111]
	v_mfma_f32_16x16x32_bf16 v[104:107], v[132:135], v[168:171], v[104:107]
	v_mfma_f32_16x16x32_bf16 v[100:103], v[136:139], v[168:171], v[100:103]
	v_mfma_f32_16x16x32_bf16 v[96:99], v[140:143], v[168:171], v[96:99]
	v_mfma_f32_16x16x32_bf16 v[92:95], v[128:131], v[164:167], v[92:95]
	v_mfma_f32_16x16x32_bf16 v[88:91], v[132:135], v[164:167], v[88:91]
	v_mfma_f32_16x16x32_bf16 v[84:87], v[136:139], v[164:167], v[84:87]
	v_mfma_f32_16x16x32_bf16 v[80:83], v[140:143], v[164:167], v[80:83]
	v_lshl_add_u64 v[172:173], v[178:179], 0, s[6:7]
	s_add_i32 s29, s9, s11
	s_mov_b32 m0, s29
	v_lshl_add_u64 v[168:169], v[172:173], 0, 64
	global_load_lds_dwordx4 v[172:173], off
	s_add_i32 m0, s29, vcc_lo
	s_nop 0
	global_load_lds_dwordx4 v[168:169], off
	s_mov_b64 s[38:39], 0x8000
	v_lshl_add_u64 v[174:175], v[172:173], 0, s[38:39]
	s_add_i32 s30, s29, 0x400
	s_mov_b32 m0, s30
	v_lshl_add_u64 v[168:169], v[174:175], 0, 64
	global_load_lds_dwordx4 v[174:175], off
	s_add_i32 m0, s30, vcc_lo
	s_nop 0
	global_load_lds_dwordx4 v[168:169], off
	s_mov_b64 s[30:31], 0x10000
	v_lshl_add_u64 v[174:175], v[172:173], 0, s[30:31]
	s_add_i32 s30, s29, 0x800
	s_mov_b32 m0, s30
	v_lshl_add_u64 v[168:169], v[174:175], 0, 64
	global_load_lds_dwordx4 v[174:175], off
	s_add_i32 m0, s30, vcc_lo
	s_nop 0
	global_load_lds_dwordx4 v[168:169], off
	s_mov_b64 s[30:31], 0x18000
	v_lshl_add_u64 v[172:173], v[172:173], 0, s[30:31]
	s_addk_i32 s29, 0xc00
	s_mov_b32 m0, s29
	v_lshl_add_u64 v[168:169], v[172:173], 0, 64
	global_load_lds_dwordx4 v[172:173], off
	s_add_i32 m0, s29, vcc_lo
	s_nop 0
	global_load_lds_dwordx4 v[168:169], off
	v_lshl_add_u64 v[172:173], v[176:177], 0, s[6:7]
	s_add_i32 s9, s9, s22
	s_mov_b32 m0, s9
	v_lshl_add_u64 v[168:169], v[172:173], 0, 64
	global_load_lds_dwordx4 v[172:173], off
	s_add_i32 m0, s9, vcc_lo
	s_nop 0
	global_load_lds_dwordx4 v[168:169], off
	v_lshl_add_u64 v[172:173], v[172:173], 0, s[38:39]
	s_addk_i32 s9, 0x400
	s_mov_b32 m0, s9
	v_lshl_add_u64 v[168:169], v[172:173], 0, 64
	global_load_lds_dwordx4 v[172:173], off
	s_add_i32 m0, s9, vcc_lo
	s_nop 0
	global_load_lds_dwordx4 v[168:169], off
	v_mfma_f32_16x16x32_bf16 v[76:79], v[128:131], v[160:163], v[76:79]
	v_mfma_f32_16x16x32_bf16 v[72:75], v[132:135], v[160:163], v[72:75]
	v_mfma_f32_16x16x32_bf16 v[68:71], v[136:139], v[160:163], v[68:71]
	v_mfma_f32_16x16x32_bf16 v[64:67], v[140:143], v[160:163], v[64:67]
	v_mfma_f32_16x16x32_bf16 v[60:63], v[128:131], v[156:159], v[60:63]
	v_mfma_f32_16x16x32_bf16 v[56:59], v[132:135], v[156:159], v[56:59]
	v_mfma_f32_16x16x32_bf16 v[52:55], v[136:139], v[156:159], v[52:55]
	v_mfma_f32_16x16x32_bf16 v[48:51], v[140:143], v[156:159], v[48:51]
	v_mfma_f32_16x16x32_bf16 v[44:47], v[128:131], v[152:155], v[44:47]
	v_mfma_f32_16x16x32_bf16 v[40:43], v[132:135], v[152:155], v[40:43]
	v_mfma_f32_16x16x32_bf16 v[36:39], v[136:139], v[152:155], v[36:39]
	v_mfma_f32_16x16x32_bf16 v[32:35], v[140:143], v[152:155], v[32:35]
	v_mfma_f32_16x16x32_bf16 v[28:31], v[128:131], v[148:151], v[28:31]
	v_mfma_f32_16x16x32_bf16 v[24:27], v[132:135], v[148:151], v[24:27]
	v_mfma_f32_16x16x32_bf16 v[20:23], v[136:139], v[148:151], v[20:23]
	v_mfma_f32_16x16x32_bf16 v[16:19], v[140:143], v[148:151], v[16:19]
	v_mfma_f32_16x16x32_bf16 v[12:15], v[128:131], v[144:147], v[12:15]
	v_mfma_f32_16x16x32_bf16 v[8:11], v[132:135], v[144:147], v[8:11]
	v_mfma_f32_16x16x32_bf16 v[4:7], v[136:139], v[144:147], v[4:7]
	v_mfma_f32_16x16x32_bf16 v[0:3], v[140:143], v[144:147], v[0:3]
	s_setprio 0
	s_add_u32 s6, s6, 64
	s_addc_u32 s7, s7, 0
	s_mov_b32 s8, 0x6000
	v_add_u32_e32 v140, s8, v223
	v_add_u32_e32 v144, s8, v222
	ds_read_b128 v[128:131], v140 offset:16384
	ds_read_b128 v[132:135], v140 offset:17408
	ds_read_b128 v[136:139], v140 offset:18432
	ds_read_b128 v[140:143], v140 offset:19456
	ds_read_b128 v[172:175], v144
	ds_read_b128 v[168:171], v144 offset:1024
	ds_read_b128 v[164:167], v144 offset:2048
	ds_read_b128 v[160:163], v144 offset:3072
	ds_read_b128 v[156:159], v144 offset:4096
	ds_read_b128 v[152:155], v144 offset:5120
	ds_read_b128 v[148:151], v144 offset:6144
	ds_read_b128 v[144:147], v144 offset:7168
	s_setprio 2
	s_waitcnt lgkmcnt(7)
; __device__ __forceinline__ f32x4 mfma16(bf16x8 a, bf16x8 b, f32x4 c) { return __builtin_amdgcn_mfma_f32_16x16x32_bf16(a, b, c, 0, 0, 0); }
; template <int MI, bool SWAP, class Epi> ...
;     ...
;     for (int kt = 0; kt < nk; ++kt) {
;         if (kt + 1 < nk && !(prefetched && kt == 0)) { if (MI == 8) asm volatile("s_waitcnt vmcnt(6)\n\ts_barrier" ::: "memory"); else if (MI == 4) asm volatile("s_waitcnt vmcnt(4)\n\ts_barrier" ::: "memory"); else asm volatile("s_waitcnt vmcnt(3)\n\ts_barrier" ::: "memory"); }
;         else asm volatile("s_waitcnt vmcnt(0)\n\ts_barrier" ::: "memory");
;         if (kt + 2 < nk) { const int nx = (cur == 0) ? 2 : cur - 1; RING_STAGE(nx, (kt + 2) * 32); }
;         const int so = cur * STAGEB;
;         bf16x8 bf[4], af[MI];
; #pragma unroll
;         for (int j = 0; j < 4; ++j) bf[j] = *(const bf16x8*)(brdb + so + j * 1024);
; #pragma unroll
;         for (int i = 0; i < MI; ++i) af[i] = *(const bf16x8*)(ardb + so + i * 1024);
;         if (blockIdx.x & 256) __builtin_amdgcn_s_setprio(2); else __builtin_amdgcn_s_setprio(1);
; #pragma unroll
;         for (int i = 0; i < MI; ++i) {
; #pragma unroll
;             for (int j = 0; j < 4; ++j) {
;                 if (SWAP) acc[i][j] = mfma16(bf[j], af[i], acc[i][j]);
;                 else acc[i][j] = mfma16(af[i], bf[j], acc[i][j]);
;             }
;         }
;         __builtin_amdgcn_s_setprio(0);
;         cur = (cur == 2) ? 0 : cur + 1;
;     }
	v_mfma_f32_16x16x32_bf16 v[124:127], v[128:131], v[172:175], v[124:127]
	v_mfma_f32_16x16x32_bf16 v[120:123], v[132:135], v[172:175], v[120:123]
	v_mfma_f32_16x16x32_bf16 v[116:119], v[136:139], v[172:175], v[116:119]
	v_mfma_f32_16x16x32_bf16 v[112:115], v[140:143], v[172:175], v[112:115]
	s_waitcnt lgkmcnt(6)
	v_mfma_f32_16x16x32_bf16 v[108:111], v[128:131], v[168:171], v[108:111]
	v_mfma_f32_16x16x32_bf16 v[104:107], v[132:135], v[168:171], v[104:107]
	v_mfma_f32_16x16x32_bf16 v[100:103], v[136:139], v[168:171], v[100:103]
	v_mfma_f32_16x16x32_bf16 v[96:99], v[140:143], v[168:171], v[96:99]
	s_waitcnt lgkmcnt(5)
	v_mfma_f32_16x16x32_bf16 v[92:95], v[128:131], v[164:167], v[92:95]
	v_mfma_f32_16x16x32_bf16 v[88:91], v[132:135], v[164:167], v[88:91]
	v_mfma_f32_16x16x32_bf16 v[84:87], v[136:139], v[164:167], v[84:87]
	v_mfma_f32_16x16x32_bf16 v[80:83], v[140:143], v[164:167], v[80:83]
	s_waitcnt lgkmcnt(4)
	v_mfma_f32_16x16x32_bf16 v[76:79], v[128:131], v[160:163], v[76:79]
	v_mfma_f32_16x16x32_bf16 v[72:75], v[132:135], v[160:163], v[72:75]
	v_mfma_f32_16x16x32_bf16 v[68:71], v[136:139], v[160:163], v[68:71]
	v_mfma_f32_16x16x32_bf16 v[64:67], v[140:143], v[160:163], v[64:67]
	s_waitcnt lgkmcnt(3)
	v_mfma_f32_16x16x32_bf16 v[60:63], v[128:131], v[156:159], v[60:63]
	v_mfma_f32_16x16x32_bf16 v[56:59], v[132:135], v[156:159], v[56:59]
	v_mfma_f32_16x16x32_bf16 v[52:55], v[136:139], v[156:159], v[52:55]
	v_mfma_f32_16x16x32_bf16 v[48:51], v[140:143], v[156:159], v[48:51]
	s_waitcnt lgkmcnt(2)
	v_mfma_f32_16x16x32_bf16 v[44:47], v[128:131], v[152:155], v[44:47]
	v_mfma_f32_16x16x32_bf16 v[40:43], v[132:135], v[152:155], v[40:43]
	v_mfma_f32_16x16x32_bf16 v[36:39], v[136:139], v[152:155], v[36:39]
	v_mfma_f32_16x16x32_bf16 v[32:35], v[140:143], v[152:155], v[32:35]
	s_waitcnt lgkmcnt(1)
	v_mfma_f32_16x16x32_bf16 v[28:31], v[128:131], v[148:151], v[28:31]
	v_mfma_f32_16x16x32_bf16 v[24:27], v[132:135], v[148:151], v[24:27]
	v_mfma_f32_16x16x32_bf16 v[20:23], v[136:139], v[148:151], v[20:23]
	v_mfma_f32_16x16x32_bf16 v[16:19], v[140:143], v[148:151], v[16:19]
	s_waitcnt lgkmcnt(0)
	v_mfma_f32_16x16x32_bf16 v[12:15], v[128:131], v[144:147], v[12:15]
	v_mfma_f32_16x16x32_bf16 v[8:11], v[132:135], v[144:147], v[8:11]
	v_mfma_f32_16x16x32_bf16 v[4:7], v[136:139], v[144:147], v[4:7]
	v_mfma_f32_16x16x32_bf16 v[0:3], v[140:143], v[144:147], v[0:3]
	s_setprio 0
	s_add_u32 s6, s6, 64
	s_addc_u32 s7, s7, 0
	s_mov_b32 s25, 2
	s_cmpk_eq_i32 s6, 0x740
	s_cbranch_scc1 .LBB0_279
	s_branch .Lru_loop_inA

; __device__ __forceinline__ f32x4 mfma16(bf16x8 a, bf16x8 b, f32x4 c) { return __builtin_amdgcn_mfma_f32_16x16x32_bf16(a, b, c, 0, 0, 0); }
; template <int MI, bool SWAP, class Epi> ...
;     ...
;     if (!prefetched) {
;         __syncthreads();
;         RING_STAGE(0, 0);
;         RING_STAGE(1, 32);
;     }
;     int cur = 0;
;     for (int kt = 0; kt < nk; ++kt) {
;         if (kt + 1 < nk && !(prefetched && kt == 0)) { if (MI == 8) asm volatile("s_waitcnt vmcnt(6)\n\ts_barrier" ::: "memory"); else if (MI == 4) asm volatile("s_waitcnt vmcnt(4)\n\ts_barrier" ::: "memory"); else asm volatile("s_waitcnt vmcnt(3)\n\ts_barrier" ::: "memory"); }
;         else asm volatile("s_waitcnt vmcnt(0)\n\ts_barrier" ::: "memory");
;         if (kt + 2 < nk) { const int nx = (cur == 0) ? 2 : cur - 1; RING_STAGE(nx, (kt + 2) * 32); }
;         const int so = cur * STAGEB;
;         bf16x8 bf[4], af[MI];
; #pragma unroll
;         for (int j = 0; j < 4; ++j) bf[j] = *(const bf16x8*)(brdb + so + j * 1024);
; #pragma unroll
;         for (int i = 0; i < MI; ++i) af[i] = *(const bf16x8*)(ardb + so + i * 1024);
;         if (blockIdx.x & 256) __builtin_amdgcn_s_setprio(2); else __builtin_amdgcn_s_setprio(1);
; #pragma unroll
;         for (int i = 0; i < MI; ++i) {
; #pragma unroll
;             for (int j = 0; j < 4; ++j) {
;                 if (SWAP) acc[i][j] = mfma16(bf[j], af[i], acc[i][j]);
;                 else acc[i][j] = mfma16(af[i], bf[j], acc[i][j]);
;             }
;         }
;         __builtin_amdgcn_s_setprio(0);
.LBB0_396:
	s_mul_i32 s6, s22, 0x6000
	s_add_i32 s7, s6, 0xffffa000
	s_cmp_lg_u32 s22, 0
	s_cselect_b32 s7, s7, 0xc000
	v_readlane_b32 vcc_lo, v248, 0
	s_nop 1
	s_bitcmp1_b32 vcc_lo, 3
	s_cbranch_scc0 .Lrp_nostag0_inB
	s_sleep 9
.Lrp_nostag0_inB:
	s_waitcnt vmcnt(6)
	s_barrier
	v_lshl_add_u64 v[128:129], v[178:179], 0, s[4:5]
	s_add_i32 s23, s7, s9
	s_mov_b32 s24, m0
	s_mov_b32 m0, s23
	s_nop 0
	global_load_lds_dwordx4 v[128:129], off
	s_mov_b32 m0, s24
	s_mov_b64 s[30:31], 0x8000
	v_lshl_add_u64 v[130:131], v[128:129], 0, s[30:31]
	s_add_i32 s24, s23, 0x400
	s_mov_b32 s25, m0
	s_mov_b32 m0, s24
	s_nop 0
	global_load_lds_dwordx4 v[130:131], off
	s_mov_b32 m0, s25
	s_mov_b64 s[24:25], 0x10000
	v_lshl_add_u64 v[130:131], v[128:129], 0, s[24:25]
	s_add_i32 s24, s23, 0x800
	s_mov_b32 s25, m0
	s_mov_b32 m0, s24
	s_nop 0
	global_load_lds_dwordx4 v[130:131], off
	s_mov_b32 m0, s25
	s_mov_b64 s[24:25], 0x18000
	v_lshl_add_u64 v[128:129], v[128:129], 0, s[24:25]
	s_addk_i32 s23, 0xc00
	s_mov_b32 s24, m0
	s_mov_b32 m0, s23
	s_nop 0
	global_load_lds_dwordx4 v[128:129], off
	s_mov_b32 m0, s24
	v_lshl_add_u64 v[128:129], v[176:177], 0, s[4:5]
	s_add_i32 s7, s7, s10
	s_mov_b32 s23, m0
	s_mov_b32 m0, s7
	s_nop 0
	global_load_lds_dwordx4 v[128:129], off
	s_mov_b32 m0, s23
	v_lshl_add_u64 v[128:129], v[128:129], 0, s[30:31]
	s_addk_i32 s7, 0x400
	s_mov_b32 s23, m0
	s_mov_b32 m0, s7
	s_nop 0
	global_load_lds_dwordx4 v[128:129], off
	s_mov_b32 m0, s23
	v_add_u32_e32 v140, s6, v223
	v_add_u32_e32 v144, s6, v222
	ds_read_b128 v[128:131], v140 offset:16384
	ds_read_b128 v[132:135], v140 offset:17408
	ds_read_b128 v[136:139], v140 offset:18432
	ds_read_b128 v[140:143], v140 offset:19456
	ds_read_b128 v[172:175], v144
	ds_read_b128 v[168:171], v144 offset:1024
	ds_read_b128 v[164:167], v144 offset:2048
	ds_read_b128 v[160:163], v144 offset:3072
	ds_read_b128 v[156:159], v144 offset:4096
	ds_read_b128 v[152:155], v144 offset:5120
	ds_read_b128 v[148:151], v144 offset:6144
	ds_read_b128 v[144:147], v144 offset:7168
	s_setprio 2
	s_waitcnt lgkmcnt(7)
	v_mfma_f32_16x16x32_bf16 v[124:127], v[172:175], v[128:131], v[124:127]
	v_mfma_f32_16x16x32_bf16 v[120:123], v[172:175], v[132:135], v[120:123]
	v_mfma_f32_16x16x32_bf16 v[116:119], v[172:175], v[136:139], v[116:119]
	v_mfma_f32_16x16x32_bf16 v[112:115], v[172:175], v[140:143], v[112:115]
	s_waitcnt lgkmcnt(6)
	v_mfma_f32_16x16x32_bf16 v[108:111], v[168:171], v[128:131], v[108:111]
	v_mfma_f32_16x16x32_bf16 v[104:107], v[168:171], v[132:135], v[104:107]
	v_mfma_f32_16x16x32_bf16 v[100:103], v[168:171], v[136:139], v[100:103]
	v_mfma_f32_16x16x32_bf16 v[96:99], v[168:171], v[140:143], v[96:99]
	s_waitcnt lgkmcnt(5)
	v_mfma_f32_16x16x32_bf16 v[92:95], v[164:167], v[128:131], v[92:95]
	v_mfma_f32_16x16x32_bf16 v[88:91], v[164:167], v[132:135], v[88:91]
	v_mfma_f32_16x16x32_bf16 v[84:87], v[164:167], v[136:139], v[84:87]
	v_mfma_f32_16x16x32_bf16 v[80:83], v[164:167], v[140:143], v[80:83]
	s_waitcnt lgkmcnt(4)
	v_mfma_f32_16x16x32_bf16 v[76:79], v[160:163], v[128:131], v[76:79]
	v_mfma_f32_16x16x32_bf16 v[72:75], v[160:163], v[132:135], v[72:75]
	v_mfma_f32_16x16x32_bf16 v[68:71], v[160:163], v[136:139], v[68:71]
	v_mfma_f32_16x16x32_bf16 v[64:67], v[160:163], v[140:143], v[64:67]
	s_waitcnt lgkmcnt(3)
	v_mfma_f32_16x16x32_bf16 v[60:63], v[156:159], v[128:131], v[60:63]
	v_mfma_f32_16x16x32_bf16 v[56:59], v[156:159], v[132:135], v[56:59]
	v_mfma_f32_16x16x32_bf16 v[52:55], v[156:159], v[136:139], v[52:55]
	v_mfma_f32_16x16x32_bf16 v[48:51], v[156:159], v[140:143], v[48:51]
	s_waitcnt lgkmcnt(2)
	v_mfma_f32_16x16x32_bf16 v[44:47], v[152:155], v[128:131], v[44:47]
	v_mfma_f32_16x16x32_bf16 v[40:43], v[152:155], v[132:135], v[40:43]
	v_mfma_f32_16x16x32_bf16 v[36:39], v[152:155], v[136:139], v[36:39]
	v_mfma_f32_16x16x32_bf16 v[32:35], v[152:155], v[140:143], v[32:35]
	s_waitcnt lgkmcnt(1)
	v_mfma_f32_16x16x32_bf16 v[28:31], v[148:151], v[128:131], v[28:31]
	v_mfma_f32_16x16x32_bf16 v[24:27], v[148:151], v[132:135], v[24:27]
	v_mfma_f32_16x16x32_bf16 v[20:23], v[148:151], v[136:139], v[20:23]
	v_mfma_f32_16x16x32_bf16 v[16:19], v[148:151], v[140:143], v[16:19]
	s_waitcnt lgkmcnt(0)
	v_mfma_f32_16x16x32_bf16 v[12:15], v[144:147], v[128:131], v[12:15]
	v_mfma_f32_16x16x32_bf16 v[8:11], v[144:147], v[132:135], v[8:11]
	v_mfma_f32_16x16x32_bf16 v[4:7], v[144:147], v[136:139], v[4:7]
	v_mfma_f32_16x16x32_bf16 v[0:3], v[144:147], v[140:143], v[0:3]
	s_setprio 0
	s_add_u32 s4, s4, 64
	s_addc_u32 s5, s5, 0
; __device__ __forceinline__ f32x4 mfma16(bf16x8 a, bf16x8 b, f32x4 c) { return __builtin_amdgcn_mfma_f32_16x16x32_bf16(a, b, c, 0, 0, 0); }
; template <int MI, bool SWAP, class Epi> ...
;     ...
;     for (int kt = 0; kt < nk; ++kt) {
;         if (kt + 1 < nk && !(prefetched && kt == 0)) { if (MI == 8) asm volatile("s_waitcnt vmcnt(6)\n\ts_barrier" ::: "memory"); else if (MI == 4) asm volatile("s_waitcnt vmcnt(4)\n\ts_barrier" ::: "memory"); else asm volatile("s_waitcnt vmcnt(3)\n\ts_barrier" ::: "memory"); }
;         else asm volatile("s_waitcnt vmcnt(0)\n\ts_barrier" ::: "memory");
;         if (kt + 2 < nk) { const int nx = (cur == 0) ? 2 : cur - 1; RING_STAGE(nx, (kt + 2) * 32); }
;         const int so = cur * STAGEB;
;         bf16x8 bf[4], af[MI];
; #pragma unroll
;         for (int j = 0; j < 4; ++j) bf[j] = *(const bf16x8*)(brdb + so + j * 1024);
; #pragma unroll
;         for (int i = 0; i < MI; ++i) af[i] = *(const bf16x8*)(ardb + so + i * 1024);
;         if (blockIdx.x & 256) __builtin_amdgcn_s_setprio(2); else __builtin_amdgcn_s_setprio(1);
; #pragma unroll
;         for (int i = 0; i < MI; ++i) {
; #pragma unroll
;             for (int j = 0; j < 4; ++j) {
;                 if (SWAP) acc[i][j] = mfma16(bf[j], af[i], acc[i][j]);
;                 else acc[i][j] = mfma16(af[i], bf[j], acc[i][j]);
;             }
;         }
;         __builtin_amdgcn_s_setprio(0);
;         cur = (cur == 2) ? 0 : cur + 1;
;     }
.Lru_loop_inB:
	s_mov_b32 s6, 0xc000
	s_mov_b32 s7, 0x6000
	s_waitcnt vmcnt(0)
	s_barrier
	v_add_u32_e32 v140, s6, v223
	v_add_u32_e32 v144, s6, v222
	ds_read_b128 v[128:131], v140 offset:16384
	ds_read_b128 v[132:135], v140 offset:17408
	ds_read_b128 v[136:139], v140 offset:18432
	ds_read_b128 v[140:143], v140 offset:19456
	ds_read_b128 v[172:175], v144
	ds_read_b128 v[168:171], v144 offset:1024
	ds_read_b128 v[164:167], v144 offset:2048
	ds_read_b128 v[160:163], v144 offset:3072
	ds_read_b128 v[156:159], v144 offset:4096
	ds_read_b128 v[152:155], v144 offset:5120
	ds_read_b128 v[148:151], v144 offset:6144
	ds_read_b128 v[144:147], v144 offset:7168
	s_waitcnt lgkmcnt(0)
	s_barrier
	s_setprio 2
	s_sub_i32 vcc_lo, s6, s7
	v_mfma_f32_16x16x32_bf16 v[124:127], v[172:175], v[128:131], v[124:127]
	v_mfma_f32_16x16x32_bf16 v[120:123], v[172:175], v[132:135], v[120:123]
	v_mfma_f32_16x16x32_bf16 v[116:119], v[172:175], v[136:139], v[116:119]
	v_mfma_f32_16x16x32_bf16 v[112:115], v[172:175], v[140:143], v[112:115]
	v_mfma_f32_16x16x32_bf16 v[108:111], v[168:171], v[128:131], v[108:111]
	v_mfma_f32_16x16x32_bf16 v[104:107], v[168:171], v[132:135], v[104:107]
	v_mfma_f32_16x16x32_bf16 v[100:103], v[168:171], v[136:139], v[100:103]
	v_mfma_f32_16x16x32_bf16 v[96:99], v[168:171], v[140:143], v[96:99]
	v_mfma_f32_16x16x32_bf16 v[92:95], v[164:167], v[128:131], v[92:95]
	v_mfma_f32_16x16x32_bf16 v[88:91], v[164:167], v[132:135], v[88:91]
	v_mfma_f32_16x16x32_bf16 v[84:87], v[164:167], v[136:139], v[84:87]
	v_mfma_f32_16x16x32_bf16 v[80:83], v[164:167], v[140:143], v[80:83]
	v_lshl_add_u64 v[172:173], v[178:179], 0, s[4:5]
	s_add_i32 s23, s7, s9
	s_mov_b32 m0, s23
	v_lshl_add_u64 v[168:169], v[172:173], 0, 64
	global_load_lds_dwordx4 v[172:173], off
	s_add_i32 m0, s23, vcc_lo
	s_nop 0
	global_load_lds_dwordx4 v[168:169], off
	s_mov_b64 s[30:31], 0x8000
	v_lshl_add_u64 v[174:175], v[172:173], 0, s[30:31]
	s_add_i32 s24, s23, 0x400
	s_mov_b32 m0, s24
	v_lshl_add_u64 v[168:169], v[174:175], 0, 64
	global_load_lds_dwordx4 v[174:175], off
	s_add_i32 m0, s24, vcc_lo
	s_nop 0
	global_load_lds_dwordx4 v[168:169], off
	s_mov_b64 s[24:25], 0x10000
	v_lshl_add_u64 v[174:175], v[172:173], 0, s[24:25]
	s_add_i32 s24, s23, 0x800
	s_mov_b32 m0, s24
	v_lshl_add_u64 v[168:169], v[174:175], 0, 64
	global_load_lds_dwordx4 v[174:175], off
	s_add_i32 m0, s24, vcc_lo
	s_nop 0
	global_load_lds_dwordx4 v[168:169], off
	s_mov_b64 s[24:25], 0x18000
	v_lshl_add_u64 v[172:173], v[172:173], 0, s[24:25]
	s_addk_i32 s23, 0xc00
	s_mov_b32 m0, s23
	v_lshl_add_u64 v[168:169], v[172:173], 0, 64
	global_load_lds_dwordx4 v[172:173], off
	s_add_i32 m0, s23, vcc_lo
	s_nop 0
	global_load_lds_dwordx4 v[168:169], off
	v_lshl_add_u64 v[172:173], v[176:177], 0, s[4:5]
	s_add_i32 s7, s7, s10
	s_mov_b32 m0, s7
	v_lshl_add_u64 v[168:169], v[172:173], 0, 64
	global_load_lds_dwordx4 v[172:173], off
	s_add_i32 m0, s7, vcc_lo
	s_nop 0
	global_load_lds_dwordx4 v[168:169], off
	v_lshl_add_u64 v[172:173], v[172:173], 0, s[30:31]
	s_addk_i32 s7, 0x400
	s_mov_b32 m0, s7
	v_lshl_add_u64 v[168:169], v[172:173], 0, 64
	global_load_lds_dwordx4 v[172:173], off
	s_add_i32 m0, s7, vcc_lo
	s_nop 0
	global_load_lds_dwordx4 v[168:169], off
	v_mfma_f32_16x16x32_bf16 v[76:79], v[160:163], v[128:131], v[76:79]
	v_mfma_f32_16x16x32_bf16 v[72:75], v[160:163], v[132:135], v[72:75]
	v_mfma_f32_16x16x32_bf16 v[68:71], v[160:163], v[136:139], v[68:71]
	v_mfma_f32_16x16x32_bf16 v[64:67], v[160:163], v[140:143], v[64:67]
	v_mfma_f32_16x16x32_bf16 v[60:63], v[156:159], v[128:131], v[60:63]
	v_mfma_f32_16x16x32_bf16 v[56:59], v[156:159], v[132:135], v[56:59]
	v_mfma_f32_16x16x32_bf16 v[52:55], v[156:159], v[136:139], v[52:55]
	v_mfma_f32_16x16x32_bf16 v[48:51], v[156:159], v[140:143], v[48:51]
	v_mfma_f32_16x16x32_bf16 v[44:47], v[152:155], v[128:131], v[44:47]
	v_mfma_f32_16x16x32_bf16 v[40:43], v[152:155], v[132:135], v[40:43]
	v_mfma_f32_16x16x32_bf16 v[36:39], v[152:155], v[136:139], v[36:39]
	v_mfma_f32_16x16x32_bf16 v[32:35], v[152:155], v[140:143], v[32:35]
	v_mfma_f32_16x16x32_bf16 v[28:31], v[148:151], v[128:131], v[28:31]
	v_mfma_f32_16x16x32_bf16 v[24:27], v[148:151], v[132:135], v[24:27]
	v_mfma_f32_16x16x32_bf16 v[20:23], v[148:151], v[136:139], v[20:23]
	v_mfma_f32_16x16x32_bf16 v[16:19], v[148:151], v[140:143], v[16:19]
	v_mfma_f32_16x16x32_bf16 v[12:15], v[144:147], v[128:131], v[12:15]
	v_mfma_f32_16x16x32_bf16 v[8:11], v[144:147], v[132:135], v[8:11]
	v_mfma_f32_16x16x32_bf16 v[4:7], v[144:147], v[136:139], v[4:7]
	v_mfma_f32_16x16x32_bf16 v[0:3], v[144:147], v[140:143], v[0:3]
	s_setprio 0
	s_add_u32 s4, s4, 64
	s_addc_u32 s5, s5, 0
	s_mov_b32 s6, 0x0
	v_add_u32_e32 v140, s6, v223
	v_add_u32_e32 v144, s6, v222
	ds_read_b128 v[128:131], v140 offset:16384
	ds_read_b128 v[132:135], v140 offset:17408
	ds_read_b128 v[136:139], v140 offset:18432
	ds_read_b128 v[140:143], v140 offset:19456
	ds_read_b128 v[172:175], v144
	ds_read_b128 v[168:171], v144 offset:1024
	ds_read_b128 v[164:167], v144 offset:2048
	ds_read_b128 v[160:163], v144 offset:3072
	ds_read_b128 v[156:159], v144 offset:4096
	ds_read_b128 v[152:155], v144 offset:5120
	ds_read_b128 v[148:151], v144 offset:6144
	ds_read_b128 v[144:147], v144 offset:7168
	s_setprio 2
	s_waitcnt lgkmcnt(7)
	v_mfma_f32_16x16x32_bf16 v[124:127], v[172:175], v[128:131], v[124:127]
	v_mfma_f32_16x16x32_bf16 v[120:123], v[172:175], v[132:135], v[120:123]
	v_mfma_f32_16x16x32_bf16 v[116:119], v[172:175], v[136:139], v[116:119]
	v_mfma_f32_16x16x32_bf16 v[112:115], v[172:175], v[140:143], v[112:115]
	s_waitcnt lgkmcnt(6)
; __device__ __forceinline__ f32x4 mfma16(bf16x8 a, bf16x8 b, f32x4 c) { return __builtin_amdgcn_mfma_f32_16x16x32_bf16(a, b, c, 0, 0, 0); }
; template <int MI, bool SWAP, class Epi> ...
;     ...
;     for (int kt = 0; kt < nk; ++kt) {
;         if (kt + 1 < nk && !(prefetched && kt == 0)) { if (MI == 8) asm volatile("s_waitcnt vmcnt(6)\n\ts_barrier" ::: "memory"); else if (MI == 4) asm volatile("s_waitcnt vmcnt(4)\n\ts_barrier" ::: "memory"); else asm volatile("s_waitcnt vmcnt(3)\n\ts_barrier" ::: "memory"); }
;         else asm volatile("s_waitcnt vmcnt(0)\n\ts_barrier" ::: "memory");
;         if (kt + 2 < nk) { const int nx = (cur == 0) ? 2 : cur - 1; RING_STAGE(nx, (kt + 2) * 32); }
;         const int so = cur * STAGEB;
;         bf16x8 bf[4], af[MI];
; #pragma unroll
;         for (int j = 0; j < 4; ++j) bf[j] = *(const bf16x8*)(brdb + so + j * 1024);
; #pragma unroll
;         for (int i = 0; i < MI; ++i) af[i] = *(const bf16x8*)(ardb + so + i * 1024);
;         if (blockIdx.x & 256) __builtin_amdgcn_s_setprio(2); else __builtin_amdgcn_s_setprio(1);
; #pragma unroll
;         for (int i = 0; i < MI; ++i) {
; #pragma unroll
;             for (int j = 0; j < 4; ++j) {
;                 if (SWAP) acc[i][j] = mfma16(bf[j], af[i], acc[i][j]);
;                 else acc[i][j] = mfma16(af[i], bf[j], acc[i][j]);
;             }
;         }
;         __builtin_amdgcn_s_setprio(0);
;         cur = (cur == 2) ? 0 : cur + 1;
;     }
	v_mfma_f32_16x16x32_bf16 v[108:111], v[168:171], v[128:131], v[108:111]
	v_mfma_f32_16x16x32_bf16 v[104:107], v[168:171], v[132:135], v[104:107]
	v_mfma_f32_16x16x32_bf16 v[100:103], v[168:171], v[136:139], v[100:103]
	v_mfma_f32_16x16x32_bf16 v[96:99], v[168:171], v[140:143], v[96:99]
	s_waitcnt lgkmcnt(5)
	v_mfma_f32_16x16x32_bf16 v[92:95], v[164:167], v[128:131], v[92:95]
	v_mfma_f32_16x16x32_bf16 v[88:91], v[164:167], v[132:135], v[88:91]
	v_mfma_f32_16x16x32_bf16 v[84:87], v[164:167], v[136:139], v[84:87]
	v_mfma_f32_16x16x32_bf16 v[80:83], v[164:167], v[140:143], v[80:83]
	s_waitcnt lgkmcnt(4)
	v_mfma_f32_16x16x32_bf16 v[76:79], v[160:163], v[128:131], v[76:79]
	v_mfma_f32_16x16x32_bf16 v[72:75], v[160:163], v[132:135], v[72:75]
	v_mfma_f32_16x16x32_bf16 v[68:71], v[160:163], v[136:139], v[68:71]
	v_mfma_f32_16x16x32_bf16 v[64:67], v[160:163], v[140:143], v[64:67]
	s_waitcnt lgkmcnt(3)
	v_mfma_f32_16x16x32_bf16 v[60:63], v[156:159], v[128:131], v[60:63]
	v_mfma_f32_16x16x32_bf16 v[56:59], v[156:159], v[132:135], v[56:59]
	v_mfma_f32_16x16x32_bf16 v[52:55], v[156:159], v[136:139], v[52:55]
	v_mfma_f32_16x16x32_bf16 v[48:51], v[156:159], v[140:143], v[48:51]
	s_waitcnt lgkmcnt(2)
	v_mfma_f32_16x16x32_bf16 v[44:47], v[152:155], v[128:131], v[44:47]
	v_mfma_f32_16x16x32_bf16 v[40:43], v[152:155], v[132:135], v[40:43]
	v_mfma_f32_16x16x32_bf16 v[36:39], v[152:155], v[136:139], v[36:39]
	v_mfma_f32_16x16x32_bf16 v[32:35], v[152:155], v[140:143], v[32:35]
	s_waitcnt lgkmcnt(1)
	v_mfma_f32_16x16x32_bf16 v[28:31], v[148:151], v[128:131], v[28:31]
	v_mfma_f32_16x16x32_bf16 v[24:27], v[148:151], v[132:135], v[24:27]
	v_mfma_f32_16x16x32_bf16 v[20:23], v[148:151], v[136:139], v[20:23]
	v_mfma_f32_16x16x32_bf16 v[16:19], v[148:151], v[140:143], v[16:19]
	s_waitcnt lgkmcnt(0)
	v_mfma_f32_16x16x32_bf16 v[12:15], v[144:147], v[128:131], v[12:15]
	v_mfma_f32_16x16x32_bf16 v[8:11], v[144:147], v[132:135], v[8:11]
	v_mfma_f32_16x16x32_bf16 v[4:7], v[144:147], v[136:139], v[4:7]
	v_mfma_f32_16x16x32_bf16 v[0:3], v[144:147], v[140:143], v[0:3]
	s_setprio 0
	s_add_u32 s4, s4, 64
	s_addc_u32 s5, s5, 0
	s_mov_b32 s22, 1
	s_cmpk_eq_i32 s4, 0x740
	s_cbranch_scc1 .LBB0_400
	s_mov_b32 s6, 0x6000
	s_mov_b32 s7, 0x0
	s_waitcnt vmcnt(0)
	s_barrier
	v_add_u32_e32 v140, s6, v223
	v_add_u32_e32 v144, s6, v222
	ds_read_b128 v[128:131], v140 offset:16384
	ds_read_b128 v[132:135], v140 offset:17408
	ds_read_b128 v[136:139], v140 offset:18432
	ds_read_b128 v[140:143], v140 offset:19456
	ds_read_b128 v[172:175], v144
	ds_read_b128 v[168:171], v144 offset:1024
	ds_read_b128 v[164:167], v144 offset:2048
	ds_read_b128 v[160:163], v144 offset:3072
	ds_read_b128 v[156:159], v144 offset:4096
	ds_read_b128 v[152:155], v144 offset:5120
	ds_read_b128 v[148:151], v144 offset:6144
	ds_read_b128 v[144:147], v144 offset:7168
	s_waitcnt lgkmcnt(0)
	s_barrier
	s_setprio 2
	s_sub_i32 vcc_lo, s6, s7
	v_mfma_f32_16x16x32_bf16 v[124:127], v[172:175], v[128:131], v[124:127]
	v_mfma_f32_16x16x32_bf16 v[120:123], v[172:175], v[132:135], v[120:123]
	v_mfma_f32_16x16x32_bf16 v[116:119], v[172:175], v[136:139], v[116:119]
	v_mfma_f32_16x16x32_bf16 v[112:115], v[172:175], v[140:143], v[112:115]
	v_mfma_f32_16x16x32_bf16 v[108:111], v[168:171], v[128:131], v[108:111]
	v_mfma_f32_16x16x32_bf16 v[104:107], v[168:171], v[132:135], v[104:107]
	v_mfma_f32_16x16x32_bf16 v[100:103], v[168:171], v[136:139], v[100:103]
	v_mfma_f32_16x16x32_bf16 v[96:99], v[168:171], v[140:143], v[96:99]
	v_mfma_f32_16x16x32_bf16 v[92:95], v[164:167], v[128:131], v[92:95]
	v_mfma_f32_16x16x32_bf16 v[88:91], v[164:167], v[132:135], v[88:91]
	v_mfma_f32_16x16x32_bf16 v[84:87], v[164:167], v[136:139], v[84:87]
	v_mfma_f32_16x16x32_bf16 v[80:83], v[164:167], v[140:143], v[80:83]
	v_lshl_add_u64 v[172:173], v[178:179], 0, s[4:5]
	s_add_i32 s23, s7, s9
	s_mov_b32 m0, s23
	v_lshl_add_u64 v[168:169], v[172:173], 0, 64
	global_load_lds_dwordx4 v[172:173], off
	s_add_i32 m0, s23, vcc_lo
	s_nop 0
	global_load_lds_dwordx4 v[168:169], off
	s_mov_b64 s[30:31], 0x8000
	v_lshl_add_u64 v[174:175], v[172:173], 0, s[30:31]
	s_add_i32 s24, s23, 0x400
	s_mov_b32 m0, s24
	v_lshl_add_u64 v[168:169], v[174:175], 0, 64
	global_load_lds_dwordx4 v[174:175], off
	s_add_i32 m0, s24, vcc_lo
	s_nop 0
	global_load_lds_dwordx4 v[168:169], off
	s_mov_b64 s[24:25], 0x10000
	v_lshl_add_u64 v[174:175], v[172:173], 0, s[24:25]
	s_add_i32 s24, s23, 0x800
	s_mov_b32 m0, s24
	v_lshl_add_u64 v[168:169], v[174:175], 0, 64
	global_load_lds_dwordx4 v[174:175], off
	s_add_i32 m0, s24, vcc_lo
	s_nop 0
	global_load_lds_dwordx4 v[168:169], off
	s_mov_b64 s[24:25], 0x18000
	v_lshl_add_u64 v[172:173], v[172:173], 0, s[24:25]
	s_addk_i32 s23, 0xc00
	s_mov_b32 m0, s23
	v_lshl_add_u64 v[168:169], v[172:173], 0, 64
	global_load_lds_dwordx4 v[172:173], off
	s_add_i32 m0, s23, vcc_lo
	s_nop 0
	global_load_lds_dwordx4 v[168:169], off
	v_lshl_add_u64 v[172:173], v[176:177], 0, s[4:5]
	s_add_i32 s7, s7, s10
	s_mov_b32 m0, s7
	v_lshl_add_u64 v[168:169], v[172:173], 0, 64
	global_load_lds_dwordx4 v[172:173], off
	s_add_i32 m0, s7, vcc_lo
	s_nop 0
	global_load_lds_dwordx4 v[168:169], off
	v_lshl_add_u64 v[172:173], v[172:173], 0, s[30:31]
	s_addk_i32 s7, 0x400
	s_mov_b32 m0, s7
	v_lshl_add_u64 v[168:169], v[172:173], 0, 64
	global_load_lds_dwordx4 v[172:173], off
	s_add_i32 m0, s7, vcc_lo
	s_nop 0
	global_load_lds_dwordx4 v[168:169], off
	v_mfma_f32_16x16x32_bf16 v[76:79], v[160:163], v[128:131], v[76:79]
	v_mfma_f32_16x16x32_bf16 v[72:75], v[160:163], v[132:135], v[72:75]
	v_mfma_f32_16x16x32_bf16 v[68:71], v[160:163], v[136:139], v[68:71]
	v_mfma_f32_16x16x32_bf16 v[64:67], v[160:163], v[140:143], v[64:67]
; __device__ __forceinline__ f32x4 mfma16(bf16x8 a, bf16x8 b, f32x4 c) { return __builtin_amdgcn_mfma_f32_16x16x32_bf16(a, b, c, 0, 0, 0); }
; template <int MI, bool SWAP, class Epi> ...
;     ...
;     for (int kt = 0; kt < nk; ++kt) {
;         if (kt + 1 < nk && !(prefetched && kt == 0)) { if (MI == 8) asm volatile("s_waitcnt vmcnt(6)\n\ts_barrier" ::: "memory"); else if (MI == 4) asm volatile("s_waitcnt vmcnt(4)\n\ts_barrier" ::: "memory"); else asm volatile("s_waitcnt vmcnt(3)\n\ts_barrier" ::: "memory"); }
;         else asm volatile("s_waitcnt vmcnt(0)\n\ts_barrier" ::: "memory");
;         if (kt + 2 < nk) { const int nx = (cur == 0) ? 2 : cur - 1; RING_STAGE(nx, (kt + 2) * 32); }
;         const int so = cur * STAGEB;
;         bf16x8 bf[4], af[MI];
; #pragma unroll
;         for (int j = 0; j < 4; ++j) bf[j] = *(const bf16x8*)(brdb + so + j * 1024);
; #pragma unroll
;         for (int i = 0; i < MI; ++i) af[i] = *(const bf16x8*)(ardb + so + i * 1024);
;         if (blockIdx.x & 256) __builtin_amdgcn_s_setprio(2); else __builtin_amdgcn_s_setprio(1);
; #pragma unroll
;         for (int i = 0; i < MI; ++i) {
; #pragma unroll
;             for (int j = 0; j < 4; ++j) {
;                 if (SWAP) acc[i][j] = mfma16(bf[j], af[i], acc[i][j]);
;                 else acc[i][j] = mfma16(af[i], bf[j], acc[i][j]);
;             }
;         }
;         __builtin_amdgcn_s_setprio(0);
;         cur = (cur == 2) ? 0 : cur + 1;
;     }
	v_mfma_f32_16x16x32_bf16 v[60:63], v[156:159], v[128:131], v[60:63]
	v_mfma_f32_16x16x32_bf16 v[56:59], v[156:159], v[132:135], v[56:59]
	v_mfma_f32_16x16x32_bf16 v[52:55], v[156:159], v[136:139], v[52:55]
	v_mfma_f32_16x16x32_bf16 v[48:51], v[156:159], v[140:143], v[48:51]
	v_mfma_f32_16x16x32_bf16 v[44:47], v[152:155], v[128:131], v[44:47]
	v_mfma_f32_16x16x32_bf16 v[40:43], v[152:155], v[132:135], v[40:43]
	v_mfma_f32_16x16x32_bf16 v[36:39], v[152:155], v[136:139], v[36:39]
	v_mfma_f32_16x16x32_bf16 v[32:35], v[152:155], v[140:143], v[32:35]
	v_mfma_f32_16x16x32_bf16 v[28:31], v[148:151], v[128:131], v[28:31]
	v_mfma_f32_16x16x32_bf16 v[24:27], v[148:151], v[132:135], v[24:27]
	v_mfma_f32_16x16x32_bf16 v[20:23], v[148:151], v[136:139], v[20:23]
	v_mfma_f32_16x16x32_bf16 v[16:19], v[148:151], v[140:143], v[16:19]
	v_mfma_f32_16x16x32_bf16 v[12:15], v[144:147], v[128:131], v[12:15]
	v_mfma_f32_16x16x32_bf16 v[8:11], v[144:147], v[132:135], v[8:11]
	v_mfma_f32_16x16x32_bf16 v[4:7], v[144:147], v[136:139], v[4:7]
	v_mfma_f32_16x16x32_bf16 v[0:3], v[144:147], v[140:143], v[0:3]
	s_setprio 0
	s_add_u32 s4, s4, 64
	s_addc_u32 s5, s5, 0
	s_mov_b32 s6, 0xc000
	v_add_u32_e32 v140, s6, v223
	v_add_u32_e32 v144, s6, v222
	ds_read_b128 v[128:131], v140 offset:16384
	ds_read_b128 v[132:135], v140 offset:17408
	ds_read_b128 v[136:139], v140 offset:18432
	ds_read_b128 v[140:143], v140 offset:19456
	ds_read_b128 v[172:175], v144
	ds_read_b128 v[168:171], v144 offset:1024
	ds_read_b128 v[164:167], v144 offset:2048
	ds_read_b128 v[160:163], v144 offset:3072
	ds_read_b128 v[156:159], v144 offset:4096
	ds_read_b128 v[152:155], v144 offset:5120
	ds_read_b128 v[148:151], v144 offset:6144
	ds_read_b128 v[144:147], v144 offset:7168
	s_setprio 2
	s_waitcnt lgkmcnt(7)
	v_mfma_f32_16x16x32_bf16 v[124:127], v[172:175], v[128:131], v[124:127]
	v_mfma_f32_16x16x32_bf16 v[120:123], v[172:175], v[132:135], v[120:123]
	v_mfma_f32_16x16x32_bf16 v[116:119], v[172:175], v[136:139], v[116:119]
	v_mfma_f32_16x16x32_bf16 v[112:115], v[172:175], v[140:143], v[112:115]
	s_waitcnt lgkmcnt(6)
	v_mfma_f32_16x16x32_bf16 v[108:111], v[168:171], v[128:131], v[108:111]
	v_mfma_f32_16x16x32_bf16 v[104:107], v[168:171], v[132:135], v[104:107]
	v_mfma_f32_16x16x32_bf16 v[100:103], v[168:171], v[136:139], v[100:103]
	v_mfma_f32_16x16x32_bf16 v[96:99], v[168:171], v[140:143], v[96:99]
	s_waitcnt lgkmcnt(5)
	v_mfma_f32_16x16x32_bf16 v[92:95], v[164:167], v[128:131], v[92:95]
	v_mfma_f32_16x16x32_bf16 v[88:91], v[164:167], v[132:135], v[88:91]
	v_mfma_f32_16x16x32_bf16 v[84:87], v[164:167], v[136:139], v[84:87]
	v_mfma_f32_16x16x32_bf16 v[80:83], v[164:167], v[140:143], v[80:83]
	s_waitcnt lgkmcnt(4)
	v_mfma_f32_16x16x32_bf16 v[76:79], v[160:163], v[128:131], v[76:79]
	v_mfma_f32_16x16x32_bf16 v[72:75], v[160:163], v[132:135], v[72:75]
	v_mfma_f32_16x16x32_bf16 v[68:71], v[160:163], v[136:139], v[68:71]
	v_mfma_f32_16x16x32_bf16 v[64:67], v[160:163], v[140:143], v[64:67]
	s_waitcnt lgkmcnt(3)
	v_mfma_f32_16x16x32_bf16 v[60:63], v[156:159], v[128:131], v[60:63]
	v_mfma_f32_16x16x32_bf16 v[56:59], v[156:159], v[132:135], v[56:59]
	v_mfma_f32_16x16x32_bf16 v[52:55], v[156:159], v[136:139], v[52:55]
	v_mfma_f32_16x16x32_bf16 v[48:51], v[156:159], v[140:143], v[48:51]
	s_waitcnt lgkmcnt(2)
	v_mfma_f32_16x16x32_bf16 v[44:47], v[152:155], v[128:131], v[44:47]
	v_mfma_f32_16x16x32_bf16 v[40:43], v[152:155], v[132:135], v[40:43]
	v_mfma_f32_16x16x32_bf16 v[36:39], v[152:155], v[136:139], v[36:39]
	v_mfma_f32_16x16x32_bf16 v[32:35], v[152:155], v[140:143], v[32:35]
	s_waitcnt lgkmcnt(1)
	v_mfma_f32_16x16x32_bf16 v[28:31], v[148:151], v[128:131], v[28:31]
	v_mfma_f32_16x16x32_bf16 v[24:27], v[148:151], v[132:135], v[24:27]
	v_mfma_f32_16x16x32_bf16 v[20:23], v[148:151], v[136:139], v[20:23]
	v_mfma_f32_16x16x32_bf16 v[16:19], v[148:151], v[140:143], v[16:19]
	s_waitcnt lgkmcnt(0)
	v_mfma_f32_16x16x32_bf16 v[12:15], v[144:147], v[128:131], v[12:15]
	v_mfma_f32_16x16x32_bf16 v[8:11], v[144:147], v[132:135], v[8:11]
	v_mfma_f32_16x16x32_bf16 v[4:7], v[144:147], v[136:139], v[4:7]
	v_mfma_f32_16x16x32_bf16 v[0:3], v[144:147], v[140:143], v[0:3]
	s_setprio 0
	s_add_u32 s4, s4, 64
	s_addc_u32 s5, s5, 0
	s_mov_b32 s22, 0
	s_cmpk_eq_i32 s4, 0x740
	s_cbranch_scc1 .LBB0_400
	s_mov_b32 s6, 0x0
	s_mov_b32 s7, 0xc000
	s_waitcnt vmcnt(0)
	s_barrier
	v_add_u32_e32 v140, s6, v223
	v_add_u32_e32 v144, s6, v222
	ds_read_b128 v[128:131], v140 offset:16384
	ds_read_b128 v[132:135], v140 offset:17408
	ds_read_b128 v[136:139], v140 offset:18432
	ds_read_b128 v[140:143], v140 offset:19456
	ds_read_b128 v[172:175], v144
	ds_read_b128 v[168:171], v144 offset:1024
	ds_read_b128 v[164:167], v144 offset:2048
	ds_read_b128 v[160:163], v144 offset:3072
	ds_read_b128 v[156:159], v144 offset:4096
	ds_read_b128 v[152:155], v144 offset:5120
	ds_read_b128 v[148:151], v144 offset:6144
	ds_read_b128 v[144:147], v144 offset:7168
	s_waitcnt lgkmcnt(0)
	s_barrier
; __device__ __forceinline__ f32x4 mfma16(bf16x8 a, bf16x8 b, f32x4 c) { return __builtin_amdgcn_mfma_f32_16x16x32_bf16(a, b, c, 0, 0, 0); }
; template <int MI, bool SWAP, class Epi> ...
;     ...
;     for (int kt = 0; kt < nk; ++kt) {
;         if (kt + 1 < nk && !(prefetched && kt == 0)) { if (MI == 8) asm volatile("s_waitcnt vmcnt(6)\n\ts_barrier" ::: "memory"); else if (MI == 4) asm volatile("s_waitcnt vmcnt(4)\n\ts_barrier" ::: "memory"); else asm volatile("s_waitcnt vmcnt(3)\n\ts_barrier" ::: "memory"); }
;         else asm volatile("s_waitcnt vmcnt(0)\n\ts_barrier" ::: "memory");
;         if (kt + 2 < nk) { const int nx = (cur == 0) ? 2 : cur - 1; RING_STAGE(nx, (kt + 2) * 32); }
;         const int so = cur * STAGEB;
;         bf16x8 bf[4], af[MI];
; #pragma unroll
;         for (int j = 0; j < 4; ++j) bf[j] = *(const bf16x8*)(brdb + so + j * 1024);
; #pragma unroll
;         for (int i = 0; i < MI; ++i) af[i] = *(const bf16x8*)(ardb + so + i * 1024);
;         if (blockIdx.x & 256) __builtin_amdgcn_s_setprio(2); else __builtin_amdgcn_s_setprio(1);
; #pragma unroll
;         for (int i = 0; i < MI; ++i) {
; #pragma unroll
;             for (int j = 0; j < 4; ++j) {
;                 if (SWAP) acc[i][j] = mfma16(bf[j], af[i], acc[i][j]);
;                 else acc[i][j] = mfma16(af[i], bf[j], acc[i][j]);
;             }
;         }
;         __builtin_amdgcn_s_setprio(0);
;         cur = (cur == 2) ? 0 : cur + 1;
;     }
	s_setprio 2
	s_sub_i32 vcc_lo, s6, s7
	v_mfma_f32_16x16x32_bf16 v[124:127], v[172:175], v[128:131], v[124:127]
	v_mfma_f32_16x16x32_bf16 v[120:123], v[172:175], v[132:135], v[120:123]
	v_mfma_f32_16x16x32_bf16 v[116:119], v[172:175], v[136:139], v[116:119]
	v_mfma_f32_16x16x32_bf16 v[112:115], v[172:175], v[140:143], v[112:115]
	v_mfma_f32_16x16x32_bf16 v[108:111], v[168:171], v[128:131], v[108:111]
	v_mfma_f32_16x16x32_bf16 v[104:107], v[168:171], v[132:135], v[104:107]
	v_mfma_f32_16x16x32_bf16 v[100:103], v[168:171], v[136:139], v[100:103]
	v_mfma_f32_16x16x32_bf16 v[96:99], v[168:171], v[140:143], v[96:99]
	v_mfma_f32_16x16x32_bf16 v[92:95], v[164:167], v[128:131], v[92:95]
	v_mfma_f32_16x16x32_bf16 v[88:91], v[164:167], v[132:135], v[88:91]
	v_mfma_f32_16x16x32_bf16 v[84:87], v[164:167], v[136:139], v[84:87]
	v_mfma_f32_16x16x32_bf16 v[80:83], v[164:167], v[140:143], v[80:83]
	v_lshl_add_u64 v[172:173], v[178:179], 0, s[4:5]
	s_add_i32 s23, s7, s9
	s_mov_b32 m0, s23
	v_lshl_add_u64 v[168:169], v[172:173], 0, 64
	global_load_lds_dwordx4 v[172:173], off
	s_add_i32 m0, s23, vcc_lo
	s_nop 0
	global_load_lds_dwordx4 v[168:169], off
	s_mov_b64 s[30:31], 0x8000
	v_lshl_add_u64 v[174:175], v[172:173], 0, s[30:31]
	s_add_i32 s24, s23, 0x400
	s_mov_b32 m0, s24
	v_lshl_add_u64 v[168:169], v[174:175], 0, 64
	global_load_lds_dwordx4 v[174:175], off
	s_add_i32 m0, s24, vcc_lo
	s_nop 0
	global_load_lds_dwordx4 v[168:169], off
	s_mov_b64 s[24:25], 0x10000
	v_lshl_add_u64 v[174:175], v[172:173], 0, s[24:25]
	s_add_i32 s24, s23, 0x800
	s_mov_b32 m0, s24
	v_lshl_add_u64 v[168:169], v[174:175], 0, 64
	global_load_lds_dwordx4 v[174:175], off
	s_add_i32 m0, s24, vcc_lo
	s_nop 0
	global_load_lds_dwordx4 v[168:169], off
	s_mov_b64 s[24:25], 0x18000
	v_lshl_add_u64 v[172:173], v[172:173], 0, s[24:25]
	s_addk_i32 s23, 0xc00
	s_mov_b32 m0, s23
	v_lshl_add_u64 v[168:169], v[172:173], 0, 64
	global_load_lds_dwordx4 v[172:173], off
	s_add_i32 m0, s23, vcc_lo
	s_nop 0
	global_load_lds_dwordx4 v[168:169], off
	v_lshl_add_u64 v[172:173], v[176:177], 0, s[4:5]
	s_add_i32 s7, s7, s10
	s_mov_b32 m0, s7
	v_lshl_add_u64 v[168:169], v[172:173], 0, 64
	global_load_lds_dwordx4 v[172:173], off
	s_add_i32 m0, s7, vcc_lo
	s_nop 0
	global_load_lds_dwordx4 v[168:169], off
	v_lshl_add_u64 v[172:173], v[172:173], 0, s[30:31]
	s_addk_i32 s7, 0x400
	s_mov_b32 m0, s7
	v_lshl_add_u64 v[168:169], v[172:173], 0, 64
	global_load_lds_dwordx4 v[172:173], off
	s_add_i32 m0, s7, vcc_lo
	s_nop 0
	global_load_lds_dwordx4 v[168:169], off
	v_mfma_f32_16x16x32_bf16 v[76:79], v[160:163], v[128:131], v[76:79]
	v_mfma_f32_16x16x32_bf16 v[72:75], v[160:163], v[132:135], v[72:75]
	v_mfma_f32_16x16x32_bf16 v[68:71], v[160:163], v[136:139], v[68:71]
	v_mfma_f32_16x16x32_bf16 v[64:67], v[160:163], v[140:143], v[64:67]
	v_mfma_f32_16x16x32_bf16 v[60:63], v[156:159], v[128:131], v[60:63]
	v_mfma_f32_16x16x32_bf16 v[56:59], v[156:159], v[132:135], v[56:59]
	v_mfma_f32_16x16x32_bf16 v[52:55], v[156:159], v[136:139], v[52:55]
	v_mfma_f32_16x16x32_bf16 v[48:51], v[156:159], v[140:143], v[48:51]
	v_mfma_f32_16x16x32_bf16 v[44:47], v[152:155], v[128:131], v[44:47]
	v_mfma_f32_16x16x32_bf16 v[40:43], v[152:155], v[132:135], v[40:43]
	v_mfma_f32_16x16x32_bf16 v[36:39], v[152:155], v[136:139], v[36:39]
	v_mfma_f32_16x16x32_bf16 v[32:35], v[152:155], v[140:143], v[32:35]
	v_mfma_f32_16x16x32_bf16 v[28:31], v[148:151], v[128:131], v[28:31]
	v_mfma_f32_16x16x32_bf16 v[24:27], v[148:151], v[132:135], v[24:27]
	v_mfma_f32_16x16x32_bf16 v[20:23], v[148:151], v[136:139], v[20:23]
	v_mfma_f32_16x16x32_bf16 v[16:19], v[148:151], v[140:143], v[16:19]
	v_mfma_f32_16x16x32_bf16 v[12:15], v[144:147], v[128:131], v[12:15]
	v_mfma_f32_16x16x32_bf16 v[8:11], v[144:147], v[132:135], v[8:11]
	v_mfma_f32_16x16x32_bf16 v[4:7], v[144:147], v[136:139], v[4:7]
	v_mfma_f32_16x16x32_bf16 v[0:3], v[144:147], v[140:143], v[0:3]
	s_setprio 0
	s_add_u32 s4, s4, 64
	s_addc_u32 s5, s5, 0
	s_mov_b32 s6, 0x6000
	v_add_u32_e32 v140, s6, v223
	v_add_u32_e32 v144, s6, v222
	ds_read_b128 v[128:131], v140 offset:16384
	ds_read_b128 v[132:135], v140 offset:17408
	ds_read_b128 v[136:139], v140 offset:18432
	ds_read_b128 v[140:143], v140 offset:19456
	ds_read_b128 v[172:175], v144
	ds_read_b128 v[168:171], v144 offset:1024
	ds_read_b128 v[164:167], v144 offset:2048
	ds_read_b128 v[160:163], v144 offset:3072
	ds_read_b128 v[156:159], v144 offset:4096
	ds_read_b128 v[152:155], v144 offset:5120
	ds_read_b128 v[148:151], v144 offset:6144
	ds_read_b128 v[144:147], v144 offset:7168
	s_setprio 2
	s_waitcnt lgkmcnt(7)
; __device__ __forceinline__ f32x4 mfma16(bf16x8 a, bf16x8 b, f32x4 c) { return __builtin_amdgcn_mfma_f32_16x16x32_bf16(a, b, c, 0, 0, 0); }
; template <int MI, bool SWAP, class Epi> ...
;     ...
;     for (int kt = 0; kt < nk; ++kt) {
;         if (kt + 1 < nk && !(prefetched && kt == 0)) { if (MI == 8) asm volatile("s_waitcnt vmcnt(6)\n\ts_barrier" ::: "memory"); else if (MI == 4) asm volatile("s_waitcnt vmcnt(4)\n\ts_barrier" ::: "memory"); else asm volatile("s_waitcnt vmcnt(3)\n\ts_barrier" ::: "memory"); }
;         else asm volatile("s_waitcnt vmcnt(0)\n\ts_barrier" ::: "memory");
;         if (kt + 2 < nk) { const int nx = (cur == 0) ? 2 : cur - 1; RING_STAGE(nx, (kt + 2) * 32); }
;         const int so = cur * STAGEB;
;         bf16x8 bf[4], af[MI];
; #pragma unroll
;         for (int j = 0; j < 4; ++j) bf[j] = *(const bf16x8*)(brdb + so + j * 1024);
; #pragma unroll
;         for (int i = 0; i < MI; ++i) af[i] = *(const bf16x8*)(ardb + so + i * 1024);
;         if (blockIdx.x & 256) __builtin_amdgcn_s_setprio(2); else __builtin_amdgcn_s_setprio(1);
; #pragma unroll
;         for (int i = 0; i < MI; ++i) {
; #pragma unroll
;             for (int j = 0; j < 4; ++j) {
;                 if (SWAP) acc[i][j] = mfma16(bf[j], af[i], acc[i][j]);
;                 else acc[i][j] = mfma16(af[i], bf[j], acc[i][j]);
;             }
;         }
;         __builtin_amdgcn_s_setprio(0);
;         cur = (cur == 2) ? 0 : cur + 1;
;     }
	v_mfma_f32_16x16x32_bf16 v[124:127], v[172:175], v[128:131], v[124:127]
	v_mfma_f32_16x16x32_bf16 v[120:123], v[172:175], v[132:135], v[120:123]
	v_mfma_f32_16x16x32_bf16 v[116:119], v[172:175], v[136:139], v[116:119]
	v_mfma_f32_16x16x32_bf16 v[112:115], v[172:175], v[140:143], v[112:115]
	s_waitcnt lgkmcnt(6)
	v_mfma_f32_16x16x32_bf16 v[108:111], v[168:171], v[128:131], v[108:111]
	v_mfma_f32_16x16x32_bf16 v[104:107], v[168:171], v[132:135], v[104:107]
	v_mfma_f32_16x16x32_bf16 v[100:103], v[168:171], v[136:139], v[100:103]
	v_mfma_f32_16x16x32_bf16 v[96:99], v[168:171], v[140:143], v[96:99]
	s_waitcnt lgkmcnt(5)
	v_mfma_f32_16x16x32_bf16 v[92:95], v[164:167], v[128:131], v[92:95]
	v_mfma_f32_16x16x32_bf16 v[88:91], v[164:167], v[132:135], v[88:91]
	v_mfma_f32_16x16x32_bf16 v[84:87], v[164:167], v[136:139], v[84:87]
	v_mfma_f32_16x16x32_bf16 v[80:83], v[164:167], v[140:143], v[80:83]
	s_waitcnt lgkmcnt(4)
	v_mfma_f32_16x16x32_bf16 v[76:79], v[160:163], v[128:131], v[76:79]
	v_mfma_f32_16x16x32_bf16 v[72:75], v[160:163], v[132:135], v[72:75]
	v_mfma_f32_16x16x32_bf16 v[68:71], v[160:163], v[136:139], v[68:71]
	v_mfma_f32_16x16x32_bf16 v[64:67], v[160:163], v[140:143], v[64:67]
	s_waitcnt lgkmcnt(3)
	v_mfma_f32_16x16x32_bf16 v[60:63], v[156:159], v[128:131], v[60:63]
	v_mfma_f32_16x16x32_bf16 v[56:59], v[156:159], v[132:135], v[56:59]
	v_mfma_f32_16x16x32_bf16 v[52:55], v[156:159], v[136:139], v[52:55]
	v_mfma_f32_16x16x32_bf16 v[48:51], v[156:159], v[140:143], v[48:51]
	s_waitcnt lgkmcnt(2)
	v_mfma_f32_16x16x32_bf16 v[44:47], v[152:155], v[128:131], v[44:47]
	v_mfma_f32_16x16x32_bf16 v[40:43], v[152:155], v[132:135], v[40:43]
	v_mfma_f32_16x16x32_bf16 v[36:39], v[152:155], v[136:139], v[36:39]
	v_mfma_f32_16x16x32_bf16 v[32:35], v[152:155], v[140:143], v[32:35]
	s_waitcnt lgkmcnt(1)
	v_mfma_f32_16x16x32_bf16 v[28:31], v[148:151], v[128:131], v[28:31]
	v_mfma_f32_16x16x32_bf16 v[24:27], v[148:151], v[132:135], v[24:27]
	v_mfma_f32_16x16x32_bf16 v[20:23], v[148:151], v[136:139], v[20:23]
	v_mfma_f32_16x16x32_bf16 v[16:19], v[148:151], v[140:143], v[16:19]
	s_waitcnt lgkmcnt(0)
	v_mfma_f32_16x16x32_bf16 v[12:15], v[144:147], v[128:131], v[12:15]
	v_mfma_f32_16x16x32_bf16 v[8:11], v[144:147], v[132:135], v[8:11]
	v_mfma_f32_16x16x32_bf16 v[4:7], v[144:147], v[136:139], v[4:7]
	v_mfma_f32_16x16x32_bf16 v[0:3], v[144:147], v[140:143], v[0:3]
	s_setprio 0
	s_add_u32 s4, s4, 64
	s_addc_u32 s5, s5, 0
	s_mov_b32 s22, 2
	s_cmpk_eq_i32 s4, 0x740
	s_cbranch_scc1 .LBB0_400
	s_branch .Lru_loop_inB

; __device__ __forceinline__ f32x4 mfma16(bf16x8 a, bf16x8 b, f32x4 c) { return __builtin_amdgcn_mfma_f32_16x16x32_bf16(a, b, c, 0, 0, 0); }
; template <int MI, bool SWAP, class Epi> ...
;     ...
;     if (!prefetched) {
;         __syncthreads();
;         RING_STAGE(0, 0);
;         RING_STAGE(1, 32);
;     }
;     int cur = 0;
;     for (int kt = 0; kt < nk; ++kt) {
;         if (kt + 1 < nk && !(prefetched && kt == 0)) { if (MI == 8) asm volatile("s_waitcnt vmcnt(6)\n\ts_barrier" ::: "memory"); else if (MI == 4) asm volatile("s_waitcnt vmcnt(4)\n\ts_barrier" ::: "memory"); else asm volatile("s_waitcnt vmcnt(3)\n\ts_barrier" ::: "memory"); }
;         else asm volatile("s_waitcnt vmcnt(0)\n\ts_barrier" ::: "memory");
;         if (kt + 2 < nk) { const int nx = (cur == 0) ? 2 : cur - 1; RING_STAGE(nx, (kt + 2) * 32); }
;         const int so = cur * STAGEB;
;         bf16x8 bf[4], af[MI];
; #pragma unroll
;         for (int j = 0; j < 4; ++j) bf[j] = *(const bf16x8*)(brdb + so + j * 1024);
; #pragma unroll
;         for (int i = 0; i < MI; ++i) af[i] = *(const bf16x8*)(ardb + so + i * 1024);
;         if (blockIdx.x & 256) __builtin_amdgcn_s_setprio(2); else __builtin_amdgcn_s_setprio(1);
; #pragma unroll
;         for (int i = 0; i < MI; ++i) {
; #pragma unroll
;             for (int j = 0; j < 4; ++j) {
;                 if (SWAP) acc[i][j] = mfma16(bf[j], af[i], acc[i][j]);
;                 else acc[i][j] = mfma16(af[i], bf[j], acc[i][j]);
;             }
;         }
;         __builtin_amdgcn_s_setprio(0);
.LBB0_1976:
	s_mul_i32 s8, s28, 0x6000
	s_add_i32 s9, s8, 0xffffa000
	s_cmp_lg_u32 s28, 0
	s_cselect_b32 s9, s9, 0xc000
	v_readlane_b32 vcc_lo, v248, 0
	s_nop 1
	s_bitcmp1_b32 vcc_lo, 3
	s_cbranch_scc0 .Lrp_nostag0_outp
	s_sleep 9
.Lrp_nostag0_outp:
	s_waitcnt vmcnt(6)
	s_barrier
	v_lshl_add_u64 v[128:129], v[178:179], 0, s[6:7]
	s_add_i32 s29, s9, s24
	s_mov_b32 s30, m0
	s_mov_b32 m0, s29
	s_nop 0
	global_load_lds_dwordx4 v[128:129], off
	s_mov_b32 m0, s30
	s_mov_b64 s[34:35], 0x8000
	v_lshl_add_u64 v[130:131], v[128:129], 0, s[34:35]
	s_add_i32 s30, s29, 0x400
	s_mov_b32 s31, m0
	s_mov_b32 m0, s30
	s_nop 0
	global_load_lds_dwordx4 v[130:131], off
	s_mov_b32 m0, s31
	s_mov_b64 s[30:31], 0x10000
	v_lshl_add_u64 v[130:131], v[128:129], 0, s[30:31]
	s_add_i32 s30, s29, 0x800
	s_mov_b32 s31, m0
	s_mov_b32 m0, s30
	s_nop 0
	global_load_lds_dwordx4 v[130:131], off
	s_mov_b32 m0, s31
	s_mov_b64 s[30:31], 0x18000
	v_lshl_add_u64 v[128:129], v[128:129], 0, s[30:31]
	s_addk_i32 s29, 0xc00
	s_mov_b32 s30, m0
	s_mov_b32 m0, s29
	s_nop 0
	global_load_lds_dwordx4 v[128:129], off
	s_mov_b32 m0, s30
	v_lshl_add_u64 v[128:129], v[176:177], 0, s[6:7]
	s_add_i32 s9, s9, s25
	s_mov_b32 s29, m0
	s_mov_b32 m0, s9
	s_nop 0
	global_load_lds_dwordx4 v[128:129], off
	s_mov_b32 m0, s29
	v_lshl_add_u64 v[128:129], v[128:129], 0, s[34:35]
	s_addk_i32 s9, 0x400
	s_mov_b32 s29, m0
	s_mov_b32 m0, s9
	s_nop 0
	global_load_lds_dwordx4 v[128:129], off
	s_mov_b32 m0, s29
	v_add_u32_e32 v140, s8, v223
	v_add_u32_e32 v144, s8, v222
	ds_read_b128 v[128:131], v140 offset:16384
	ds_read_b128 v[132:135], v140 offset:17408
	ds_read_b128 v[136:139], v140 offset:18432
	ds_read_b128 v[140:143], v140 offset:19456
	ds_read_b128 v[172:175], v144
	ds_read_b128 v[168:171], v144 offset:1024
	ds_read_b128 v[164:167], v144 offset:2048
	ds_read_b128 v[160:163], v144 offset:3072
	ds_read_b128 v[156:159], v144 offset:4096
	ds_read_b128 v[152:155], v144 offset:5120
	ds_read_b128 v[148:151], v144 offset:6144
	ds_read_b128 v[144:147], v144 offset:7168
	s_setprio 2
	s_waitcnt lgkmcnt(7)
	v_mfma_f32_16x16x32_bf16 v[120:123], v[128:131], v[172:175], v[120:123]
	v_mfma_f32_16x16x32_bf16 v[116:119], v[132:135], v[172:175], v[116:119]
	v_mfma_f32_16x16x32_bf16 v[112:115], v[136:139], v[172:175], v[112:115]
	v_mfma_f32_16x16x32_bf16 v[108:111], v[140:143], v[172:175], v[108:111]
	s_waitcnt lgkmcnt(6)
	v_mfma_f32_16x16x32_bf16 v[104:107], v[128:131], v[168:171], v[104:107]
	v_mfma_f32_16x16x32_bf16 v[100:103], v[132:135], v[168:171], v[100:103]
	v_mfma_f32_16x16x32_bf16 v[96:99], v[136:139], v[168:171], v[96:99]
	v_mfma_f32_16x16x32_bf16 v[92:95], v[140:143], v[168:171], v[92:95]
	s_waitcnt lgkmcnt(5)
	v_mfma_f32_16x16x32_bf16 v[88:91], v[128:131], v[164:167], v[88:91]
	v_mfma_f32_16x16x32_bf16 v[84:87], v[132:135], v[164:167], v[84:87]
	v_mfma_f32_16x16x32_bf16 v[80:83], v[136:139], v[164:167], v[80:83]
	v_mfma_f32_16x16x32_bf16 v[76:79], v[140:143], v[164:167], v[76:79]
	s_waitcnt lgkmcnt(4)
	v_mfma_f32_16x16x32_bf16 v[72:75], v[128:131], v[160:163], v[72:75]
	v_mfma_f32_16x16x32_bf16 v[68:71], v[132:135], v[160:163], v[68:71]
	v_mfma_f32_16x16x32_bf16 v[64:67], v[136:139], v[160:163], v[64:67]
	v_mfma_f32_16x16x32_bf16 v[60:63], v[140:143], v[160:163], v[60:63]
	s_waitcnt lgkmcnt(3)
	v_mfma_f32_16x16x32_bf16 v[56:59], v[128:131], v[156:159], v[56:59]
	v_mfma_f32_16x16x32_bf16 v[52:55], v[132:135], v[156:159], v[52:55]
	v_mfma_f32_16x16x32_bf16 v[48:51], v[136:139], v[156:159], v[48:51]
	v_mfma_f32_16x16x32_bf16 v[44:47], v[140:143], v[156:159], v[44:47]
	s_waitcnt lgkmcnt(2)
	v_mfma_f32_16x16x32_bf16 v[40:43], v[128:131], v[152:155], v[40:43]
	v_mfma_f32_16x16x32_bf16 v[36:39], v[132:135], v[152:155], v[36:39]
	v_mfma_f32_16x16x32_bf16 v[32:35], v[136:139], v[152:155], v[32:35]
	v_mfma_f32_16x16x32_bf16 v[28:31], v[140:143], v[152:155], v[28:31]
	s_waitcnt lgkmcnt(1)
	v_mfma_f32_16x16x32_bf16 v[24:27], v[128:131], v[148:151], v[24:27]
	v_mfma_f32_16x16x32_bf16 v[20:23], v[132:135], v[148:151], v[20:23]
	v_mfma_f32_16x16x32_bf16 v[16:19], v[136:139], v[148:151], v[16:19]
	v_mfma_f32_16x16x32_bf16 v[12:15], v[140:143], v[148:151], v[12:15]
	s_waitcnt lgkmcnt(0)
	v_mfma_f32_16x16x32_bf16 v[8:11], v[128:131], v[144:147], v[8:11]
	v_mfma_f32_16x16x32_bf16 v[4:7], v[132:135], v[144:147], v[4:7]
	v_mfma_f32_16x16x32_bf16 v[0:3], v[136:139], v[144:147], v[0:3]
	v_mfma_f32_16x16x32_bf16 v[124:127], v[140:143], v[144:147], v[124:127]
	s_setprio 0
	s_add_u32 s6, s6, 64
	s_addc_u32 s7, s7, 0
; __device__ __forceinline__ f32x4 mfma16(bf16x8 a, bf16x8 b, f32x4 c) { return __builtin_amdgcn_mfma_f32_16x16x32_bf16(a, b, c, 0, 0, 0); }
; template <int MI, bool SWAP, class Epi> ...
;     ...
;     for (int kt = 0; kt < nk; ++kt) {
;         if (kt + 1 < nk && !(prefetched && kt == 0)) { if (MI == 8) asm volatile("s_waitcnt vmcnt(6)\n\ts_barrier" ::: "memory"); else if (MI == 4) asm volatile("s_waitcnt vmcnt(4)\n\ts_barrier" ::: "memory"); else asm volatile("s_waitcnt vmcnt(3)\n\ts_barrier" ::: "memory"); }
;         else asm volatile("s_waitcnt vmcnt(0)\n\ts_barrier" ::: "memory");
;         if (kt + 2 < nk) { const int nx = (cur == 0) ? 2 : cur - 1; RING_STAGE(nx, (kt + 2) * 32); }
;         const int so = cur * STAGEB;
;         bf16x8 bf[4], af[MI];
; #pragma unroll
;         for (int j = 0; j < 4; ++j) bf[j] = *(const bf16x8*)(brdb + so + j * 1024);
; #pragma unroll
;         for (int i = 0; i < MI; ++i) af[i] = *(const bf16x8*)(ardb + so + i * 1024);
;         if (blockIdx.x & 256) __builtin_amdgcn_s_setprio(2); else __builtin_amdgcn_s_setprio(1);
; #pragma unroll
;         for (int i = 0; i < MI; ++i) {
; #pragma unroll
;             for (int j = 0; j < 4; ++j) {
;                 if (SWAP) acc[i][j] = mfma16(bf[j], af[i], acc[i][j]);
;                 else acc[i][j] = mfma16(af[i], bf[j], acc[i][j]);
;             }
;         }
;         __builtin_amdgcn_s_setprio(0);
;         cur = (cur == 2) ? 0 : cur + 1;
;     }
.Lru_loop_outp:
	s_mov_b32 s8, 0xc000
	s_mov_b32 s9, 0x6000
	s_waitcnt vmcnt(0)
	s_barrier
	v_add_u32_e32 v140, s8, v223
	v_add_u32_e32 v144, s8, v222
	ds_read_b128 v[128:131], v140 offset:16384
	ds_read_b128 v[132:135], v140 offset:17408
	ds_read_b128 v[136:139], v140 offset:18432
	ds_read_b128 v[140:143], v140 offset:19456
	ds_read_b128 v[172:175], v144
	ds_read_b128 v[168:171], v144 offset:1024
	ds_read_b128 v[164:167], v144 offset:2048
	ds_read_b128 v[160:163], v144 offset:3072
	ds_read_b128 v[156:159], v144 offset:4096
	ds_read_b128 v[152:155], v144 offset:5120
	ds_read_b128 v[148:151], v144 offset:6144
	ds_read_b128 v[144:147], v144 offset:7168
	s_waitcnt lgkmcnt(0)
	s_barrier
	s_setprio 2
	s_sub_i32 vcc_lo, s8, s9
	v_mfma_f32_16x16x32_bf16 v[120:123], v[128:131], v[172:175], v[120:123]
	v_mfma_f32_16x16x32_bf16 v[116:119], v[132:135], v[172:175], v[116:119]
	v_mfma_f32_16x16x32_bf16 v[112:115], v[136:139], v[172:175], v[112:115]
	v_mfma_f32_16x16x32_bf16 v[108:111], v[140:143], v[172:175], v[108:111]
	v_mfma_f32_16x16x32_bf16 v[104:107], v[128:131], v[168:171], v[104:107]
	v_mfma_f32_16x16x32_bf16 v[100:103], v[132:135], v[168:171], v[100:103]
	v_mfma_f32_16x16x32_bf16 v[96:99], v[136:139], v[168:171], v[96:99]
	v_mfma_f32_16x16x32_bf16 v[92:95], v[140:143], v[168:171], v[92:95]
	v_mfma_f32_16x16x32_bf16 v[88:91], v[128:131], v[164:167], v[88:91]
	v_mfma_f32_16x16x32_bf16 v[84:87], v[132:135], v[164:167], v[84:87]
	v_mfma_f32_16x16x32_bf16 v[80:83], v[136:139], v[164:167], v[80:83]
	v_mfma_f32_16x16x32_bf16 v[76:79], v[140:143], v[164:167], v[76:79]
	v_lshl_add_u64 v[172:173], v[178:179], 0, s[6:7]
	s_add_i32 s29, s9, s24
	s_mov_b32 m0, s29
	v_lshl_add_u64 v[168:169], v[172:173], 0, 64
	global_load_lds_dwordx4 v[172:173], off
	s_add_i32 m0, s29, vcc_lo
	s_nop 0
	global_load_lds_dwordx4 v[168:169], off
	s_mov_b64 s[34:35], 0x8000
	v_lshl_add_u64 v[174:175], v[172:173], 0, s[34:35]
	s_add_i32 s30, s29, 0x400
	s_mov_b32 m0, s30
	v_lshl_add_u64 v[168:169], v[174:175], 0, 64
	global_load_lds_dwordx4 v[174:175], off
	s_add_i32 m0, s30, vcc_lo
	s_nop 0
	global_load_lds_dwordx4 v[168:169], off
	s_mov_b64 s[30:31], 0x10000
	v_lshl_add_u64 v[174:175], v[172:173], 0, s[30:31]
	s_add_i32 s30, s29, 0x800
	s_mov_b32 m0, s30
	v_lshl_add_u64 v[168:169], v[174:175], 0, 64
	global_load_lds_dwordx4 v[174:175], off
	s_add_i32 m0, s30, vcc_lo
	s_nop 0
	global_load_lds_dwordx4 v[168:169], off
	s_mov_b64 s[30:31], 0x18000
	v_lshl_add_u64 v[172:173], v[172:173], 0, s[30:31]
	s_addk_i32 s29, 0xc00
	s_mov_b32 m0, s29
	v_lshl_add_u64 v[168:169], v[172:173], 0, 64
	global_load_lds_dwordx4 v[172:173], off
	s_add_i32 m0, s29, vcc_lo
	s_nop 0
	global_load_lds_dwordx4 v[168:169], off
	v_lshl_add_u64 v[172:173], v[176:177], 0, s[6:7]
	s_add_i32 s9, s9, s25
	s_mov_b32 m0, s9
	v_lshl_add_u64 v[168:169], v[172:173], 0, 64
	global_load_lds_dwordx4 v[172:173], off
	s_add_i32 m0, s9, vcc_lo
	s_nop 0
	global_load_lds_dwordx4 v[168:169], off
	v_lshl_add_u64 v[172:173], v[172:173], 0, s[34:35]
	s_addk_i32 s9, 0x400
	s_mov_b32 m0, s9
	v_lshl_add_u64 v[168:169], v[172:173], 0, 64
	global_load_lds_dwordx4 v[172:173], off
	s_add_i32 m0, s9, vcc_lo
	s_nop 0
	global_load_lds_dwordx4 v[168:169], off
	v_mfma_f32_16x16x32_bf16 v[72:75], v[128:131], v[160:163], v[72:75]
	v_mfma_f32_16x16x32_bf16 v[68:71], v[132:135], v[160:163], v[68:71]
	v_mfma_f32_16x16x32_bf16 v[64:67], v[136:139], v[160:163], v[64:67]
	v_mfma_f32_16x16x32_bf16 v[60:63], v[140:143], v[160:163], v[60:63]
	v_mfma_f32_16x16x32_bf16 v[56:59], v[128:131], v[156:159], v[56:59]
	v_mfma_f32_16x16x32_bf16 v[52:55], v[132:135], v[156:159], v[52:55]
	v_mfma_f32_16x16x32_bf16 v[48:51], v[136:139], v[156:159], v[48:51]
	v_mfma_f32_16x16x32_bf16 v[44:47], v[140:143], v[156:159], v[44:47]
	v_mfma_f32_16x16x32_bf16 v[40:43], v[128:131], v[152:155], v[40:43]
	v_mfma_f32_16x16x32_bf16 v[36:39], v[132:135], v[152:155], v[36:39]
	v_mfma_f32_16x16x32_bf16 v[32:35], v[136:139], v[152:155], v[32:35]
	v_mfma_f32_16x16x32_bf16 v[28:31], v[140:143], v[152:155], v[28:31]
	v_mfma_f32_16x16x32_bf16 v[24:27], v[128:131], v[148:151], v[24:27]
	v_mfma_f32_16x16x32_bf16 v[20:23], v[132:135], v[148:151], v[20:23]
	v_mfma_f32_16x16x32_bf16 v[16:19], v[136:139], v[148:151], v[16:19]
	v_mfma_f32_16x16x32_bf16 v[12:15], v[140:143], v[148:151], v[12:15]
	v_mfma_f32_16x16x32_bf16 v[8:11], v[128:131], v[144:147], v[8:11]
	v_mfma_f32_16x16x32_bf16 v[4:7], v[132:135], v[144:147], v[4:7]
	v_mfma_f32_16x16x32_bf16 v[0:3], v[136:139], v[144:147], v[0:3]
	v_mfma_f32_16x16x32_bf16 v[124:127], v[140:143], v[144:147], v[124:127]
	s_setprio 0
	s_add_u32 s6, s6, 64
	s_addc_u32 s7, s7, 0
	s_mov_b32 s8, 0x0
	v_add_u32_e32 v140, s8, v223
	v_add_u32_e32 v144, s8, v222
	ds_read_b128 v[128:131], v140 offset:16384
	ds_read_b128 v[132:135], v140 offset:17408
	ds_read_b128 v[136:139], v140 offset:18432
	ds_read_b128 v[140:143], v140 offset:19456
	ds_read_b128 v[172:175], v144
	ds_read_b128 v[168:171], v144 offset:1024
	ds_read_b128 v[164:167], v144 offset:2048
	ds_read_b128 v[160:163], v144 offset:3072
	ds_read_b128 v[156:159], v144 offset:4096
	ds_read_b128 v[152:155], v144 offset:5120
	ds_read_b128 v[148:151], v144 offset:6144
	ds_read_b128 v[144:147], v144 offset:7168
	s_setprio 2
	s_waitcnt lgkmcnt(7)
	v_mfma_f32_16x16x32_bf16 v[120:123], v[128:131], v[172:175], v[120:123]
	v_mfma_f32_16x16x32_bf16 v[116:119], v[132:135], v[172:175], v[116:119]
	v_mfma_f32_16x16x32_bf16 v[112:115], v[136:139], v[172:175], v[112:115]
	v_mfma_f32_16x16x32_bf16 v[108:111], v[140:143], v[172:175], v[108:111]
	s_waitcnt lgkmcnt(6)
; __device__ __forceinline__ f32x4 mfma16(bf16x8 a, bf16x8 b, f32x4 c) { return __builtin_amdgcn_mfma_f32_16x16x32_bf16(a, b, c, 0, 0, 0); }
; template <int MI, bool SWAP, class Epi> ...
;     ...
;     for (int kt = 0; kt < nk; ++kt) {
;         if (kt + 1 < nk && !(prefetched && kt == 0)) { if (MI == 8) asm volatile("s_waitcnt vmcnt(6)\n\ts_barrier" ::: "memory"); else if (MI == 4) asm volatile("s_waitcnt vmcnt(4)\n\ts_barrier" ::: "memory"); else asm volatile("s_waitcnt vmcnt(3)\n\ts_barrier" ::: "memory"); }
;         else asm volatile("s_waitcnt vmcnt(0)\n\ts_barrier" ::: "memory");
;         if (kt + 2 < nk) { const int nx = (cur == 0) ? 2 : cur - 1; RING_STAGE(nx, (kt + 2) * 32); }
;         const int so = cur * STAGEB;
;         bf16x8 bf[4], af[MI];
; #pragma unroll
;         for (int j = 0; j < 4; ++j) bf[j] = *(const bf16x8*)(brdb + so + j * 1024);
; #pragma unroll
;         for (int i = 0; i < MI; ++i) af[i] = *(const bf16x8*)(ardb + so + i * 1024);
;         if (blockIdx.x & 256) __builtin_amdgcn_s_setprio(2); else __builtin_amdgcn_s_setprio(1);
; #pragma unroll
;         for (int i = 0; i < MI; ++i) {
; #pragma unroll
;             for (int j = 0; j < 4; ++j) {
;                 if (SWAP) acc[i][j] = mfma16(bf[j], af[i], acc[i][j]);
;                 else acc[i][j] = mfma16(af[i], bf[j], acc[i][j]);
;             }
;         }
;         __builtin_amdgcn_s_setprio(0);
;         cur = (cur == 2) ? 0 : cur + 1;
;     }
	v_mfma_f32_16x16x32_bf16 v[104:107], v[128:131], v[168:171], v[104:107]
	v_mfma_f32_16x16x32_bf16 v[100:103], v[132:135], v[168:171], v[100:103]
	v_mfma_f32_16x16x32_bf16 v[96:99], v[136:139], v[168:171], v[96:99]
	v_mfma_f32_16x16x32_bf16 v[92:95], v[140:143], v[168:171], v[92:95]
	s_waitcnt lgkmcnt(5)
	v_mfma_f32_16x16x32_bf16 v[88:91], v[128:131], v[164:167], v[88:91]
	v_mfma_f32_16x16x32_bf16 v[84:87], v[132:135], v[164:167], v[84:87]
	v_mfma_f32_16x16x32_bf16 v[80:83], v[136:139], v[164:167], v[80:83]
	v_mfma_f32_16x16x32_bf16 v[76:79], v[140:143], v[164:167], v[76:79]
	s_waitcnt lgkmcnt(4)
	v_mfma_f32_16x16x32_bf16 v[72:75], v[128:131], v[160:163], v[72:75]
	v_mfma_f32_16x16x32_bf16 v[68:71], v[132:135], v[160:163], v[68:71]
	v_mfma_f32_16x16x32_bf16 v[64:67], v[136:139], v[160:163], v[64:67]
	v_mfma_f32_16x16x32_bf16 v[60:63], v[140:143], v[160:163], v[60:63]
	s_waitcnt lgkmcnt(3)
	v_mfma_f32_16x16x32_bf16 v[56:59], v[128:131], v[156:159], v[56:59]
	v_mfma_f32_16x16x32_bf16 v[52:55], v[132:135], v[156:159], v[52:55]
	v_mfma_f32_16x16x32_bf16 v[48:51], v[136:139], v[156:159], v[48:51]
	v_mfma_f32_16x16x32_bf16 v[44:47], v[140:143], v[156:159], v[44:47]
	s_waitcnt lgkmcnt(2)
	v_mfma_f32_16x16x32_bf16 v[40:43], v[128:131], v[152:155], v[40:43]
	v_mfma_f32_16x16x32_bf16 v[36:39], v[132:135], v[152:155], v[36:39]
	v_mfma_f32_16x16x32_bf16 v[32:35], v[136:139], v[152:155], v[32:35]
	v_mfma_f32_16x16x32_bf16 v[28:31], v[140:143], v[152:155], v[28:31]
	s_waitcnt lgkmcnt(1)
	v_mfma_f32_16x16x32_bf16 v[24:27], v[128:131], v[148:151], v[24:27]
	v_mfma_f32_16x16x32_bf16 v[20:23], v[132:135], v[148:151], v[20:23]
	v_mfma_f32_16x16x32_bf16 v[16:19], v[136:139], v[148:151], v[16:19]
	v_mfma_f32_16x16x32_bf16 v[12:15], v[140:143], v[148:151], v[12:15]
	s_waitcnt lgkmcnt(0)
	v_mfma_f32_16x16x32_bf16 v[8:11], v[128:131], v[144:147], v[8:11]
	v_mfma_f32_16x16x32_bf16 v[4:7], v[132:135], v[144:147], v[4:7]
	v_mfma_f32_16x16x32_bf16 v[0:3], v[136:139], v[144:147], v[0:3]
	v_mfma_f32_16x16x32_bf16 v[124:127], v[140:143], v[144:147], v[124:127]
	s_setprio 0
	s_add_u32 s6, s6, 64
	s_addc_u32 s7, s7, 0
	s_mov_b32 s28, 1
	s_cmpk_eq_i32 s6, 0x740
	s_cbranch_scc1 .LBB0_1980
	s_mov_b32 s8, 0x6000
	s_mov_b32 s9, 0x0
	s_waitcnt vmcnt(0)
	s_barrier
	v_add_u32_e32 v140, s8, v223
	v_add_u32_e32 v144, s8, v222
	ds_read_b128 v[128:131], v140 offset:16384
	ds_read_b128 v[132:135], v140 offset:17408
	ds_read_b128 v[136:139], v140 offset:18432
	ds_read_b128 v[140:143], v140 offset:19456
	ds_read_b128 v[172:175], v144
	ds_read_b128 v[168:171], v144 offset:1024
	ds_read_b128 v[164:167], v144 offset:2048
	ds_read_b128 v[160:163], v144 offset:3072
	ds_read_b128 v[156:159], v144 offset:4096
	ds_read_b128 v[152:155], v144 offset:5120
	ds_read_b128 v[148:151], v144 offset:6144
	ds_read_b128 v[144:147], v144 offset:7168
	s_waitcnt lgkmcnt(0)
	s_barrier
	s_setprio 2
	s_sub_i32 vcc_lo, s8, s9
	v_mfma_f32_16x16x32_bf16 v[120:123], v[128:131], v[172:175], v[120:123]
	v_mfma_f32_16x16x32_bf16 v[116:119], v[132:135], v[172:175], v[116:119]
	v_mfma_f32_16x16x32_bf16 v[112:115], v[136:139], v[172:175], v[112:115]
	v_mfma_f32_16x16x32_bf16 v[108:111], v[140:143], v[172:175], v[108:111]
	v_mfma_f32_16x16x32_bf16 v[104:107], v[128:131], v[168:171], v[104:107]
	v_mfma_f32_16x16x32_bf16 v[100:103], v[132:135], v[168:171], v[100:103]
	v_mfma_f32_16x16x32_bf16 v[96:99], v[136:139], v[168:171], v[96:99]
	v_mfma_f32_16x16x32_bf16 v[92:95], v[140:143], v[168:171], v[92:95]
	v_mfma_f32_16x16x32_bf16 v[88:91], v[128:131], v[164:167], v[88:91]
	v_mfma_f32_16x16x32_bf16 v[84:87], v[132:135], v[164:167], v[84:87]
	v_mfma_f32_16x16x32_bf16 v[80:83], v[136:139], v[164:167], v[80:83]
	v_mfma_f32_16x16x32_bf16 v[76:79], v[140:143], v[164:167], v[76:79]
	v_lshl_add_u64 v[172:173], v[178:179], 0, s[6:7]
	s_add_i32 s29, s9, s24
	s_mov_b32 m0, s29
	v_lshl_add_u64 v[168:169], v[172:173], 0, 64
	global_load_lds_dwordx4 v[172:173], off
	s_add_i32 m0, s29, vcc_lo
	s_nop 0
	global_load_lds_dwordx4 v[168:169], off
	s_mov_b64 s[34:35], 0x8000
	v_lshl_add_u64 v[174:175], v[172:173], 0, s[34:35]
	s_add_i32 s30, s29, 0x400
	s_mov_b32 m0, s30
	v_lshl_add_u64 v[168:169], v[174:175], 0, 64
	global_load_lds_dwordx4 v[174:175], off
	s_add_i32 m0, s30, vcc_lo
	s_nop 0
	global_load_lds_dwordx4 v[168:169], off
	s_mov_b64 s[30:31], 0x10000
	v_lshl_add_u64 v[174:175], v[172:173], 0, s[30:31]
	s_add_i32 s30, s29, 0x800
	s_mov_b32 m0, s30
	v_lshl_add_u64 v[168:169], v[174:175], 0, 64
	global_load_lds_dwordx4 v[174:175], off
	s_add_i32 m0, s30, vcc_lo
	s_nop 0
	global_load_lds_dwordx4 v[168:169], off
	s_mov_b64 s[30:31], 0x18000
	v_lshl_add_u64 v[172:173], v[172:173], 0, s[30:31]
	s_addk_i32 s29, 0xc00
	s_mov_b32 m0, s29
	v_lshl_add_u64 v[168:169], v[172:173], 0, 64
	global_load_lds_dwordx4 v[172:173], off
	s_add_i32 m0, s29, vcc_lo
	s_nop 0
	global_load_lds_dwordx4 v[168:169], off
	v_lshl_add_u64 v[172:173], v[176:177], 0, s[6:7]
	s_add_i32 s9, s9, s25
	s_mov_b32 m0, s9
	v_lshl_add_u64 v[168:169], v[172:173], 0, 64
	global_load_lds_dwordx4 v[172:173], off
	s_add_i32 m0, s9, vcc_lo
	s_nop 0
	global_load_lds_dwordx4 v[168:169], off
	v_lshl_add_u64 v[172:173], v[172:173], 0, s[34:35]
	s_addk_i32 s9, 0x400
	s_mov_b32 m0, s9
	v_lshl_add_u64 v[168:169], v[172:173], 0, 64
	global_load_lds_dwordx4 v[172:173], off
	s_add_i32 m0, s9, vcc_lo
	s_nop 0
	global_load_lds_dwordx4 v[168:169], off
	v_mfma_f32_16x16x32_bf16 v[72:75], v[128:131], v[160:163], v[72:75]
	v_mfma_f32_16x16x32_bf16 v[68:71], v[132:135], v[160:163], v[68:71]
	v_mfma_f32_16x16x32_bf16 v[64:67], v[136:139], v[160:163], v[64:67]
	v_mfma_f32_16x16x32_bf16 v[60:63], v[140:143], v[160:163], v[60:63]
; __device__ __forceinline__ f32x4 mfma16(bf16x8 a, bf16x8 b, f32x4 c) { return __builtin_amdgcn_mfma_f32_16x16x32_bf16(a, b, c, 0, 0, 0); }
; template <int MI, bool SWAP, class Epi> ...
;     ...
;     if (!prefetched) {
;         __syncthreads();
;         RING_STAGE(0, 0);
;         RING_STAGE(1, 32);
;     }
;     int cur = 0;
;     for (int kt = 0; kt < nk; ++kt) {
;         if (kt + 1 < nk && !(prefetched && kt == 0)) { if (MI == 8) asm volatile("s_waitcnt vmcnt(6)\n\ts_barrier" ::: "memory"); else if (MI == 4) asm volatile("s_waitcnt vmcnt(4)\n\ts_barrier" ::: "memory"); else asm volatile("s_waitcnt vmcnt(3)\n\ts_barrier" ::: "memory"); }
;         else asm volatile("s_waitcnt vmcnt(0)\n\ts_barrier" ::: "memory");
;         if (kt + 2 < nk) { const int nx = (cur == 0) ? 2 : cur - 1; RING_STAGE(nx, (kt + 2) * 32); }
;         const int so = cur * STAGEB;
;         bf16x8 bf[4], af[MI];
; #pragma unroll
;         for (int j = 0; j < 4; ++j) bf[j] = *(const bf16x8*)(brdb + so + j * 1024);
; #pragma unroll
;         for (int i = 0; i < MI; ++i) af[i] = *(const bf16x8*)(ardb + so + i * 1024);
;         if (blockIdx.x & 256) __builtin_amdgcn_s_setprio(2); else __builtin_amdgcn_s_setprio(1);
; #pragma unroll
;         for (int i = 0; i < MI; ++i) {
; #pragma unroll
;             for (int j = 0; j < 4; ++j) {
;                 if (SWAP) acc[i][j] = mfma16(bf[j], af[i], acc[i][j]);
;                 else acc[i][j] = mfma16(af[i], bf[j], acc[i][j]);
;             }
;         }
;         __builtin_amdgcn_s_setprio(0);
;         cur = (cur == 2) ? 0 : cur + 1;
;     }
	v_mfma_f32_16x16x32_bf16 v[56:59], v[128:131], v[156:159], v[56:59]
	v_mfma_f32_16x16x32_bf16 v[52:55], v[132:135], v[156:159], v[52:55]
	v_mfma_f32_16x16x32_bf16 v[48:51], v[136:139], v[156:159], v[48:51]
	v_mfma_f32_16x16x32_bf16 v[44:47], v[140:143], v[156:159], v[44:47]
	v_mfma_f32_16x16x32_bf16 v[40:43], v[128:131], v[152:155], v[40:43]
	v_mfma_f32_16x16x32_bf16 v[36:39], v[132:135], v[152:155], v[36:39]
	v_mfma_f32_16x16x32_bf16 v[32:35], v[136:139], v[152:155], v[32:35]
	v_mfma_f32_16x16x32_bf16 v[28:31], v[140:143], v[152:155], v[28:31]
	v_mfma_f32_16x16x32_bf16 v[24:27], v[128:131], v[148:151], v[24:27]
	v_mfma_f32_16x16x32_bf16 v[20:23], v[132:135], v[148:151], v[20:23]
	v_mfma_f32_16x16x32_bf16 v[16:19], v[136:139], v[148:151], v[16:19]
	v_mfma_f32_16x16x32_bf16 v[12:15], v[140:143], v[148:151], v[12:15]
	v_mfma_f32_16x16x32_bf16 v[8:11], v[128:131], v[144:147], v[8:11]
	v_mfma_f32_16x16x32_bf16 v[4:7], v[132:135], v[144:147], v[4:7]
	v_mfma_f32_16x16x32_bf16 v[0:3], v[136:139], v[144:147], v[0:3]
	v_mfma_f32_16x16x32_bf16 v[124:127], v[140:143], v[144:147], v[124:127]
	s_setprio 0
	s_add_u32 s6, s6, 64
	s_addc_u32 s7, s7, 0
	s_mov_b32 s8, 0xc000
	v_add_u32_e32 v140, s8, v223
	v_add_u32_e32 v144, s8, v222
	ds_read_b128 v[128:131], v140 offset:16384
	ds_read_b128 v[132:135], v140 offset:17408
	ds_read_b128 v[136:139], v140 offset:18432
	ds_read_b128 v[140:143], v140 offset:19456
	ds_read_b128 v[172:175], v144
	ds_read_b128 v[168:171], v144 offset:1024
	ds_read_b128 v[164:167], v144 offset:2048
	ds_read_b128 v[160:163], v144 offset:3072
	ds_read_b128 v[156:159], v144 offset:4096
	ds_read_b128 v[152:155], v144 offset:5120
	ds_read_b128 v[148:151], v144 offset:6144
	ds_read_b128 v[144:147], v144 offset:7168
	s_setprio 2
	s_waitcnt lgkmcnt(7)
	v_mfma_f32_16x16x32_bf16 v[120:123], v[128:131], v[172:175], v[120:123]
	v_mfma_f32_16x16x32_bf16 v[116:119], v[132:135], v[172:175], v[116:119]
	v_mfma_f32_16x16x32_bf16 v[112:115], v[136:139], v[172:175], v[112:115]
	v_mfma_f32_16x16x32_bf16 v[108:111], v[140:143], v[172:175], v[108:111]
	s_waitcnt lgkmcnt(6)
	v_mfma_f32_16x16x32_bf16 v[104:107], v[128:131], v[168:171], v[104:107]
	v_mfma_f32_16x16x32_bf16 v[100:103], v[132:135], v[168:171], v[100:103]
	v_mfma_f32_16x16x32_bf16 v[96:99], v[136:139], v[168:171], v[96:99]
	v_mfma_f32_16x16x32_bf16 v[92:95], v[140:143], v[168:171], v[92:95]
	s_waitcnt lgkmcnt(5)
	v_mfma_f32_16x16x32_bf16 v[88:91], v[128:131], v[164:167], v[88:91]
	v_mfma_f32_16x16x32_bf16 v[84:87], v[132:135], v[164:167], v[84:87]
	v_mfma_f32_16x16x32_bf16 v[80:83], v[136:139], v[164:167], v[80:83]
	v_mfma_f32_16x16x32_bf16 v[76:79], v[140:143], v[164:167], v[76:79]
	s_waitcnt lgkmcnt(4)
	v_mfma_f32_16x16x32_bf16 v[72:75], v[128:131], v[160:163], v[72:75]
	v_mfma_f32_16x16x32_bf16 v[68:71], v[132:135], v[160:163], v[68:71]
	v_mfma_f32_16x16x32_bf16 v[64:67], v[136:139], v[160:163], v[64:67]
	v_mfma_f32_16x16x32_bf16 v[60:63], v[140:143], v[160:163], v[60:63]
	s_waitcnt lgkmcnt(3)
	v_mfma_f32_16x16x32_bf16 v[56:59], v[128:131], v[156:159], v[56:59]
	v_mfma_f32_16x16x32_bf16 v[52:55], v[132:135], v[156:159], v[52:55]
	v_mfma_f32_16x16x32_bf16 v[48:51], v[136:139], v[156:159], v[48:51]
	v_mfma_f32_16x16x32_bf16 v[44:47], v[140:143], v[156:159], v[44:47]
	s_waitcnt lgkmcnt(2)
	v_mfma_f32_16x16x32_bf16 v[40:43], v[128:131], v[152:155], v[40:43]
	v_mfma_f32_16x16x32_bf16 v[36:39], v[132:135], v[152:155], v[36:39]
	v_mfma_f32_16x16x32_bf16 v[32:35], v[136:139], v[152:155], v[32:35]
	v_mfma_f32_16x16x32_bf16 v[28:31], v[140:143], v[152:155], v[28:31]
	s_waitcnt lgkmcnt(1)
	v_mfma_f32_16x16x32_bf16 v[24:27], v[128:131], v[148:151], v[24:27]
	v_mfma_f32_16x16x32_bf16 v[20:23], v[132:135], v[148:151], v[20:23]
	v_mfma_f32_16x16x32_bf16 v[16:19], v[136:139], v[148:151], v[16:19]
	v_mfma_f32_16x16x32_bf16 v[12:15], v[140:143], v[148:151], v[12:15]
	s_waitcnt lgkmcnt(0)
	v_mfma_f32_16x16x32_bf16 v[8:11], v[128:131], v[144:147], v[8:11]
	v_mfma_f32_16x16x32_bf16 v[4:7], v[132:135], v[144:147], v[4:7]
	v_mfma_f32_16x16x32_bf16 v[0:3], v[136:139], v[144:147], v[0:3]
	v_mfma_f32_16x16x32_bf16 v[124:127], v[140:143], v[144:147], v[124:127]
	s_setprio 0
	s_add_u32 s6, s6, 64
	s_addc_u32 s7, s7, 0
	s_mov_b32 s28, 0
	s_cmpk_eq_i32 s6, 0x740
	s_cbranch_scc1 .LBB0_1980
	s_mov_b32 s8, 0x0
	s_mov_b32 s9, 0xc000
	s_waitcnt vmcnt(0)
	s_barrier
	v_add_u32_e32 v140, s8, v223
	v_add_u32_e32 v144, s8, v222
	ds_read_b128 v[128:131], v140 offset:16384
	ds_read_b128 v[132:135], v140 offset:17408
	ds_read_b128 v[136:139], v140 offset:18432
	ds_read_b128 v[140:143], v140 offset:19456
	ds_read_b128 v[172:175], v144
	ds_read_b128 v[168:171], v144 offset:1024
	ds_read_b128 v[164:167], v144 offset:2048
	ds_read_b128 v[160:163], v144 offset:3072
	ds_read_b128 v[156:159], v144 offset:4096
	ds_read_b128 v[152:155], v144 offset:5120
	ds_read_b128 v[148:151], v144 offset:6144
	ds_read_b128 v[144:147], v144 offset:7168
	s_waitcnt lgkmcnt(0)
	s_barrier
; __device__ __forceinline__ f32x4 mfma16(bf16x8 a, bf16x8 b, f32x4 c) { return __builtin_amdgcn_mfma_f32_16x16x32_bf16(a, b, c, 0, 0, 0); }
; template <int MI, bool SWAP, class Epi> ...
;     ...
;     if (!prefetched) {
;         __syncthreads();
;         RING_STAGE(0, 0);
;         RING_STAGE(1, 32);
;     }
;     int cur = 0;
;     for (int kt = 0; kt < nk; ++kt) {
;         if (kt + 1 < nk && !(prefetched && kt == 0)) { if (MI == 8) asm volatile("s_waitcnt vmcnt(6)\n\ts_barrier" ::: "memory"); else if (MI == 4) asm volatile("s_waitcnt vmcnt(4)\n\ts_barrier" ::: "memory"); else asm volatile("s_waitcnt vmcnt(3)\n\ts_barrier" ::: "memory"); }
;         else asm volatile("s_waitcnt vmcnt(0)\n\ts_barrier" ::: "memory");
;         if (kt + 2 < nk) { const int nx = (cur == 0) ? 2 : cur - 1; RING_STAGE(nx, (kt + 2) * 32); }
;         const int so = cur * STAGEB;
;         bf16x8 bf[4], af[MI];
; #pragma unroll
;         for (int j = 0; j < 4; ++j) bf[j] = *(const bf16x8*)(brdb + so + j * 1024);
; #pragma unroll
;         for (int i = 0; i < MI; ++i) af[i] = *(const bf16x8*)(ardb + so + i * 1024);
;         if (blockIdx.x & 256) __builtin_amdgcn_s_setprio(2); else __builtin_amdgcn_s_setprio(1);
; #pragma unroll
;         for (int i = 0; i < MI; ++i) {
; #pragma unroll
;             for (int j = 0; j < 4; ++j) {
;                 if (SWAP) acc[i][j] = mfma16(bf[j], af[i], acc[i][j]);
;                 else acc[i][j] = mfma16(af[i], bf[j], acc[i][j]);
;             }
;         }
;         __builtin_amdgcn_s_setprio(0);
;         cur = (cur == 2) ? 0 : cur + 1;
;     }
	s_setprio 2
	s_sub_i32 vcc_lo, s8, s9
	v_mfma_f32_16x16x32_bf16 v[120:123], v[128:131], v[172:175], v[120:123]
	v_mfma_f32_16x16x32_bf16 v[116:119], v[132:135], v[172:175], v[116:119]
	v_mfma_f32_16x16x32_bf16 v[112:115], v[136:139], v[172:175], v[112:115]
	v_mfma_f32_16x16x32_bf16 v[108:111], v[140:143], v[172:175], v[108:111]
	v_mfma_f32_16x16x32_bf16 v[104:107], v[128:131], v[168:171], v[104:107]
	v_mfma_f32_16x16x32_bf16 v[100:103], v[132:135], v[168:171], v[100:103]
	v_mfma_f32_16x16x32_bf16 v[96:99], v[136:139], v[168:171], v[96:99]
	v_mfma_f32_16x16x32_bf16 v[92:95], v[140:143], v[168:171], v[92:95]
	v_mfma_f32_16x16x32_bf16 v[88:91], v[128:131], v[164:167], v[88:91]
	v_mfma_f32_16x16x32_bf16 v[84:87], v[132:135], v[164:167], v[84:87]
	v_mfma_f32_16x16x32_bf16 v[80:83], v[136:139], v[164:167], v[80:83]
	v_mfma_f32_16x16x32_bf16 v[76:79], v[140:143], v[164:167], v[76:79]
	v_lshl_add_u64 v[172:173], v[178:179], 0, s[6:7]
	s_add_i32 s29, s9, s24
	s_mov_b32 m0, s29
	v_lshl_add_u64 v[168:169], v[172:173], 0, 64
	global_load_lds_dwordx4 v[172:173], off
	s_add_i32 m0, s29, vcc_lo
	s_nop 0
	global_load_lds_dwordx4 v[168:169], off
	s_mov_b64 s[34:35], 0x8000
	v_lshl_add_u64 v[174:175], v[172:173], 0, s[34:35]
	s_add_i32 s30, s29, 0x400
	s_mov_b32 m0, s30
	v_lshl_add_u64 v[168:169], v[174:175], 0, 64
	global_load_lds_dwordx4 v[174:175], off
	s_add_i32 m0, s30, vcc_lo
	s_nop 0
	global_load_lds_dwordx4 v[168:169], off
	s_mov_b64 s[30:31], 0x10000
	v_lshl_add_u64 v[174:175], v[172:173], 0, s[30:31]
	s_add_i32 s30, s29, 0x800
	s_mov_b32 m0, s30
	v_lshl_add_u64 v[168:169], v[174:175], 0, 64
	global_load_lds_dwordx4 v[174:175], off
	s_add_i32 m0, s30, vcc_lo
	s_nop 0
	global_load_lds_dwordx4 v[168:169], off
	s_mov_b64 s[30:31], 0x18000
	v_lshl_add_u64 v[172:173], v[172:173], 0, s[30:31]
	s_addk_i32 s29, 0xc00
	s_mov_b32 m0, s29
	v_lshl_add_u64 v[168:169], v[172:173], 0, 64
	global_load_lds_dwordx4 v[172:173], off
	s_add_i32 m0, s29, vcc_lo
	s_nop 0
	global_load_lds_dwordx4 v[168:169], off
	v_lshl_add_u64 v[172:173], v[176:177], 0, s[6:7]
	s_add_i32 s9, s9, s25
	s_mov_b32 m0, s9
	v_lshl_add_u64 v[168:169], v[172:173], 0, 64
	global_load_lds_dwordx4 v[172:173], off
	s_add_i32 m0, s9, vcc_lo
	s_nop 0
	global_load_lds_dwordx4 v[168:169], off
	v_lshl_add_u64 v[172:173], v[172:173], 0, s[34:35]
	s_addk_i32 s9, 0x400
	s_mov_b32 m0, s9
	v_lshl_add_u64 v[168:169], v[172:173], 0, 64
	global_load_lds_dwordx4 v[172:173], off
	s_add_i32 m0, s9, vcc_lo
	s_nop 0
	global_load_lds_dwordx4 v[168:169], off
	v_mfma_f32_16x16x32_bf16 v[72:75], v[128:131], v[160:163], v[72:75]
	v_mfma_f32_16x16x32_bf16 v[68:71], v[132:135], v[160:163], v[68:71]
	v_mfma_f32_16x16x32_bf16 v[64:67], v[136:139], v[160:163], v[64:67]
	v_mfma_f32_16x16x32_bf16 v[60:63], v[140:143], v[160:163], v[60:63]
	v_mfma_f32_16x16x32_bf16 v[56:59], v[128:131], v[156:159], v[56:59]
	v_mfma_f32_16x16x32_bf16 v[52:55], v[132:135], v[156:159], v[52:55]
	v_mfma_f32_16x16x32_bf16 v[48:51], v[136:139], v[156:159], v[48:51]
	v_mfma_f32_16x16x32_bf16 v[44:47], v[140:143], v[156:159], v[44:47]
	v_mfma_f32_16x16x32_bf16 v[40:43], v[128:131], v[152:155], v[40:43]
	v_mfma_f32_16x16x32_bf16 v[36:39], v[132:135], v[152:155], v[36:39]
	v_mfma_f32_16x16x32_bf16 v[32:35], v[136:139], v[152:155], v[32:35]
	v_mfma_f32_16x16x32_bf16 v[28:31], v[140:143], v[152:155], v[28:31]
	v_mfma_f32_16x16x32_bf16 v[24:27], v[128:131], v[148:151], v[24:27]
	v_mfma_f32_16x16x32_bf16 v[20:23], v[132:135], v[148:151], v[20:23]
	v_mfma_f32_16x16x32_bf16 v[16:19], v[136:139], v[148:151], v[16:19]
	v_mfma_f32_16x16x32_bf16 v[12:15], v[140:143], v[148:151], v[12:15]
	v_mfma_f32_16x16x32_bf16 v[8:11], v[128:131], v[144:147], v[8:11]
	v_mfma_f32_16x16x32_bf16 v[4:7], v[132:135], v[144:147], v[4:7]
	v_mfma_f32_16x16x32_bf16 v[0:3], v[136:139], v[144:147], v[0:3]
	v_mfma_f32_16x16x32_bf16 v[124:127], v[140:143], v[144:147], v[124:127]
	s_setprio 0
	s_add_u32 s6, s6, 64
	s_addc_u32 s7, s7, 0
	s_mov_b32 s8, 0x6000
	v_add_u32_e32 v140, s8, v223
	v_add_u32_e32 v144, s8, v222
	ds_read_b128 v[128:131], v140 offset:16384
	ds_read_b128 v[132:135], v140 offset:17408
	ds_read_b128 v[136:139], v140 offset:18432
	ds_read_b128 v[140:143], v140 offset:19456
	ds_read_b128 v[172:175], v144
	ds_read_b128 v[168:171], v144 offset:1024
	ds_read_b128 v[164:167], v144 offset:2048
	ds_read_b128 v[160:163], v144 offset:3072
	ds_read_b128 v[156:159], v144 offset:4096
	ds_read_b128 v[152:155], v144 offset:5120
	ds_read_b128 v[148:151], v144 offset:6144
	ds_read_b128 v[144:147], v144 offset:7168
	s_setprio 2
	s_waitcnt lgkmcnt(7)
; __device__ __forceinline__ f32x4 mfma16(bf16x8 a, bf16x8 b, f32x4 c) { return __builtin_amdgcn_mfma_f32_16x16x32_bf16(a, b, c, 0, 0, 0); }
; template <int MI, bool SWAP, class Epi> ...
;     ...
;     for (int kt = 0; kt < nk; ++kt) {
;         if (kt + 1 < nk && !(prefetched && kt == 0)) { if (MI == 8) asm volatile("s_waitcnt vmcnt(6)\n\ts_barrier" ::: "memory"); else if (MI == 4) asm volatile("s_waitcnt vmcnt(4)\n\ts_barrier" ::: "memory"); else asm volatile("s_waitcnt vmcnt(3)\n\ts_barrier" ::: "memory"); }
;         else asm volatile("s_waitcnt vmcnt(0)\n\ts_barrier" ::: "memory");
;         if (kt + 2 < nk) { const int nx = (cur == 0) ? 2 : cur - 1; RING_STAGE(nx, (kt + 2) * 32); }
;         const int so = cur * STAGEB;
;         bf16x8 bf[4], af[MI];
; #pragma unroll
;         for (int j = 0; j < 4; ++j) bf[j] = *(const bf16x8*)(brdb + so + j * 1024);
; #pragma unroll
;         for (int i = 0; i < MI; ++i) af[i] = *(const bf16x8*)(ardb + so + i * 1024);
;         if (blockIdx.x & 256) __builtin_amdgcn_s_setprio(2); else __builtin_amdgcn_s_setprio(1);
; #pragma unroll
;         for (int i = 0; i < MI; ++i) {
; #pragma unroll
;             for (int j = 0; j < 4; ++j) {
;                 if (SWAP) acc[i][j] = mfma16(bf[j], af[i], acc[i][j]);
;                 else acc[i][j] = mfma16(af[i], bf[j], acc[i][j]);
;             }
;         }
;         __builtin_amdgcn_s_setprio(0);
;         cur = (cur == 2) ? 0 : cur + 1;
;     }
	v_mfma_f32_16x16x32_bf16 v[120:123], v[128:131], v[172:175], v[120:123]
	v_mfma_f32_16x16x32_bf16 v[116:119], v[132:135], v[172:175], v[116:119]
	v_mfma_f32_16x16x32_bf16 v[112:115], v[136:139], v[172:175], v[112:115]
	v_mfma_f32_16x16x32_bf16 v[108:111], v[140:143], v[172:175], v[108:111]
	s_waitcnt lgkmcnt(6)
	v_mfma_f32_16x16x32_bf16 v[104:107], v[128:131], v[168:171], v[104:107]
	v_mfma_f32_16x16x32_bf16 v[100:103], v[132:135], v[168:171], v[100:103]
	v_mfma_f32_16x16x32_bf16 v[96:99], v[136:139], v[168:171], v[96:99]
	v_mfma_f32_16x16x32_bf16 v[92:95], v[140:143], v[168:171], v[92:95]
	s_waitcnt lgkmcnt(5)
	v_mfma_f32_16x16x32_bf16 v[88:91], v[128:131], v[164:167], v[88:91]
	v_mfma_f32_16x16x32_bf16 v[84:87], v[132:135], v[164:167], v[84:87]
	v_mfma_f32_16x16x32_bf16 v[80:83], v[136:139], v[164:167], v[80:83]
	v_mfma_f32_16x16x32_bf16 v[76:79], v[140:143], v[164:167], v[76:79]
	s_waitcnt lgkmcnt(4)
	v_mfma_f32_16x16x32_bf16 v[72:75], v[128:131], v[160:163], v[72:75]
	v_mfma_f32_16x16x32_bf16 v[68:71], v[132:135], v[160:163], v[68:71]
	v_mfma_f32_16x16x32_bf16 v[64:67], v[136:139], v[160:163], v[64:67]
	v_mfma_f32_16x16x32_bf16 v[60:63], v[140:143], v[160:163], v[60:63]
	s_waitcnt lgkmcnt(3)
	v_mfma_f32_16x16x32_bf16 v[56:59], v[128:131], v[156:159], v[56:59]
	v_mfma_f32_16x16x32_bf16 v[52:55], v[132:135], v[156:159], v[52:55]
	v_mfma_f32_16x16x32_bf16 v[48:51], v[136:139], v[156:159], v[48:51]
	v_mfma_f32_16x16x32_bf16 v[44:47], v[140:143], v[156:159], v[44:47]
	s_waitcnt lgkmcnt(2)
	v_mfma_f32_16x16x32_bf16 v[40:43], v[128:131], v[152:155], v[40:43]
	v_mfma_f32_16x16x32_bf16 v[36:39], v[132:135], v[152:155], v[36:39]
	v_mfma_f32_16x16x32_bf16 v[32:35], v[136:139], v[152:155], v[32:35]
	v_mfma_f32_16x16x32_bf16 v[28:31], v[140:143], v[152:155], v[28:31]
	s_waitcnt lgkmcnt(1)
	v_mfma_f32_16x16x32_bf16 v[24:27], v[128:131], v[148:151], v[24:27]
	v_mfma_f32_16x16x32_bf16 v[20:23], v[132:135], v[148:151], v[20:23]
	v_mfma_f32_16x16x32_bf16 v[16:19], v[136:139], v[148:151], v[16:19]
	v_mfma_f32_16x16x32_bf16 v[12:15], v[140:143], v[148:151], v[12:15]
	s_waitcnt lgkmcnt(0)
	v_mfma_f32_16x16x32_bf16 v[8:11], v[128:131], v[144:147], v[8:11]
	v_mfma_f32_16x16x32_bf16 v[4:7], v[132:135], v[144:147], v[4:7]
	v_mfma_f32_16x16x32_bf16 v[0:3], v[136:139], v[144:147], v[0:3]
	v_mfma_f32_16x16x32_bf16 v[124:127], v[140:143], v[144:147], v[124:127]
	s_setprio 0
	s_add_u32 s6, s6, 64
	s_addc_u32 s7, s7, 0
	s_mov_b32 s28, 2
	s_cmpk_eq_i32 s6, 0x740
	s_cbranch_scc1 .LBB0_1980
	s_branch .Lru_loop_outp

; __device__ __forceinline__ f32x4 mfma16(bf16x8 a, bf16x8 b, f32x4 c) { return __builtin_amdgcn_mfma_f32_16x16x32_bf16(a, b, c, 0, 0, 0); }
; template <int MI, bool SWAP, class Epi> ...
;     ...
;     if (!prefetched) {
;         __syncthreads();
;         RING_STAGE(0, 0);
;         RING_STAGE(1, 32);
;     }
;     int cur = 0;
;     for (int kt = 0; kt < nk; ++kt) {
;         if (kt + 1 < nk && !(prefetched && kt == 0)) { if (MI == 8) asm volatile("s_waitcnt vmcnt(6)\n\ts_barrier" ::: "memory"); else if (MI == 4) asm volatile("s_waitcnt vmcnt(4)\n\ts_barrier" ::: "memory"); else asm volatile("s_waitcnt vmcnt(3)\n\ts_barrier" ::: "memory"); }
;         else asm volatile("s_waitcnt vmcnt(0)\n\ts_barrier" ::: "memory");
;         if (kt + 2 < nk) { const int nx = (cur == 0) ? 2 : cur - 1; RING_STAGE(nx, (kt + 2) * 32); }
;         const int so = cur * STAGEB;
;         bf16x8 bf[4], af[MI];
; #pragma unroll
;         for (int j = 0; j < 4; ++j) bf[j] = *(const bf16x8*)(brdb + so + j * 1024);
; #pragma unroll
;         for (int i = 0; i < MI; ++i) af[i] = *(const bf16x8*)(ardb + so + i * 1024);
;         if (blockIdx.x & 256) __builtin_amdgcn_s_setprio(2); else __builtin_amdgcn_s_setprio(1);
; #pragma unroll
;         for (int i = 0; i < MI; ++i) {
; #pragma unroll
;             for (int j = 0; j < 4; ++j) {
;                 if (SWAP) acc[i][j] = mfma16(bf[j], af[i], acc[i][j]);
;                 else acc[i][j] = mfma16(af[i], bf[j], acc[i][j]);
;             }
;         }
;         __builtin_amdgcn_s_setprio(0);
;         cur = (cur == 2) ? 0 : cur + 1;
;     }
.LBB0_2193:
	s_mul_i32 s8, s27, 0x6000
	s_add_i32 s9, s8, 0xffffa000
	s_cmp_lg_u32 s27, 0
	s_cselect_b32 s9, s9, 0xc000
	v_readlane_b32 vcc_lo, v248, 0
	s_nop 1
	s_bitcmp1_b32 vcc_lo, 3
	s_cbranch_scc0 .Lrp_nostag0_ff1
	s_sleep 9
.Lrp_nostag0_ff1:
	s_waitcnt vmcnt(6)
	s_barrier
	v_lshl_add_u64 v[128:129], v[178:179], 0, s[6:7]
	s_add_i32 s28, s9, s23
	s_mov_b32 s29, m0
	s_mov_b32 m0, s28
	s_nop 0
	global_load_lds_dwordx4 v[128:129], off
	s_mov_b32 m0, s29
	s_mov_b64 s[12:13], 0x8000
	v_lshl_add_u64 v[130:131], v[128:129], 0, s[12:13]
	s_add_i32 s29, s28, 0x400
	s_mov_b32 s30, m0
	s_mov_b32 m0, s29
	s_nop 0
	global_load_lds_dwordx4 v[130:131], off
	s_mov_b32 m0, s30
	s_mov_b64 s[14:15], 0x10000
	v_lshl_add_u64 v[130:131], v[128:129], 0, s[14:15]
	s_add_i32 s29, s28, 0x800
	s_mov_b32 s30, m0
	s_mov_b32 m0, s29
	s_nop 0
	global_load_lds_dwordx4 v[130:131], off
	s_mov_b32 m0, s30
	s_mov_b64 s[14:15], 0x18000
	v_lshl_add_u64 v[128:129], v[128:129], 0, s[14:15]
	s_addk_i32 s28, 0xc00
	s_mov_b32 s29, m0
	s_mov_b32 m0, s28
	s_nop 0
	global_load_lds_dwordx4 v[128:129], off
	s_mov_b32 m0, s29
	v_lshl_add_u64 v[128:129], v[176:177], 0, s[6:7]
	s_add_i32 s9, s9, s24
	s_mov_b32 s28, m0
	s_mov_b32 m0, s9
	s_nop 0
	global_load_lds_dwordx4 v[128:129], off
	s_mov_b32 m0, s28
	v_lshl_add_u64 v[128:129], v[128:129], 0, s[12:13]
	s_addk_i32 s9, 0x400
	s_mov_b32 s28, m0
	s_mov_b32 m0, s9
	s_nop 0
	global_load_lds_dwordx4 v[128:129], off
	s_mov_b32 m0, s28
	v_add_u32_e32 v140, s8, v223
	v_add_u32_e32 v144, s8, v222
	ds_read_b128 v[128:131], v140 offset:16384
	ds_read_b128 v[132:135], v140 offset:17408
	ds_read_b128 v[136:139], v140 offset:18432
	ds_read_b128 v[140:143], v140 offset:19456
	ds_read_b128 v[172:175], v144
	ds_read_b128 v[168:171], v144 offset:1024
	ds_read_b128 v[164:167], v144 offset:2048
	ds_read_b128 v[160:163], v144 offset:3072
	ds_read_b128 v[156:159], v144 offset:4096
	ds_read_b128 v[152:155], v144 offset:5120
	ds_read_b128 v[148:151], v144 offset:6144
	ds_read_b128 v[144:147], v144 offset:7168
	s_setprio 2
	s_waitcnt lgkmcnt(7)
	v_mfma_f32_16x16x32_bf16 v[120:123], v[128:131], v[172:175], v[120:123]
	v_mfma_f32_16x16x32_bf16 v[116:119], v[132:135], v[172:175], v[116:119]
	v_mfma_f32_16x16x32_bf16 v[112:115], v[136:139], v[172:175], v[112:115]
	v_mfma_f32_16x16x32_bf16 v[108:111], v[140:143], v[172:175], v[108:111]
	s_waitcnt lgkmcnt(6)
	v_mfma_f32_16x16x32_bf16 v[104:107], v[128:131], v[168:171], v[104:107]
	v_mfma_f32_16x16x32_bf16 v[100:103], v[132:135], v[168:171], v[100:103]
	v_mfma_f32_16x16x32_bf16 v[96:99], v[136:139], v[168:171], v[96:99]
	v_mfma_f32_16x16x32_bf16 v[92:95], v[140:143], v[168:171], v[92:95]
	s_waitcnt lgkmcnt(5)
	v_mfma_f32_16x16x32_bf16 v[88:91], v[128:131], v[164:167], v[88:91]
	v_mfma_f32_16x16x32_bf16 v[84:87], v[132:135], v[164:167], v[84:87]
	v_mfma_f32_16x16x32_bf16 v[80:83], v[136:139], v[164:167], v[80:83]
	v_mfma_f32_16x16x32_bf16 v[76:79], v[140:143], v[164:167], v[76:79]
	s_waitcnt lgkmcnt(4)
	v_mfma_f32_16x16x32_bf16 v[72:75], v[128:131], v[160:163], v[72:75]
	v_mfma_f32_16x16x32_bf16 v[68:71], v[132:135], v[160:163], v[68:71]
	v_mfma_f32_16x16x32_bf16 v[64:67], v[136:139], v[160:163], v[64:67]
	v_mfma_f32_16x16x32_bf16 v[60:63], v[140:143], v[160:163], v[60:63]
	s_waitcnt lgkmcnt(3)
	v_mfma_f32_16x16x32_bf16 v[56:59], v[128:131], v[156:159], v[56:59]
	v_mfma_f32_16x16x32_bf16 v[52:55], v[132:135], v[156:159], v[52:55]
	v_mfma_f32_16x16x32_bf16 v[48:51], v[136:139], v[156:159], v[48:51]
	v_mfma_f32_16x16x32_bf16 v[44:47], v[140:143], v[156:159], v[44:47]
	s_waitcnt lgkmcnt(2)
	v_mfma_f32_16x16x32_bf16 v[40:43], v[128:131], v[152:155], v[40:43]
	v_mfma_f32_16x16x32_bf16 v[36:39], v[132:135], v[152:155], v[36:39]
	v_mfma_f32_16x16x32_bf16 v[32:35], v[136:139], v[152:155], v[32:35]
	v_mfma_f32_16x16x32_bf16 v[28:31], v[140:143], v[152:155], v[28:31]
	s_waitcnt lgkmcnt(1)
	v_mfma_f32_16x16x32_bf16 v[24:27], v[128:131], v[148:151], v[24:27]
	v_mfma_f32_16x16x32_bf16 v[20:23], v[132:135], v[148:151], v[20:23]
	v_mfma_f32_16x16x32_bf16 v[16:19], v[136:139], v[148:151], v[16:19]
	v_mfma_f32_16x16x32_bf16 v[12:15], v[140:143], v[148:151], v[12:15]
	s_waitcnt lgkmcnt(0)
	v_mfma_f32_16x16x32_bf16 v[8:11], v[128:131], v[144:147], v[8:11]
	v_mfma_f32_16x16x32_bf16 v[4:7], v[132:135], v[144:147], v[4:7]
	v_mfma_f32_16x16x32_bf16 v[0:3], v[136:139], v[144:147], v[0:3]
	v_mfma_f32_16x16x32_bf16 v[124:127], v[140:143], v[144:147], v[124:127]
	s_setprio 0
	s_add_u32 s6, s6, 64
	s_addc_u32 s7, s7, 0
; __device__ __forceinline__ f32x4 mfma16(bf16x8 a, bf16x8 b, f32x4 c) { return __builtin_amdgcn_mfma_f32_16x16x32_bf16(a, b, c, 0, 0, 0); }
; template <int MI, bool SWAP, class Epi> ...
;     ...
;     if (!prefetched) {
;         __syncthreads();
;         RING_STAGE(0, 0);
;         RING_STAGE(1, 32);
;     }
;     int cur = 0;
;     for (int kt = 0; kt < nk; ++kt) {
;         if (kt + 1 < nk && !(prefetched && kt == 0)) { if (MI == 8) asm volatile("s_waitcnt vmcnt(6)\n\ts_barrier" ::: "memory"); else if (MI == 4) asm volatile("s_waitcnt vmcnt(4)\n\ts_barrier" ::: "memory"); else asm volatile("s_waitcnt vmcnt(3)\n\ts_barrier" ::: "memory"); }
;         else asm volatile("s_waitcnt vmcnt(0)\n\ts_barrier" ::: "memory");
;         if (kt + 2 < nk) { const int nx = (cur == 0) ? 2 : cur - 1; RING_STAGE(nx, (kt + 2) * 32); }
;         const int so = cur * STAGEB;
;         bf16x8 bf[4], af[MI];
; #pragma unroll
;         for (int j = 0; j < 4; ++j) bf[j] = *(const bf16x8*)(brdb + so + j * 1024);
; #pragma unroll
;         for (int i = 0; i < MI; ++i) af[i] = *(const bf16x8*)(ardb + so + i * 1024);
;         if (blockIdx.x & 256) __builtin_amdgcn_s_setprio(2); else __builtin_amdgcn_s_setprio(1);
; #pragma unroll
;         for (int i = 0; i < MI; ++i) {
; #pragma unroll
;             for (int j = 0; j < 4; ++j) {
;                 if (SWAP) acc[i][j] = mfma16(bf[j], af[i], acc[i][j]);
;                 else acc[i][j] = mfma16(af[i], bf[j], acc[i][j]);
;             }
;         }
;         __builtin_amdgcn_s_setprio(0);
;         cur = (cur == 2) ? 0 : cur + 1;
;     }
.Lru_loop_ff1:
	s_mov_b32 s8, 0xc000
	s_mov_b32 s9, 0x6000
	s_waitcnt vmcnt(0)
	s_barrier
	v_add_u32_e32 v140, s8, v223
	v_add_u32_e32 v144, s8, v222
	ds_read_b128 v[128:131], v140 offset:16384
	ds_read_b128 v[132:135], v140 offset:17408
	ds_read_b128 v[136:139], v140 offset:18432
	ds_read_b128 v[140:143], v140 offset:19456
	ds_read_b128 v[172:175], v144
	ds_read_b128 v[168:171], v144 offset:1024
	ds_read_b128 v[164:167], v144 offset:2048
	ds_read_b128 v[160:163], v144 offset:3072
	ds_read_b128 v[156:159], v144 offset:4096
	ds_read_b128 v[152:155], v144 offset:5120
	ds_read_b128 v[148:151], v144 offset:6144
	ds_read_b128 v[144:147], v144 offset:7168
	s_waitcnt lgkmcnt(0)
	s_barrier
	s_setprio 2
	s_sub_i32 vcc_lo, s8, s9
	v_mfma_f32_16x16x32_bf16 v[120:123], v[128:131], v[172:175], v[120:123]
	v_mfma_f32_16x16x32_bf16 v[116:119], v[132:135], v[172:175], v[116:119]
	v_mfma_f32_16x16x32_bf16 v[112:115], v[136:139], v[172:175], v[112:115]
	v_mfma_f32_16x16x32_bf16 v[108:111], v[140:143], v[172:175], v[108:111]
	v_mfma_f32_16x16x32_bf16 v[104:107], v[128:131], v[168:171], v[104:107]
	v_mfma_f32_16x16x32_bf16 v[100:103], v[132:135], v[168:171], v[100:103]
	v_mfma_f32_16x16x32_bf16 v[96:99], v[136:139], v[168:171], v[96:99]
	v_mfma_f32_16x16x32_bf16 v[92:95], v[140:143], v[168:171], v[92:95]
	v_mfma_f32_16x16x32_bf16 v[88:91], v[128:131], v[164:167], v[88:91]
	v_mfma_f32_16x16x32_bf16 v[84:87], v[132:135], v[164:167], v[84:87]
	v_mfma_f32_16x16x32_bf16 v[80:83], v[136:139], v[164:167], v[80:83]
	v_mfma_f32_16x16x32_bf16 v[76:79], v[140:143], v[164:167], v[76:79]
	v_lshl_add_u64 v[172:173], v[178:179], 0, s[6:7]
	s_add_i32 s28, s9, s23
	s_mov_b32 m0, s28
	v_lshl_add_u64 v[168:169], v[172:173], 0, 64
	global_load_lds_dwordx4 v[172:173], off
	s_add_i32 m0, s28, vcc_lo
	s_nop 0
	global_load_lds_dwordx4 v[168:169], off
	s_mov_b64 s[12:13], 0x8000
	v_lshl_add_u64 v[174:175], v[172:173], 0, s[12:13]
	s_add_i32 s29, s28, 0x400
	s_mov_b32 m0, s29
	v_lshl_add_u64 v[168:169], v[174:175], 0, 64
	global_load_lds_dwordx4 v[174:175], off
	s_add_i32 m0, s29, vcc_lo
	s_nop 0
	global_load_lds_dwordx4 v[168:169], off
	s_mov_b64 s[14:15], 0x10000
	v_lshl_add_u64 v[174:175], v[172:173], 0, s[14:15]
	s_add_i32 s29, s28, 0x800
	s_mov_b32 m0, s29
	v_lshl_add_u64 v[168:169], v[174:175], 0, 64
	global_load_lds_dwordx4 v[174:175], off
	s_add_i32 m0, s29, vcc_lo
	s_nop 0
	global_load_lds_dwordx4 v[168:169], off
	s_mov_b64 s[14:15], 0x18000
	v_lshl_add_u64 v[172:173], v[172:173], 0, s[14:15]
	s_addk_i32 s28, 0xc00
	s_mov_b32 m0, s28
	v_lshl_add_u64 v[168:169], v[172:173], 0, 64
	global_load_lds_dwordx4 v[172:173], off
	s_add_i32 m0, s28, vcc_lo
	s_nop 0
	global_load_lds_dwordx4 v[168:169], off
	v_lshl_add_u64 v[172:173], v[176:177], 0, s[6:7]
	s_add_i32 s9, s9, s24
	s_mov_b32 m0, s9
	v_lshl_add_u64 v[168:169], v[172:173], 0, 64
	global_load_lds_dwordx4 v[172:173], off
	s_add_i32 m0, s9, vcc_lo
	s_nop 0
	global_load_lds_dwordx4 v[168:169], off
	v_lshl_add_u64 v[172:173], v[172:173], 0, s[12:13]
	s_addk_i32 s9, 0x400
	s_mov_b32 m0, s9
	v_lshl_add_u64 v[168:169], v[172:173], 0, 64
	global_load_lds_dwordx4 v[172:173], off
	s_add_i32 m0, s9, vcc_lo
	s_nop 0
	global_load_lds_dwordx4 v[168:169], off
	v_mfma_f32_16x16x32_bf16 v[72:75], v[128:131], v[160:163], v[72:75]
	v_mfma_f32_16x16x32_bf16 v[68:71], v[132:135], v[160:163], v[68:71]
	v_mfma_f32_16x16x32_bf16 v[64:67], v[136:139], v[160:163], v[64:67]
	v_mfma_f32_16x16x32_bf16 v[60:63], v[140:143], v[160:163], v[60:63]
	v_mfma_f32_16x16x32_bf16 v[56:59], v[128:131], v[156:159], v[56:59]
	v_mfma_f32_16x16x32_bf16 v[52:55], v[132:135], v[156:159], v[52:55]
	v_mfma_f32_16x16x32_bf16 v[48:51], v[136:139], v[156:159], v[48:51]
	v_mfma_f32_16x16x32_bf16 v[44:47], v[140:143], v[156:159], v[44:47]
	v_mfma_f32_16x16x32_bf16 v[40:43], v[128:131], v[152:155], v[40:43]
	v_mfma_f32_16x16x32_bf16 v[36:39], v[132:135], v[152:155], v[36:39]
	v_mfma_f32_16x16x32_bf16 v[32:35], v[136:139], v[152:155], v[32:35]
	v_mfma_f32_16x16x32_bf16 v[28:31], v[140:143], v[152:155], v[28:31]
	v_mfma_f32_16x16x32_bf16 v[24:27], v[128:131], v[148:151], v[24:27]
	v_mfma_f32_16x16x32_bf16 v[20:23], v[132:135], v[148:151], v[20:23]
	v_mfma_f32_16x16x32_bf16 v[16:19], v[136:139], v[148:151], v[16:19]
	v_mfma_f32_16x16x32_bf16 v[12:15], v[140:143], v[148:151], v[12:15]
	v_mfma_f32_16x16x32_bf16 v[8:11], v[128:131], v[144:147], v[8:11]
	v_mfma_f32_16x16x32_bf16 v[4:7], v[132:135], v[144:147], v[4:7]
	v_mfma_f32_16x16x32_bf16 v[0:3], v[136:139], v[144:147], v[0:3]
	v_mfma_f32_16x16x32_bf16 v[124:127], v[140:143], v[144:147], v[124:127]
	s_setprio 0
	s_add_u32 s6, s6, 64
	s_addc_u32 s7, s7, 0
	s_mov_b32 s8, 0x0
	v_add_u32_e32 v140, s8, v223
	v_add_u32_e32 v144, s8, v222
	ds_read_b128 v[128:131], v140 offset:16384
	ds_read_b128 v[132:135], v140 offset:17408
	ds_read_b128 v[136:139], v140 offset:18432
	ds_read_b128 v[140:143], v140 offset:19456
	ds_read_b128 v[172:175], v144
	ds_read_b128 v[168:171], v144 offset:1024
	ds_read_b128 v[164:167], v144 offset:2048
	ds_read_b128 v[160:163], v144 offset:3072
	ds_read_b128 v[156:159], v144 offset:4096
	ds_read_b128 v[152:155], v144 offset:5120
	ds_read_b128 v[148:151], v144 offset:6144
	ds_read_b128 v[144:147], v144 offset:7168
	s_setprio 2
	s_waitcnt lgkmcnt(7)
	v_mfma_f32_16x16x32_bf16 v[120:123], v[128:131], v[172:175], v[120:123]
	v_mfma_f32_16x16x32_bf16 v[116:119], v[132:135], v[172:175], v[116:119]
	v_mfma_f32_16x16x32_bf16 v[112:115], v[136:139], v[172:175], v[112:115]
	v_mfma_f32_16x16x32_bf16 v[108:111], v[140:143], v[172:175], v[108:111]
	s_waitcnt lgkmcnt(6)
; __device__ __forceinline__ f32x4 mfma16(bf16x8 a, bf16x8 b, f32x4 c) { return __builtin_amdgcn_mfma_f32_16x16x32_bf16(a, b, c, 0, 0, 0); }
; template <int MI, bool SWAP, class Epi> ...
;     ...
;     if (!prefetched) {
;         __syncthreads();
;         RING_STAGE(0, 0);
;         RING_STAGE(1, 32);
;     }
;     int cur = 0;
;     for (int kt = 0; kt < nk; ++kt) {
;         if (kt + 1 < nk && !(prefetched && kt == 0)) { if (MI == 8) asm volatile("s_waitcnt vmcnt(6)\n\ts_barrier" ::: "memory"); else if (MI == 4) asm volatile("s_waitcnt vmcnt(4)\n\ts_barrier" ::: "memory"); else asm volatile("s_waitcnt vmcnt(3)\n\ts_barrier" ::: "memory"); }
;         else asm volatile("s_waitcnt vmcnt(0)\n\ts_barrier" ::: "memory");
;         if (kt + 2 < nk) { const int nx = (cur == 0) ? 2 : cur - 1; RING_STAGE(nx, (kt + 2) * 32); }
;         const int so = cur * STAGEB;
;         bf16x8 bf[4], af[MI];
; #pragma unroll
;         for (int j = 0; j < 4; ++j) bf[j] = *(const bf16x8*)(brdb + so + j * 1024);
; #pragma unroll
;         for (int i = 0; i < MI; ++i) af[i] = *(const bf16x8*)(ardb + so + i * 1024);
;         if (blockIdx.x & 256) __builtin_amdgcn_s_setprio(2); else __builtin_amdgcn_s_setprio(1);
; #pragma unroll
;         for (int i = 0; i < MI; ++i) {
; #pragma unroll
;             for (int j = 0; j < 4; ++j) {
;                 if (SWAP) acc[i][j] = mfma16(bf[j], af[i], acc[i][j]);
;                 else acc[i][j] = mfma16(af[i], bf[j], acc[i][j]);
;             }
;         }
;         __builtin_amdgcn_s_setprio(0);
;         cur = (cur == 2) ? 0 : cur + 1;
;     }
	v_mfma_f32_16x16x32_bf16 v[104:107], v[128:131], v[168:171], v[104:107]
	v_mfma_f32_16x16x32_bf16 v[100:103], v[132:135], v[168:171], v[100:103]
	v_mfma_f32_16x16x32_bf16 v[96:99], v[136:139], v[168:171], v[96:99]
	v_mfma_f32_16x16x32_bf16 v[92:95], v[140:143], v[168:171], v[92:95]
	s_waitcnt lgkmcnt(5)
	v_mfma_f32_16x16x32_bf16 v[88:91], v[128:131], v[164:167], v[88:91]
	v_mfma_f32_16x16x32_bf16 v[84:87], v[132:135], v[164:167], v[84:87]
	v_mfma_f32_16x16x32_bf16 v[80:83], v[136:139], v[164:167], v[80:83]
	v_mfma_f32_16x16x32_bf16 v[76:79], v[140:143], v[164:167], v[76:79]
	s_waitcnt lgkmcnt(4)
	v_mfma_f32_16x16x32_bf16 v[72:75], v[128:131], v[160:163], v[72:75]
	v_mfma_f32_16x16x32_bf16 v[68:71], v[132:135], v[160:163], v[68:71]
	v_mfma_f32_16x16x32_bf16 v[64:67], v[136:139], v[160:163], v[64:67]
	v_mfma_f32_16x16x32_bf16 v[60:63], v[140:143], v[160:163], v[60:63]
	s_waitcnt lgkmcnt(3)
	v_mfma_f32_16x16x32_bf16 v[56:59], v[128:131], v[156:159], v[56:59]
	v_mfma_f32_16x16x32_bf16 v[52:55], v[132:135], v[156:159], v[52:55]
	v_mfma_f32_16x16x32_bf16 v[48:51], v[136:139], v[156:159], v[48:51]
	v_mfma_f32_16x16x32_bf16 v[44:47], v[140:143], v[156:159], v[44:47]
	s_waitcnt lgkmcnt(2)
	v_mfma_f32_16x16x32_bf16 v[40:43], v[128:131], v[152:155], v[40:43]
	v_mfma_f32_16x16x32_bf16 v[36:39], v[132:135], v[152:155], v[36:39]
	v_mfma_f32_16x16x32_bf16 v[32:35], v[136:139], v[152:155], v[32:35]
	v_mfma_f32_16x16x32_bf16 v[28:31], v[140:143], v[152:155], v[28:31]
	s_waitcnt lgkmcnt(1)
	v_mfma_f32_16x16x32_bf16 v[24:27], v[128:131], v[148:151], v[24:27]
	v_mfma_f32_16x16x32_bf16 v[20:23], v[132:135], v[148:151], v[20:23]
	v_mfma_f32_16x16x32_bf16 v[16:19], v[136:139], v[148:151], v[16:19]
	v_mfma_f32_16x16x32_bf16 v[12:15], v[140:143], v[148:151], v[12:15]
	s_waitcnt lgkmcnt(0)
	v_mfma_f32_16x16x32_bf16 v[8:11], v[128:131], v[144:147], v[8:11]
	v_mfma_f32_16x16x32_bf16 v[4:7], v[132:135], v[144:147], v[4:7]
	v_mfma_f32_16x16x32_bf16 v[0:3], v[136:139], v[144:147], v[0:3]
	v_mfma_f32_16x16x32_bf16 v[124:127], v[140:143], v[144:147], v[124:127]
	s_setprio 0
	s_add_u32 s6, s6, 64
	s_addc_u32 s7, s7, 0
	s_mov_b32 s27, 1
	s_cmpk_eq_i32 s6, 0x740
	s_cbranch_scc1 .LBB0_2197
	s_mov_b32 s8, 0x6000
	s_mov_b32 s9, 0x0
	s_waitcnt vmcnt(0)
	s_barrier
	v_add_u32_e32 v140, s8, v223
	v_add_u32_e32 v144, s8, v222
	ds_read_b128 v[128:131], v140 offset:16384
	ds_read_b128 v[132:135], v140 offset:17408
	ds_read_b128 v[136:139], v140 offset:18432
	ds_read_b128 v[140:143], v140 offset:19456
	ds_read_b128 v[172:175], v144
	ds_read_b128 v[168:171], v144 offset:1024
	ds_read_b128 v[164:167], v144 offset:2048
	ds_read_b128 v[160:163], v144 offset:3072
	ds_read_b128 v[156:159], v144 offset:4096
	ds_read_b128 v[152:155], v144 offset:5120
	ds_read_b128 v[148:151], v144 offset:6144
	ds_read_b128 v[144:147], v144 offset:7168
	s_waitcnt lgkmcnt(0)
	s_barrier
	s_setprio 2
	s_sub_i32 vcc_lo, s8, s9
	v_mfma_f32_16x16x32_bf16 v[120:123], v[128:131], v[172:175], v[120:123]
	v_mfma_f32_16x16x32_bf16 v[116:119], v[132:135], v[172:175], v[116:119]
	v_mfma_f32_16x16x32_bf16 v[112:115], v[136:139], v[172:175], v[112:115]
	v_mfma_f32_16x16x32_bf16 v[108:111], v[140:143], v[172:175], v[108:111]
	v_mfma_f32_16x16x32_bf16 v[104:107], v[128:131], v[168:171], v[104:107]
	v_mfma_f32_16x16x32_bf16 v[100:103], v[132:135], v[168:171], v[100:103]
	v_mfma_f32_16x16x32_bf16 v[96:99], v[136:139], v[168:171], v[96:99]
	v_mfma_f32_16x16x32_bf16 v[92:95], v[140:143], v[168:171], v[92:95]
	v_mfma_f32_16x16x32_bf16 v[88:91], v[128:131], v[164:167], v[88:91]
	v_mfma_f32_16x16x32_bf16 v[84:87], v[132:135], v[164:167], v[84:87]
	v_mfma_f32_16x16x32_bf16 v[80:83], v[136:139], v[164:167], v[80:83]
	v_mfma_f32_16x16x32_bf16 v[76:79], v[140:143], v[164:167], v[76:79]
	v_lshl_add_u64 v[172:173], v[178:179], 0, s[6:7]
	s_add_i32 s28, s9, s23
	s_mov_b32 m0, s28
	v_lshl_add_u64 v[168:169], v[172:173], 0, 64
	global_load_lds_dwordx4 v[172:173], off
	s_add_i32 m0, s28, vcc_lo
	s_nop 0
	global_load_lds_dwordx4 v[168:169], off
	s_mov_b64 s[12:13], 0x8000
	v_lshl_add_u64 v[174:175], v[172:173], 0, s[12:13]
	s_add_i32 s29, s28, 0x400
	s_mov_b32 m0, s29
	v_lshl_add_u64 v[168:169], v[174:175], 0, 64
	global_load_lds_dwordx4 v[174:175], off
	s_add_i32 m0, s29, vcc_lo
	s_nop 0
	global_load_lds_dwordx4 v[168:169], off
	s_mov_b64 s[14:15], 0x10000
	v_lshl_add_u64 v[174:175], v[172:173], 0, s[14:15]
	s_add_i32 s29, s28, 0x800
	s_mov_b32 m0, s29
	v_lshl_add_u64 v[168:169], v[174:175], 0, 64
	global_load_lds_dwordx4 v[174:175], off
	s_add_i32 m0, s29, vcc_lo
	s_nop 0
	global_load_lds_dwordx4 v[168:169], off
	s_mov_b64 s[14:15], 0x18000
	v_lshl_add_u64 v[172:173], v[172:173], 0, s[14:15]
	s_addk_i32 s28, 0xc00
	s_mov_b32 m0, s28
	v_lshl_add_u64 v[168:169], v[172:173], 0, 64
	global_load_lds_dwordx4 v[172:173], off
	s_add_i32 m0, s28, vcc_lo
	s_nop 0
	global_load_lds_dwordx4 v[168:169], off
	v_lshl_add_u64 v[172:173], v[176:177], 0, s[6:7]
	s_add_i32 s9, s9, s24
	s_mov_b32 m0, s9
	v_lshl_add_u64 v[168:169], v[172:173], 0, 64
	global_load_lds_dwordx4 v[172:173], off
	s_add_i32 m0, s9, vcc_lo
	s_nop 0
	global_load_lds_dwordx4 v[168:169], off
	v_lshl_add_u64 v[172:173], v[172:173], 0, s[12:13]
	s_addk_i32 s9, 0x400
	s_mov_b32 m0, s9
	v_lshl_add_u64 v[168:169], v[172:173], 0, 64
	global_load_lds_dwordx4 v[172:173], off
	s_add_i32 m0, s9, vcc_lo
	s_nop 0
	global_load_lds_dwordx4 v[168:169], off
	v_mfma_f32_16x16x32_bf16 v[72:75], v[128:131], v[160:163], v[72:75]
	v_mfma_f32_16x16x32_bf16 v[68:71], v[132:135], v[160:163], v[68:71]
	v_mfma_f32_16x16x32_bf16 v[64:67], v[136:139], v[160:163], v[64:67]
	v_mfma_f32_16x16x32_bf16 v[60:63], v[140:143], v[160:163], v[60:63]
; __device__ __forceinline__ f32x4 mfma16(bf16x8 a, bf16x8 b, f32x4 c) { return __builtin_amdgcn_mfma_f32_16x16x32_bf16(a, b, c, 0, 0, 0); }
; template <int MI, bool SWAP, class Epi> ...
;     ...
;     if (!prefetched) {
;         __syncthreads();
;         RING_STAGE(0, 0);
;         RING_STAGE(1, 32);
;     }
;     int cur = 0;
;     for (int kt = 0; kt < nk; ++kt) {
;         if (kt + 1 < nk && !(prefetched && kt == 0)) { if (MI == 8) asm volatile("s_waitcnt vmcnt(6)\n\ts_barrier" ::: "memory"); else if (MI == 4) asm volatile("s_waitcnt vmcnt(4)\n\ts_barrier" ::: "memory"); else asm volatile("s_waitcnt vmcnt(3)\n\ts_barrier" ::: "memory"); }
;         else asm volatile("s_waitcnt vmcnt(0)\n\ts_barrier" ::: "memory");
;         if (kt + 2 < nk) { const int nx = (cur == 0) ? 2 : cur - 1; RING_STAGE(nx, (kt + 2) * 32); }
;         const int so = cur * STAGEB;
;         bf16x8 bf[4], af[MI];
; #pragma unroll
;         for (int j = 0; j < 4; ++j) bf[j] = *(const bf16x8*)(brdb + so + j * 1024);
; #pragma unroll
;         for (int i = 0; i < MI; ++i) af[i] = *(const bf16x8*)(ardb + so + i * 1024);
;         if (blockIdx.x & 256) __builtin_amdgcn_s_setprio(2); else __builtin_amdgcn_s_setprio(1);
; #pragma unroll
;         for (int i = 0; i < MI; ++i) {
; #pragma unroll
;             for (int j = 0; j < 4; ++j) {
;                 if (SWAP) acc[i][j] = mfma16(bf[j], af[i], acc[i][j]);
;                 else acc[i][j] = mfma16(af[i], bf[j], acc[i][j]);
;             }
;         }
;         __builtin_amdgcn_s_setprio(0);
;         cur = (cur == 2) ? 0 : cur + 1;
;     }
	v_mfma_f32_16x16x32_bf16 v[56:59], v[128:131], v[156:159], v[56:59]
	v_mfma_f32_16x16x32_bf16 v[52:55], v[132:135], v[156:159], v[52:55]
	v_mfma_f32_16x16x32_bf16 v[48:51], v[136:139], v[156:159], v[48:51]
	v_mfma_f32_16x16x32_bf16 v[44:47], v[140:143], v[156:159], v[44:47]
	v_mfma_f32_16x16x32_bf16 v[40:43], v[128:131], v[152:155], v[40:43]
	v_mfma_f32_16x16x32_bf16 v[36:39], v[132:135], v[152:155], v[36:39]
	v_mfma_f32_16x16x32_bf16 v[32:35], v[136:139], v[152:155], v[32:35]
	v_mfma_f32_16x16x32_bf16 v[28:31], v[140:143], v[152:155], v[28:31]
	v_mfma_f32_16x16x32_bf16 v[24:27], v[128:131], v[148:151], v[24:27]
	v_mfma_f32_16x16x32_bf16 v[20:23], v[132:135], v[148:151], v[20:23]
	v_mfma_f32_16x16x32_bf16 v[16:19], v[136:139], v[148:151], v[16:19]
	v_mfma_f32_16x16x32_bf16 v[12:15], v[140:143], v[148:151], v[12:15]
	v_mfma_f32_16x16x32_bf16 v[8:11], v[128:131], v[144:147], v[8:11]
	v_mfma_f32_16x16x32_bf16 v[4:7], v[132:135], v[144:147], v[4:7]
	v_mfma_f32_16x16x32_bf16 v[0:3], v[136:139], v[144:147], v[0:3]
	v_mfma_f32_16x16x32_bf16 v[124:127], v[140:143], v[144:147], v[124:127]
	s_setprio 0
	s_add_u32 s6, s6, 64
	s_addc_u32 s7, s7, 0
	s_mov_b32 s8, 0xc000
	v_add_u32_e32 v140, s8, v223
	v_add_u32_e32 v144, s8, v222
	ds_read_b128 v[128:131], v140 offset:16384
	ds_read_b128 v[132:135], v140 offset:17408
	ds_read_b128 v[136:139], v140 offset:18432
	ds_read_b128 v[140:143], v140 offset:19456
	ds_read_b128 v[172:175], v144
	ds_read_b128 v[168:171], v144 offset:1024
	ds_read_b128 v[164:167], v144 offset:2048
	ds_read_b128 v[160:163], v144 offset:3072
	ds_read_b128 v[156:159], v144 offset:4096
	ds_read_b128 v[152:155], v144 offset:5120
	ds_read_b128 v[148:151], v144 offset:6144
	ds_read_b128 v[144:147], v144 offset:7168
	s_setprio 2
	s_waitcnt lgkmcnt(7)
	v_mfma_f32_16x16x32_bf16 v[120:123], v[128:131], v[172:175], v[120:123]
	v_mfma_f32_16x16x32_bf16 v[116:119], v[132:135], v[172:175], v[116:119]
	v_mfma_f32_16x16x32_bf16 v[112:115], v[136:139], v[172:175], v[112:115]
	v_mfma_f32_16x16x32_bf16 v[108:111], v[140:143], v[172:175], v[108:111]
	s_waitcnt lgkmcnt(6)
	v_mfma_f32_16x16x32_bf16 v[104:107], v[128:131], v[168:171], v[104:107]
	v_mfma_f32_16x16x32_bf16 v[100:103], v[132:135], v[168:171], v[100:103]
	v_mfma_f32_16x16x32_bf16 v[96:99], v[136:139], v[168:171], v[96:99]
	v_mfma_f32_16x16x32_bf16 v[92:95], v[140:143], v[168:171], v[92:95]
	s_waitcnt lgkmcnt(5)
	v_mfma_f32_16x16x32_bf16 v[88:91], v[128:131], v[164:167], v[88:91]
	v_mfma_f32_16x16x32_bf16 v[84:87], v[132:135], v[164:167], v[84:87]
	v_mfma_f32_16x16x32_bf16 v[80:83], v[136:139], v[164:167], v[80:83]
	v_mfma_f32_16x16x32_bf16 v[76:79], v[140:143], v[164:167], v[76:79]
	s_waitcnt lgkmcnt(4)
	v_mfma_f32_16x16x32_bf16 v[72:75], v[128:131], v[160:163], v[72:75]
	v_mfma_f32_16x16x32_bf16 v[68:71], v[132:135], v[160:163], v[68:71]
	v_mfma_f32_16x16x32_bf16 v[64:67], v[136:139], v[160:163], v[64:67]
	v_mfma_f32_16x16x32_bf16 v[60:63], v[140:143], v[160:163], v[60:63]
	s_waitcnt lgkmcnt(3)
	v_mfma_f32_16x16x32_bf16 v[56:59], v[128:131], v[156:159], v[56:59]
	v_mfma_f32_16x16x32_bf16 v[52:55], v[132:135], v[156:159], v[52:55]
	v_mfma_f32_16x16x32_bf16 v[48:51], v[136:139], v[156:159], v[48:51]
	v_mfma_f32_16x16x32_bf16 v[44:47], v[140:143], v[156:159], v[44:47]
	s_waitcnt lgkmcnt(2)
	v_mfma_f32_16x16x32_bf16 v[40:43], v[128:131], v[152:155], v[40:43]
	v_mfma_f32_16x16x32_bf16 v[36:39], v[132:135], v[152:155], v[36:39]
	v_mfma_f32_16x16x32_bf16 v[32:35], v[136:139], v[152:155], v[32:35]
	v_mfma_f32_16x16x32_bf16 v[28:31], v[140:143], v[152:155], v[28:31]
	s_waitcnt lgkmcnt(1)
	v_mfma_f32_16x16x32_bf16 v[24:27], v[128:131], v[148:151], v[24:27]
	v_mfma_f32_16x16x32_bf16 v[20:23], v[132:135], v[148:151], v[20:23]
	v_mfma_f32_16x16x32_bf16 v[16:19], v[136:139], v[148:151], v[16:19]
	v_mfma_f32_16x16x32_bf16 v[12:15], v[140:143], v[148:151], v[12:15]
	s_waitcnt lgkmcnt(0)
	v_mfma_f32_16x16x32_bf16 v[8:11], v[128:131], v[144:147], v[8:11]
	v_mfma_f32_16x16x32_bf16 v[4:7], v[132:135], v[144:147], v[4:7]
	v_mfma_f32_16x16x32_bf16 v[0:3], v[136:139], v[144:147], v[0:3]
	v_mfma_f32_16x16x32_bf16 v[124:127], v[140:143], v[144:147], v[124:127]
	s_setprio 0
	s_add_u32 s6, s6, 64
	s_addc_u32 s7, s7, 0
	s_mov_b32 s27, 0
	s_cmpk_eq_i32 s6, 0x740
	s_cbranch_scc1 .LBB0_2197
	s_mov_b32 s8, 0x0
	s_mov_b32 s9, 0xc000
	s_waitcnt vmcnt(0)
	s_barrier
	v_add_u32_e32 v140, s8, v223
	v_add_u32_e32 v144, s8, v222
	ds_read_b128 v[128:131], v140 offset:16384
	ds_read_b128 v[132:135], v140 offset:17408
	ds_read_b128 v[136:139], v140 offset:18432
	ds_read_b128 v[140:143], v140 offset:19456
	ds_read_b128 v[172:175], v144
	ds_read_b128 v[168:171], v144 offset:1024
	ds_read_b128 v[164:167], v144 offset:2048
	ds_read_b128 v[160:163], v144 offset:3072
	ds_read_b128 v[156:159], v144 offset:4096
	ds_read_b128 v[152:155], v144 offset:5120
	ds_read_b128 v[148:151], v144 offset:6144
	ds_read_b128 v[144:147], v144 offset:7168
	s_waitcnt lgkmcnt(0)
	s_barrier
; __device__ __forceinline__ f32x4 mfma16(bf16x8 a, bf16x8 b, f32x4 c) { return __builtin_amdgcn_mfma_f32_16x16x32_bf16(a, b, c, 0, 0, 0); }
; template <int MI, bool SWAP, class Epi> ...
;     ...
;     if (!prefetched) {
;         __syncthreads();
;         RING_STAGE(0, 0);
;         RING_STAGE(1, 32);
;     }
;     int cur = 0;
;     for (int kt = 0; kt < nk; ++kt) {
;         if (kt + 1 < nk && !(prefetched && kt == 0)) { if (MI == 8) asm volatile("s_waitcnt vmcnt(6)\n\ts_barrier" ::: "memory"); else if (MI == 4) asm volatile("s_waitcnt vmcnt(4)\n\ts_barrier" ::: "memory"); else asm volatile("s_waitcnt vmcnt(3)\n\ts_barrier" ::: "memory"); }
;         else asm volatile("s_waitcnt vmcnt(0)\n\ts_barrier" ::: "memory");
;         if (kt + 2 < nk) { const int nx = (cur == 0) ? 2 : cur - 1; RING_STAGE(nx, (kt + 2) * 32); }
;         const int so = cur * STAGEB;
;         bf16x8 bf[4], af[MI];
; #pragma unroll
;         for (int j = 0; j < 4; ++j) bf[j] = *(const bf16x8*)(brdb + so + j * 1024);
; #pragma unroll
;         for (int i = 0; i < MI; ++i) af[i] = *(const bf16x8*)(ardb + so + i * 1024);
;         if (blockIdx.x & 256) __builtin_amdgcn_s_setprio(2); else __builtin_amdgcn_s_setprio(1);
; #pragma unroll
;         for (int i = 0; i < MI; ++i) {
; #pragma unroll
;             for (int j = 0; j < 4; ++j) {
;                 if (SWAP) acc[i][j] = mfma16(bf[j], af[i], acc[i][j]);
;                 else acc[i][j] = mfma16(af[i], bf[j], acc[i][j]);
;             }
;         }
;         __builtin_amdgcn_s_setprio(0);
;         cur = (cur == 2) ? 0 : cur + 1;
;     }
	s_setprio 2
	s_sub_i32 vcc_lo, s8, s9
	v_mfma_f32_16x16x32_bf16 v[120:123], v[128:131], v[172:175], v[120:123]
	v_mfma_f32_16x16x32_bf16 v[116:119], v[132:135], v[172:175], v[116:119]
	v_mfma_f32_16x16x32_bf16 v[112:115], v[136:139], v[172:175], v[112:115]
	v_mfma_f32_16x16x32_bf16 v[108:111], v[140:143], v[172:175], v[108:111]
	v_mfma_f32_16x16x32_bf16 v[104:107], v[128:131], v[168:171], v[104:107]
	v_mfma_f32_16x16x32_bf16 v[100:103], v[132:135], v[168:171], v[100:103]
	v_mfma_f32_16x16x32_bf16 v[96:99], v[136:139], v[168:171], v[96:99]
	v_mfma_f32_16x16x32_bf16 v[92:95], v[140:143], v[168:171], v[92:95]
	v_mfma_f32_16x16x32_bf16 v[88:91], v[128:131], v[164:167], v[88:91]
	v_mfma_f32_16x16x32_bf16 v[84:87], v[132:135], v[164:167], v[84:87]
	v_mfma_f32_16x16x32_bf16 v[80:83], v[136:139], v[164:167], v[80:83]
	v_mfma_f32_16x16x32_bf16 v[76:79], v[140:143], v[164:167], v[76:79]
	v_lshl_add_u64 v[172:173], v[178:179], 0, s[6:7]
	s_add_i32 s28, s9, s23
	s_mov_b32 m0, s28
	v_lshl_add_u64 v[168:169], v[172:173], 0, 64
	global_load_lds_dwordx4 v[172:173], off
	s_add_i32 m0, s28, vcc_lo
	s_nop 0
	global_load_lds_dwordx4 v[168:169], off
	s_mov_b64 s[12:13], 0x8000
	v_lshl_add_u64 v[174:175], v[172:173], 0, s[12:13]
	s_add_i32 s29, s28, 0x400
	s_mov_b32 m0, s29
	v_lshl_add_u64 v[168:169], v[174:175], 0, 64
	global_load_lds_dwordx4 v[174:175], off
	s_add_i32 m0, s29, vcc_lo
	s_nop 0
	global_load_lds_dwordx4 v[168:169], off
	s_mov_b64 s[14:15], 0x10000
	v_lshl_add_u64 v[174:175], v[172:173], 0, s[14:15]
	s_add_i32 s29, s28, 0x800
	s_mov_b32 m0, s29
	v_lshl_add_u64 v[168:169], v[174:175], 0, 64
	global_load_lds_dwordx4 v[174:175], off
	s_add_i32 m0, s29, vcc_lo
	s_nop 0
	global_load_lds_dwordx4 v[168:169], off
	s_mov_b64 s[14:15], 0x18000
	v_lshl_add_u64 v[172:173], v[172:173], 0, s[14:15]
	s_addk_i32 s28, 0xc00
	s_mov_b32 m0, s28
	v_lshl_add_u64 v[168:169], v[172:173], 0, 64
	global_load_lds_dwordx4 v[172:173], off
	s_add_i32 m0, s28, vcc_lo
	s_nop 0
	global_load_lds_dwordx4 v[168:169], off
	v_lshl_add_u64 v[172:173], v[176:177], 0, s[6:7]
	s_add_i32 s9, s9, s24
	s_mov_b32 m0, s9
	v_lshl_add_u64 v[168:169], v[172:173], 0, 64
	global_load_lds_dwordx4 v[172:173], off
	s_add_i32 m0, s9, vcc_lo
	s_nop 0
	global_load_lds_dwordx4 v[168:169], off
	v_lshl_add_u64 v[172:173], v[172:173], 0, s[12:13]
	s_addk_i32 s9, 0x400
	s_mov_b32 m0, s9
	v_lshl_add_u64 v[168:169], v[172:173], 0, 64
	global_load_lds_dwordx4 v[172:173], off
	s_add_i32 m0, s9, vcc_lo
	s_nop 0
	global_load_lds_dwordx4 v[168:169], off
	v_mfma_f32_16x16x32_bf16 v[72:75], v[128:131], v[160:163], v[72:75]
	v_mfma_f32_16x16x32_bf16 v[68:71], v[132:135], v[160:163], v[68:71]
	v_mfma_f32_16x16x32_bf16 v[64:67], v[136:139], v[160:163], v[64:67]
	v_mfma_f32_16x16x32_bf16 v[60:63], v[140:143], v[160:163], v[60:63]
	v_mfma_f32_16x16x32_bf16 v[56:59], v[128:131], v[156:159], v[56:59]
	v_mfma_f32_16x16x32_bf16 v[52:55], v[132:135], v[156:159], v[52:55]
	v_mfma_f32_16x16x32_bf16 v[48:51], v[136:139], v[156:159], v[48:51]
	v_mfma_f32_16x16x32_bf16 v[44:47], v[140:143], v[156:159], v[44:47]
	v_mfma_f32_16x16x32_bf16 v[40:43], v[128:131], v[152:155], v[40:43]
	v_mfma_f32_16x16x32_bf16 v[36:39], v[132:135], v[152:155], v[36:39]
	v_mfma_f32_16x16x32_bf16 v[32:35], v[136:139], v[152:155], v[32:35]
	v_mfma_f32_16x16x32_bf16 v[28:31], v[140:143], v[152:155], v[28:31]
	v_mfma_f32_16x16x32_bf16 v[24:27], v[128:131], v[148:151], v[24:27]
	v_mfma_f32_16x16x32_bf16 v[20:23], v[132:135], v[148:151], v[20:23]
	v_mfma_f32_16x16x32_bf16 v[16:19], v[136:139], v[148:151], v[16:19]
	v_mfma_f32_16x16x32_bf16 v[12:15], v[140:143], v[148:151], v[12:15]
	v_mfma_f32_16x16x32_bf16 v[8:11], v[128:131], v[144:147], v[8:11]
	v_mfma_f32_16x16x32_bf16 v[4:7], v[132:135], v[144:147], v[4:7]
	v_mfma_f32_16x16x32_bf16 v[0:3], v[136:139], v[144:147], v[0:3]
	v_mfma_f32_16x16x32_bf16 v[124:127], v[140:143], v[144:147], v[124:127]
	s_setprio 0
	s_add_u32 s6, s6, 64
	s_addc_u32 s7, s7, 0
	s_mov_b32 s8, 0x6000
	v_add_u32_e32 v140, s8, v223
	v_add_u32_e32 v144, s8, v222
	ds_read_b128 v[128:131], v140 offset:16384
	ds_read_b128 v[132:135], v140 offset:17408
	ds_read_b128 v[136:139], v140 offset:18432
	ds_read_b128 v[140:143], v140 offset:19456
	ds_read_b128 v[172:175], v144
	ds_read_b128 v[168:171], v144 offset:1024
	ds_read_b128 v[164:167], v144 offset:2048
	ds_read_b128 v[160:163], v144 offset:3072
	ds_read_b128 v[156:159], v144 offset:4096
	ds_read_b128 v[152:155], v144 offset:5120
	ds_read_b128 v[148:151], v144 offset:6144
	ds_read_b128 v[144:147], v144 offset:7168
	s_setprio 2
	s_waitcnt lgkmcnt(7)
; __device__ __forceinline__ f32x4 mfma16(bf16x8 a, bf16x8 b, f32x4 c) { return __builtin_amdgcn_mfma_f32_16x16x32_bf16(a, b, c, 0, 0, 0); }
; template <int MI, bool SWAP, class Epi> ...
;     ...
;     for (int kt = 0; kt < nk; ++kt) {
;         if (kt + 1 < nk && !(prefetched && kt == 0)) { if (MI == 8) asm volatile("s_waitcnt vmcnt(6)\n\ts_barrier" ::: "memory"); else if (MI == 4) asm volatile("s_waitcnt vmcnt(4)\n\ts_barrier" ::: "memory"); else asm volatile("s_waitcnt vmcnt(3)\n\ts_barrier" ::: "memory"); }
;         else asm volatile("s_waitcnt vmcnt(0)\n\ts_barrier" ::: "memory");
;         if (kt + 2 < nk) { const int nx = (cur == 0) ? 2 : cur - 1; RING_STAGE(nx, (kt + 2) * 32); }
;         const int so = cur * STAGEB;
;         bf16x8 bf[4], af[MI];
; #pragma unroll
;         for (int j = 0; j < 4; ++j) bf[j] = *(const bf16x8*)(brdb + so + j * 1024);
; #pragma unroll
;         for (int i = 0; i < MI; ++i) af[i] = *(const bf16x8*)(ardb + so + i * 1024);
;         if (blockIdx.x & 256) __builtin_amdgcn_s_setprio(2); else __builtin_amdgcn_s_setprio(1);
; #pragma unroll
;         for (int i = 0; i < MI; ++i) {
; #pragma unroll
;             for (int j = 0; j < 4; ++j) {
;                 if (SWAP) acc[i][j] = mfma16(bf[j], af[i], acc[i][j]);
;                 else acc[i][j] = mfma16(af[i], bf[j], acc[i][j]);
;             }
;         }
;         __builtin_amdgcn_s_setprio(0);
;         cur = (cur == 2) ? 0 : cur + 1;
;     }
	v_mfma_f32_16x16x32_bf16 v[120:123], v[128:131], v[172:175], v[120:123]
	v_mfma_f32_16x16x32_bf16 v[116:119], v[132:135], v[172:175], v[116:119]
	v_mfma_f32_16x16x32_bf16 v[112:115], v[136:139], v[172:175], v[112:115]
	v_mfma_f32_16x16x32_bf16 v[108:111], v[140:143], v[172:175], v[108:111]
	s_waitcnt lgkmcnt(6)
	v_mfma_f32_16x16x32_bf16 v[104:107], v[128:131], v[168:171], v[104:107]
	v_mfma_f32_16x16x32_bf16 v[100:103], v[132:135], v[168:171], v[100:103]
	v_mfma_f32_16x16x32_bf16 v[96:99], v[136:139], v[168:171], v[96:99]
	v_mfma_f32_16x16x32_bf16 v[92:95], v[140:143], v[168:171], v[92:95]
	s_waitcnt lgkmcnt(5)
	v_mfma_f32_16x16x32_bf16 v[88:91], v[128:131], v[164:167], v[88:91]
	v_mfma_f32_16x16x32_bf16 v[84:87], v[132:135], v[164:167], v[84:87]
	v_mfma_f32_16x16x32_bf16 v[80:83], v[136:139], v[164:167], v[80:83]
	v_mfma_f32_16x16x32_bf16 v[76:79], v[140:143], v[164:167], v[76:79]
	s_waitcnt lgkmcnt(4)
	v_mfma_f32_16x16x32_bf16 v[72:75], v[128:131], v[160:163], v[72:75]
	v_mfma_f32_16x16x32_bf16 v[68:71], v[132:135], v[160:163], v[68:71]
	v_mfma_f32_16x16x32_bf16 v[64:67], v[136:139], v[160:163], v[64:67]
	v_mfma_f32_16x16x32_bf16 v[60:63], v[140:143], v[160:163], v[60:63]
	s_waitcnt lgkmcnt(3)
	v_mfma_f32_16x16x32_bf16 v[56:59], v[128:131], v[156:159], v[56:59]
	v_mfma_f32_16x16x32_bf16 v[52:55], v[132:135], v[156:159], v[52:55]
	v_mfma_f32_16x16x32_bf16 v[48:51], v[136:139], v[156:159], v[48:51]
	v_mfma_f32_16x16x32_bf16 v[44:47], v[140:143], v[156:159], v[44:47]
	s_waitcnt lgkmcnt(2)
	v_mfma_f32_16x16x32_bf16 v[40:43], v[128:131], v[152:155], v[40:43]
	v_mfma_f32_16x16x32_bf16 v[36:39], v[132:135], v[152:155], v[36:39]
	v_mfma_f32_16x16x32_bf16 v[32:35], v[136:139], v[152:155], v[32:35]
	v_mfma_f32_16x16x32_bf16 v[28:31], v[140:143], v[152:155], v[28:31]
	s_waitcnt lgkmcnt(1)
	v_mfma_f32_16x16x32_bf16 v[24:27], v[128:131], v[148:151], v[24:27]
	v_mfma_f32_16x16x32_bf16 v[20:23], v[132:135], v[148:151], v[20:23]
	v_mfma_f32_16x16x32_bf16 v[16:19], v[136:139], v[148:151], v[16:19]
	v_mfma_f32_16x16x32_bf16 v[12:15], v[140:143], v[148:151], v[12:15]
	s_waitcnt lgkmcnt(0)
	v_mfma_f32_16x16x32_bf16 v[8:11], v[128:131], v[144:147], v[8:11]
	v_mfma_f32_16x16x32_bf16 v[4:7], v[132:135], v[144:147], v[4:7]
	v_mfma_f32_16x16x32_bf16 v[0:3], v[136:139], v[144:147], v[0:3]
	v_mfma_f32_16x16x32_bf16 v[124:127], v[140:143], v[144:147], v[124:127]
	s_setprio 0
	s_add_u32 s6, s6, 64
	s_addc_u32 s7, s7, 0
	s_mov_b32 s27, 2
	s_cmpk_eq_i32 s6, 0x740
	s_cbranch_scc1 .LBB0_2197
	s_branch .Lru_loop_ff1

; __device__ __forceinline__ f32x4 mfma16(bf16x8 a, bf16x8 b, f32x4 c) { return __builtin_amdgcn_mfma_f32_16x16x32_bf16(a, b, c, 0, 0, 0); }
; template <int MI, bool SWAP, class Epi> ...
;     ...
;     if (!prefetched) {
;         __syncthreads();
;         RING_STAGE(0, 0);
;         RING_STAGE(1, 32);
;     }
;     int cur = 0;
;     for (int kt = 0; kt < nk; ++kt) {
;         if (kt + 1 < nk && !(prefetched && kt == 0)) { if (MI == 8) asm volatile("s_waitcnt vmcnt(6)\n\ts_barrier" ::: "memory"); else if (MI == 4) asm volatile("s_waitcnt vmcnt(4)\n\ts_barrier" ::: "memory"); else asm volatile("s_waitcnt vmcnt(3)\n\ts_barrier" ::: "memory"); }
;         else asm volatile("s_waitcnt vmcnt(0)\n\ts_barrier" ::: "memory");
;         if (kt + 2 < nk) { const int nx = (cur == 0) ? 2 : cur - 1; RING_STAGE(nx, (kt + 2) * 32); }
;         const int so = cur * STAGEB;
;         bf16x8 bf[4], af[MI];
; #pragma unroll
;         for (int j = 0; j < 4; ++j) bf[j] = *(const bf16x8*)(brdb + so + j * 1024);
; #pragma unroll
;         for (int i = 0; i < MI; ++i) af[i] = *(const bf16x8*)(ardb + so + i * 1024);
;         if (blockIdx.x & 256) __builtin_amdgcn_s_setprio(2); else __builtin_amdgcn_s_setprio(1);
; #pragma unroll
;         for (int i = 0; i < MI; ++i) {
; #pragma unroll
;             for (int j = 0; j < 4; ++j) {
;                 if (SWAP) acc[i][j] = mfma16(bf[j], af[i], acc[i][j]);
;                 else acc[i][j] = mfma16(af[i], bf[j], acc[i][j]);
;             }
;         }
;         __builtin_amdgcn_s_setprio(0);
;         cur = (cur == 2) ? 0 : cur + 1;
;     }
.LBB0_2308:
	s_mul_i32 s8, s30, 0x6000
	s_add_i32 s9, s8, 0xffffa000
	s_cmp_lg_u32 s30, 0
	s_cselect_b32 s9, s9, 0xc000
	v_readlane_b32 vcc_lo, v248, 0
	s_nop 1
	s_bitcmp1_b32 vcc_lo, 3
	s_cbranch_scc0 .Lrp_nostag0_ff2
	s_sleep 9
.Lrp_nostag0_ff2:
	s_waitcnt vmcnt(6)
	s_barrier
	v_lshl_add_u64 v[128:129], v[178:179], 0, s[6:7]
	s_add_i32 s31, s9, s26
	s_mov_b32 s34, m0
	s_mov_b32 m0, s31
	s_nop 0
	global_load_lds_dwordx4 v[128:129], off
	s_mov_b32 m0, s34
	s_mov_b64 s[12:13], 0x20000
	v_lshl_add_u64 v[130:131], v[128:129], 0, s[12:13]
	s_add_i32 s34, s31, 0x400
	s_mov_b32 s35, m0
	s_mov_b32 m0, s34
	s_nop 0
	global_load_lds_dwordx4 v[130:131], off
	s_mov_b32 m0, s35
	s_mov_b64 s[34:35], 0x40000
	v_lshl_add_u64 v[130:131], v[128:129], 0, s[34:35]
	s_add_i32 s34, s31, 0x800
	s_mov_b32 s35, m0
	s_mov_b32 m0, s34
	s_nop 0
	global_load_lds_dwordx4 v[130:131], off
	s_mov_b32 m0, s35
	s_mov_b64 s[34:35], 0x60000
	v_lshl_add_u64 v[128:129], v[128:129], 0, s[34:35]
	s_addk_i32 s31, 0xc00
	s_mov_b32 s34, m0
	s_mov_b32 m0, s31
	s_nop 0
	global_load_lds_dwordx4 v[128:129], off
	s_mov_b32 m0, s34
	v_lshl_add_u64 v[128:129], v[176:177], 0, s[6:7]
	s_add_i32 s9, s9, s27
	s_mov_b32 s31, m0
	s_mov_b32 m0, s9
	s_nop 0
	global_load_lds_dwordx4 v[128:129], off
	s_mov_b32 m0, s31
	v_lshl_add_u64 v[128:129], v[128:129], 0, s[12:13]
	s_addk_i32 s9, 0x400
	s_mov_b32 s31, m0
	s_mov_b32 m0, s9
	s_nop 0
	global_load_lds_dwordx4 v[128:129], off
	s_mov_b32 m0, s31
	v_add_u32_e32 v140, s8, v223
	v_add_u32_e32 v144, s8, v222
	ds_read_b128 v[128:131], v140 offset:16384
	ds_read_b128 v[132:135], v140 offset:17408
	ds_read_b128 v[136:139], v140 offset:18432
	ds_read_b128 v[140:143], v140 offset:19456
	ds_read_b128 v[172:175], v144
	ds_read_b128 v[168:171], v144 offset:1024
	ds_read_b128 v[164:167], v144 offset:2048
	ds_read_b128 v[160:163], v144 offset:3072
	ds_read_b128 v[156:159], v144 offset:4096
	ds_read_b128 v[152:155], v144 offset:5120
	ds_read_b128 v[148:151], v144 offset:6144
	ds_read_b128 v[144:147], v144 offset:7168
	s_setprio 2
	s_waitcnt lgkmcnt(7)
	v_mfma_f32_16x16x32_bf16 v[120:123], v[128:131], v[172:175], v[120:123]
	v_mfma_f32_16x16x32_bf16 v[116:119], v[132:135], v[172:175], v[116:119]
	v_mfma_f32_16x16x32_bf16 v[112:115], v[136:139], v[172:175], v[112:115]
	v_mfma_f32_16x16x32_bf16 v[108:111], v[140:143], v[172:175], v[108:111]
	s_waitcnt lgkmcnt(6)
	v_mfma_f32_16x16x32_bf16 v[104:107], v[128:131], v[168:171], v[104:107]
	v_mfma_f32_16x16x32_bf16 v[100:103], v[132:135], v[168:171], v[100:103]
	v_mfma_f32_16x16x32_bf16 v[96:99], v[136:139], v[168:171], v[96:99]
	v_mfma_f32_16x16x32_bf16 v[92:95], v[140:143], v[168:171], v[92:95]
	s_waitcnt lgkmcnt(5)
	v_mfma_f32_16x16x32_bf16 v[88:91], v[128:131], v[164:167], v[88:91]
	v_mfma_f32_16x16x32_bf16 v[84:87], v[132:135], v[164:167], v[84:87]
	v_mfma_f32_16x16x32_bf16 v[80:83], v[136:139], v[164:167], v[80:83]
	v_mfma_f32_16x16x32_bf16 v[76:79], v[140:143], v[164:167], v[76:79]
	s_waitcnt lgkmcnt(4)
	v_mfma_f32_16x16x32_bf16 v[72:75], v[128:131], v[160:163], v[72:75]
	v_mfma_f32_16x16x32_bf16 v[68:71], v[132:135], v[160:163], v[68:71]
	v_mfma_f32_16x16x32_bf16 v[64:67], v[136:139], v[160:163], v[64:67]
	v_mfma_f32_16x16x32_bf16 v[60:63], v[140:143], v[160:163], v[60:63]
	s_waitcnt lgkmcnt(3)
	v_mfma_f32_16x16x32_bf16 v[56:59], v[128:131], v[156:159], v[56:59]
	v_mfma_f32_16x16x32_bf16 v[52:55], v[132:135], v[156:159], v[52:55]
	v_mfma_f32_16x16x32_bf16 v[48:51], v[136:139], v[156:159], v[48:51]
	v_mfma_f32_16x16x32_bf16 v[44:47], v[140:143], v[156:159], v[44:47]
	s_waitcnt lgkmcnt(2)
	v_mfma_f32_16x16x32_bf16 v[40:43], v[128:131], v[152:155], v[40:43]
	v_mfma_f32_16x16x32_bf16 v[36:39], v[132:135], v[152:155], v[36:39]
	v_mfma_f32_16x16x32_bf16 v[32:35], v[136:139], v[152:155], v[32:35]
	v_mfma_f32_16x16x32_bf16 v[28:31], v[140:143], v[152:155], v[28:31]
	s_waitcnt lgkmcnt(1)
	v_mfma_f32_16x16x32_bf16 v[24:27], v[128:131], v[148:151], v[24:27]
	v_mfma_f32_16x16x32_bf16 v[20:23], v[132:135], v[148:151], v[20:23]
	v_mfma_f32_16x16x32_bf16 v[16:19], v[136:139], v[148:151], v[16:19]
	v_mfma_f32_16x16x32_bf16 v[12:15], v[140:143], v[148:151], v[12:15]
	s_waitcnt lgkmcnt(0)
	v_mfma_f32_16x16x32_bf16 v[8:11], v[128:131], v[144:147], v[8:11]
	v_mfma_f32_16x16x32_bf16 v[4:7], v[132:135], v[144:147], v[4:7]
	v_mfma_f32_16x16x32_bf16 v[0:3], v[136:139], v[144:147], v[0:3]
	v_mfma_f32_16x16x32_bf16 v[124:127], v[140:143], v[144:147], v[124:127]
	s_setprio 0
	s_add_u32 s6, s6, 64
	s_addc_u32 s7, s7, 0
; __device__ __forceinline__ f32x4 mfma16(bf16x8 a, bf16x8 b, f32x4 c) { return __builtin_amdgcn_mfma_f32_16x16x32_bf16(a, b, c, 0, 0, 0); }
; template <int MI, bool SWAP, class Epi> ...
;     ...
;     if (!prefetched) {
;         __syncthreads();
;         RING_STAGE(0, 0);
;         RING_STAGE(1, 32);
;     }
;     int cur = 0;
;     for (int kt = 0; kt < nk; ++kt) {
;         if (kt + 1 < nk && !(prefetched && kt == 0)) { if (MI == 8) asm volatile("s_waitcnt vmcnt(6)\n\ts_barrier" ::: "memory"); else if (MI == 4) asm volatile("s_waitcnt vmcnt(4)\n\ts_barrier" ::: "memory"); else asm volatile("s_waitcnt vmcnt(3)\n\ts_barrier" ::: "memory"); }
;         else asm volatile("s_waitcnt vmcnt(0)\n\ts_barrier" ::: "memory");
;         if (kt + 2 < nk) { const int nx = (cur == 0) ? 2 : cur - 1; RING_STAGE(nx, (kt + 2) * 32); }
;         const int so = cur * STAGEB;
;         bf16x8 bf[4], af[MI];
; #pragma unroll
;         for (int j = 0; j < 4; ++j) bf[j] = *(const bf16x8*)(brdb + so + j * 1024);
; #pragma unroll
;         for (int i = 0; i < MI; ++i) af[i] = *(const bf16x8*)(ardb + so + i * 1024);
;         if (blockIdx.x & 256) __builtin_amdgcn_s_setprio(2); else __builtin_amdgcn_s_setprio(1);
; #pragma unroll
;         for (int i = 0; i < MI; ++i) {
; #pragma unroll
;             for (int j = 0; j < 4; ++j) {
;                 if (SWAP) acc[i][j] = mfma16(bf[j], af[i], acc[i][j]);
;                 else acc[i][j] = mfma16(af[i], bf[j], acc[i][j]);
;             }
;         }
;         __builtin_amdgcn_s_setprio(0);
;         cur = (cur == 2) ? 0 : cur + 1;
;     }
.Lru_loop_ff2:
	s_mov_b32 s8, 0xc000
	s_mov_b32 s9, 0x6000
	s_waitcnt vmcnt(0)
	s_barrier
	v_add_u32_e32 v140, s8, v223
	v_add_u32_e32 v144, s8, v222
	ds_read_b128 v[128:131], v140 offset:16384
	ds_read_b128 v[132:135], v140 offset:17408
	ds_read_b128 v[136:139], v140 offset:18432
	ds_read_b128 v[140:143], v140 offset:19456
	ds_read_b128 v[172:175], v144
	ds_read_b128 v[168:171], v144 offset:1024
	ds_read_b128 v[164:167], v144 offset:2048
	ds_read_b128 v[160:163], v144 offset:3072
	ds_read_b128 v[156:159], v144 offset:4096
	ds_read_b128 v[152:155], v144 offset:5120
	ds_read_b128 v[148:151], v144 offset:6144
	ds_read_b128 v[144:147], v144 offset:7168
	s_waitcnt lgkmcnt(0)
	s_barrier
	s_setprio 2
	s_sub_i32 vcc_lo, s8, s9
	v_mfma_f32_16x16x32_bf16 v[120:123], v[128:131], v[172:175], v[120:123]
	v_mfma_f32_16x16x32_bf16 v[116:119], v[132:135], v[172:175], v[116:119]
	v_mfma_f32_16x16x32_bf16 v[112:115], v[136:139], v[172:175], v[112:115]
	v_mfma_f32_16x16x32_bf16 v[108:111], v[140:143], v[172:175], v[108:111]
	v_mfma_f32_16x16x32_bf16 v[104:107], v[128:131], v[168:171], v[104:107]
	v_mfma_f32_16x16x32_bf16 v[100:103], v[132:135], v[168:171], v[100:103]
	v_mfma_f32_16x16x32_bf16 v[96:99], v[136:139], v[168:171], v[96:99]
	v_mfma_f32_16x16x32_bf16 v[92:95], v[140:143], v[168:171], v[92:95]
	v_mfma_f32_16x16x32_bf16 v[88:91], v[128:131], v[164:167], v[88:91]
	v_mfma_f32_16x16x32_bf16 v[84:87], v[132:135], v[164:167], v[84:87]
	v_mfma_f32_16x16x32_bf16 v[80:83], v[136:139], v[164:167], v[80:83]
	v_mfma_f32_16x16x32_bf16 v[76:79], v[140:143], v[164:167], v[76:79]
	v_lshl_add_u64 v[172:173], v[178:179], 0, s[6:7]
	s_add_i32 s31, s9, s26
	s_mov_b32 m0, s31
	v_lshl_add_u64 v[168:169], v[172:173], 0, 64
	global_load_lds_dwordx4 v[172:173], off
	s_add_i32 m0, s31, vcc_lo
	s_nop 0
	global_load_lds_dwordx4 v[168:169], off
	s_mov_b64 s[12:13], 0x20000
	v_lshl_add_u64 v[174:175], v[172:173], 0, s[12:13]
	s_add_i32 s34, s31, 0x400
	s_mov_b32 m0, s34
	v_lshl_add_u64 v[168:169], v[174:175], 0, 64
	global_load_lds_dwordx4 v[174:175], off
	s_add_i32 m0, s34, vcc_lo
	s_nop 0
	global_load_lds_dwordx4 v[168:169], off
	s_mov_b64 s[34:35], 0x40000
	v_lshl_add_u64 v[174:175], v[172:173], 0, s[34:35]
	s_add_i32 s34, s31, 0x800
	s_mov_b32 m0, s34
	v_lshl_add_u64 v[168:169], v[174:175], 0, 64
	global_load_lds_dwordx4 v[174:175], off
	s_add_i32 m0, s34, vcc_lo
	s_nop 0
	global_load_lds_dwordx4 v[168:169], off
	s_mov_b64 s[34:35], 0x60000
	v_lshl_add_u64 v[172:173], v[172:173], 0, s[34:35]
	s_addk_i32 s31, 0xc00
	s_mov_b32 m0, s31
	v_lshl_add_u64 v[168:169], v[172:173], 0, 64
	global_load_lds_dwordx4 v[172:173], off
	s_add_i32 m0, s31, vcc_lo
	s_nop 0
	global_load_lds_dwordx4 v[168:169], off
	v_lshl_add_u64 v[172:173], v[176:177], 0, s[6:7]
	s_add_i32 s9, s9, s27
	s_mov_b32 m0, s9
	v_lshl_add_u64 v[168:169], v[172:173], 0, 64
	global_load_lds_dwordx4 v[172:173], off
	s_add_i32 m0, s9, vcc_lo
	s_nop 0
	global_load_lds_dwordx4 v[168:169], off
	v_lshl_add_u64 v[172:173], v[172:173], 0, s[12:13]
	s_addk_i32 s9, 0x400
	s_mov_b32 m0, s9
	v_lshl_add_u64 v[168:169], v[172:173], 0, 64
	global_load_lds_dwordx4 v[172:173], off
	s_add_i32 m0, s9, vcc_lo
	s_nop 0
	global_load_lds_dwordx4 v[168:169], off
	v_mfma_f32_16x16x32_bf16 v[72:75], v[128:131], v[160:163], v[72:75]
	v_mfma_f32_16x16x32_bf16 v[68:71], v[132:135], v[160:163], v[68:71]
	v_mfma_f32_16x16x32_bf16 v[64:67], v[136:139], v[160:163], v[64:67]
	v_mfma_f32_16x16x32_bf16 v[60:63], v[140:143], v[160:163], v[60:63]
	v_mfma_f32_16x16x32_bf16 v[56:59], v[128:131], v[156:159], v[56:59]
	v_mfma_f32_16x16x32_bf16 v[52:55], v[132:135], v[156:159], v[52:55]
	v_mfma_f32_16x16x32_bf16 v[48:51], v[136:139], v[156:159], v[48:51]
	v_mfma_f32_16x16x32_bf16 v[44:47], v[140:143], v[156:159], v[44:47]
	v_mfma_f32_16x16x32_bf16 v[40:43], v[128:131], v[152:155], v[40:43]
	v_mfma_f32_16x16x32_bf16 v[36:39], v[132:135], v[152:155], v[36:39]
	v_mfma_f32_16x16x32_bf16 v[32:35], v[136:139], v[152:155], v[32:35]
	v_mfma_f32_16x16x32_bf16 v[28:31], v[140:143], v[152:155], v[28:31]
	v_mfma_f32_16x16x32_bf16 v[24:27], v[128:131], v[148:151], v[24:27]
	v_mfma_f32_16x16x32_bf16 v[20:23], v[132:135], v[148:151], v[20:23]
	v_mfma_f32_16x16x32_bf16 v[16:19], v[136:139], v[148:151], v[16:19]
	v_mfma_f32_16x16x32_bf16 v[12:15], v[140:143], v[148:151], v[12:15]
	v_mfma_f32_16x16x32_bf16 v[8:11], v[128:131], v[144:147], v[8:11]
	v_mfma_f32_16x16x32_bf16 v[4:7], v[132:135], v[144:147], v[4:7]
	v_mfma_f32_16x16x32_bf16 v[0:3], v[136:139], v[144:147], v[0:3]
	v_mfma_f32_16x16x32_bf16 v[124:127], v[140:143], v[144:147], v[124:127]
	s_setprio 0
	s_add_u32 s6, s6, 64
	s_addc_u32 s7, s7, 0
	s_mov_b32 s8, 0x0
	v_add_u32_e32 v140, s8, v223
	v_add_u32_e32 v144, s8, v222
	ds_read_b128 v[128:131], v140 offset:16384
	ds_read_b128 v[132:135], v140 offset:17408
	ds_read_b128 v[136:139], v140 offset:18432
	ds_read_b128 v[140:143], v140 offset:19456
	ds_read_b128 v[172:175], v144
	ds_read_b128 v[168:171], v144 offset:1024
	ds_read_b128 v[164:167], v144 offset:2048
	ds_read_b128 v[160:163], v144 offset:3072
	ds_read_b128 v[156:159], v144 offset:4096
	ds_read_b128 v[152:155], v144 offset:5120
	ds_read_b128 v[148:151], v144 offset:6144
	ds_read_b128 v[144:147], v144 offset:7168
	s_setprio 2
	s_waitcnt lgkmcnt(7)
	v_mfma_f32_16x16x32_bf16 v[120:123], v[128:131], v[172:175], v[120:123]
	v_mfma_f32_16x16x32_bf16 v[116:119], v[132:135], v[172:175], v[116:119]
	v_mfma_f32_16x16x32_bf16 v[112:115], v[136:139], v[172:175], v[112:115]
	v_mfma_f32_16x16x32_bf16 v[108:111], v[140:143], v[172:175], v[108:111]
	s_waitcnt lgkmcnt(6)
; __device__ __forceinline__ f32x4 mfma16(bf16x8 a, bf16x8 b, f32x4 c) { return __builtin_amdgcn_mfma_f32_16x16x32_bf16(a, b, c, 0, 0, 0); }
; template <int MI, bool SWAP, class Epi> ...
;     ...
;     if (!prefetched) {
;         __syncthreads();
;         RING_STAGE(0, 0);
;         RING_STAGE(1, 32);
;     }
;     int cur = 0;
;     for (int kt = 0; kt < nk; ++kt) {
;         if (kt + 1 < nk && !(prefetched && kt == 0)) { if (MI == 8) asm volatile("s_waitcnt vmcnt(6)\n\ts_barrier" ::: "memory"); else if (MI == 4) asm volatile("s_waitcnt vmcnt(4)\n\ts_barrier" ::: "memory"); else asm volatile("s_waitcnt vmcnt(3)\n\ts_barrier" ::: "memory"); }
;         else asm volatile("s_waitcnt vmcnt(0)\n\ts_barrier" ::: "memory");
;         if (kt + 2 < nk) { const int nx = (cur == 0) ? 2 : cur - 1; RING_STAGE(nx, (kt + 2) * 32); }
;         const int so = cur * STAGEB;
;         bf16x8 bf[4], af[MI];
; #pragma unroll
;         for (int j = 0; j < 4; ++j) bf[j] = *(const bf16x8*)(brdb + so + j * 1024);
; #pragma unroll
;         for (int i = 0; i < MI; ++i) af[i] = *(const bf16x8*)(ardb + so + i * 1024);
;         if (blockIdx.x & 256) __builtin_amdgcn_s_setprio(2); else __builtin_amdgcn_s_setprio(1);
; #pragma unroll
;         for (int i = 0; i < MI; ++i) {
; #pragma unroll
;             for (int j = 0; j < 4; ++j) {
;                 if (SWAP) acc[i][j] = mfma16(bf[j], af[i], acc[i][j]);
;                 else acc[i][j] = mfma16(af[i], bf[j], acc[i][j]);
;             }
;         }
;         __builtin_amdgcn_s_setprio(0);
;         cur = (cur == 2) ? 0 : cur + 1;
;     }
	v_mfma_f32_16x16x32_bf16 v[104:107], v[128:131], v[168:171], v[104:107]
	v_mfma_f32_16x16x32_bf16 v[100:103], v[132:135], v[168:171], v[100:103]
	v_mfma_f32_16x16x32_bf16 v[96:99], v[136:139], v[168:171], v[96:99]
	v_mfma_f32_16x16x32_bf16 v[92:95], v[140:143], v[168:171], v[92:95]
	s_waitcnt lgkmcnt(5)
	v_mfma_f32_16x16x32_bf16 v[88:91], v[128:131], v[164:167], v[88:91]
	v_mfma_f32_16x16x32_bf16 v[84:87], v[132:135], v[164:167], v[84:87]
	v_mfma_f32_16x16x32_bf16 v[80:83], v[136:139], v[164:167], v[80:83]
	v_mfma_f32_16x16x32_bf16 v[76:79], v[140:143], v[164:167], v[76:79]
	s_waitcnt lgkmcnt(4)
	v_mfma_f32_16x16x32_bf16 v[72:75], v[128:131], v[160:163], v[72:75]
	v_mfma_f32_16x16x32_bf16 v[68:71], v[132:135], v[160:163], v[68:71]
	v_mfma_f32_16x16x32_bf16 v[64:67], v[136:139], v[160:163], v[64:67]
	v_mfma_f32_16x16x32_bf16 v[60:63], v[140:143], v[160:163], v[60:63]
	s_waitcnt lgkmcnt(3)
	v_mfma_f32_16x16x32_bf16 v[56:59], v[128:131], v[156:159], v[56:59]
	v_mfma_f32_16x16x32_bf16 v[52:55], v[132:135], v[156:159], v[52:55]
	v_mfma_f32_16x16x32_bf16 v[48:51], v[136:139], v[156:159], v[48:51]
	v_mfma_f32_16x16x32_bf16 v[44:47], v[140:143], v[156:159], v[44:47]
	s_waitcnt lgkmcnt(2)
	v_mfma_f32_16x16x32_bf16 v[40:43], v[128:131], v[152:155], v[40:43]
	v_mfma_f32_16x16x32_bf16 v[36:39], v[132:135], v[152:155], v[36:39]
	v_mfma_f32_16x16x32_bf16 v[32:35], v[136:139], v[152:155], v[32:35]
	v_mfma_f32_16x16x32_bf16 v[28:31], v[140:143], v[152:155], v[28:31]
	s_waitcnt lgkmcnt(1)
	v_mfma_f32_16x16x32_bf16 v[24:27], v[128:131], v[148:151], v[24:27]
	v_mfma_f32_16x16x32_bf16 v[20:23], v[132:135], v[148:151], v[20:23]
	v_mfma_f32_16x16x32_bf16 v[16:19], v[136:139], v[148:151], v[16:19]
	v_mfma_f32_16x16x32_bf16 v[12:15], v[140:143], v[148:151], v[12:15]
	s_waitcnt lgkmcnt(0)
	v_mfma_f32_16x16x32_bf16 v[8:11], v[128:131], v[144:147], v[8:11]
	v_mfma_f32_16x16x32_bf16 v[4:7], v[132:135], v[144:147], v[4:7]
	v_mfma_f32_16x16x32_bf16 v[0:3], v[136:139], v[144:147], v[0:3]
	v_mfma_f32_16x16x32_bf16 v[124:127], v[140:143], v[144:147], v[124:127]
	s_setprio 0
	s_add_u32 s6, s6, 64
	s_addc_u32 s7, s7, 0
	s_mov_b32 s30, 1
	s_cmpk_eq_i32 s6, 0x1f40
	s_cbranch_scc1 .LBB0_2312
	s_mov_b32 s8, 0x6000
	s_mov_b32 s9, 0x0
	s_waitcnt vmcnt(0)
	s_barrier
	v_add_u32_e32 v140, s8, v223
	v_add_u32_e32 v144, s8, v222
	ds_read_b128 v[128:131], v140 offset:16384
	ds_read_b128 v[132:135], v140 offset:17408
	ds_read_b128 v[136:139], v140 offset:18432
	ds_read_b128 v[140:143], v140 offset:19456
	ds_read_b128 v[172:175], v144
	ds_read_b128 v[168:171], v144 offset:1024
	ds_read_b128 v[164:167], v144 offset:2048
	ds_read_b128 v[160:163], v144 offset:3072
	ds_read_b128 v[156:159], v144 offset:4096
	ds_read_b128 v[152:155], v144 offset:5120
	ds_read_b128 v[148:151], v144 offset:6144
	ds_read_b128 v[144:147], v144 offset:7168
	s_waitcnt lgkmcnt(0)
	s_barrier
	s_setprio 2
	s_sub_i32 vcc_lo, s8, s9
	v_mfma_f32_16x16x32_bf16 v[120:123], v[128:131], v[172:175], v[120:123]
	v_mfma_f32_16x16x32_bf16 v[116:119], v[132:135], v[172:175], v[116:119]
	v_mfma_f32_16x16x32_bf16 v[112:115], v[136:139], v[172:175], v[112:115]
	v_mfma_f32_16x16x32_bf16 v[108:111], v[140:143], v[172:175], v[108:111]
	v_mfma_f32_16x16x32_bf16 v[104:107], v[128:131], v[168:171], v[104:107]
	v_mfma_f32_16x16x32_bf16 v[100:103], v[132:135], v[168:171], v[100:103]
	v_mfma_f32_16x16x32_bf16 v[96:99], v[136:139], v[168:171], v[96:99]
	v_mfma_f32_16x16x32_bf16 v[92:95], v[140:143], v[168:171], v[92:95]
	v_mfma_f32_16x16x32_bf16 v[88:91], v[128:131], v[164:167], v[88:91]
	v_mfma_f32_16x16x32_bf16 v[84:87], v[132:135], v[164:167], v[84:87]
	v_mfma_f32_16x16x32_bf16 v[80:83], v[136:139], v[164:167], v[80:83]
	v_mfma_f32_16x16x32_bf16 v[76:79], v[140:143], v[164:167], v[76:79]
	v_lshl_add_u64 v[172:173], v[178:179], 0, s[6:7]
	s_add_i32 s31, s9, s26
	s_mov_b32 m0, s31
	v_lshl_add_u64 v[168:169], v[172:173], 0, 64
	global_load_lds_dwordx4 v[172:173], off
	s_add_i32 m0, s31, vcc_lo
	s_nop 0
	global_load_lds_dwordx4 v[168:169], off
	s_mov_b64 s[12:13], 0x20000
	v_lshl_add_u64 v[174:175], v[172:173], 0, s[12:13]
	s_add_i32 s34, s31, 0x400
	s_mov_b32 m0, s34
	v_lshl_add_u64 v[168:169], v[174:175], 0, 64
	global_load_lds_dwordx4 v[174:175], off
	s_add_i32 m0, s34, vcc_lo
	s_nop 0
	global_load_lds_dwordx4 v[168:169], off
	s_mov_b64 s[34:35], 0x40000
	v_lshl_add_u64 v[174:175], v[172:173], 0, s[34:35]
	s_add_i32 s34, s31, 0x800
	s_mov_b32 m0, s34
	v_lshl_add_u64 v[168:169], v[174:175], 0, 64
	global_load_lds_dwordx4 v[174:175], off
	s_add_i32 m0, s34, vcc_lo
	s_nop 0
	global_load_lds_dwordx4 v[168:169], off
	s_mov_b64 s[34:35], 0x60000
	v_lshl_add_u64 v[172:173], v[172:173], 0, s[34:35]
	s_addk_i32 s31, 0xc00
	s_mov_b32 m0, s31
	v_lshl_add_u64 v[168:169], v[172:173], 0, 64
	global_load_lds_dwordx4 v[172:173], off
	s_add_i32 m0, s31, vcc_lo
	s_nop 0
	global_load_lds_dwordx4 v[168:169], off
	v_lshl_add_u64 v[172:173], v[176:177], 0, s[6:7]
	s_add_i32 s9, s9, s27
	s_mov_b32 m0, s9
	v_lshl_add_u64 v[168:169], v[172:173], 0, 64
	global_load_lds_dwordx4 v[172:173], off
	s_add_i32 m0, s9, vcc_lo
	s_nop 0
	global_load_lds_dwordx4 v[168:169], off
	v_lshl_add_u64 v[172:173], v[172:173], 0, s[12:13]
	s_addk_i32 s9, 0x400
	s_mov_b32 m0, s9
	v_lshl_add_u64 v[168:169], v[172:173], 0, 64
	global_load_lds_dwordx4 v[172:173], off
	s_add_i32 m0, s9, vcc_lo
	s_nop 0
	global_load_lds_dwordx4 v[168:169], off
	v_mfma_f32_16x16x32_bf16 v[72:75], v[128:131], v[160:163], v[72:75]
	v_mfma_f32_16x16x32_bf16 v[68:71], v[132:135], v[160:163], v[68:71]
	v_mfma_f32_16x16x32_bf16 v[64:67], v[136:139], v[160:163], v[64:67]
	v_mfma_f32_16x16x32_bf16 v[60:63], v[140:143], v[160:163], v[60:63]
; __device__ __forceinline__ f32x4 mfma16(bf16x8 a, bf16x8 b, f32x4 c) { return __builtin_amdgcn_mfma_f32_16x16x32_bf16(a, b, c, 0, 0, 0); }
; template <int MI, bool SWAP, class Epi> ...
;     ...
;     if (!prefetched) {
;         __syncthreads();
;         RING_STAGE(0, 0);
;         RING_STAGE(1, 32);
;     }
;     int cur = 0;
;     for (int kt = 0; kt < nk; ++kt) {
;         if (kt + 1 < nk && !(prefetched && kt == 0)) { if (MI == 8) asm volatile("s_waitcnt vmcnt(6)\n\ts_barrier" ::: "memory"); else if (MI == 4) asm volatile("s_waitcnt vmcnt(4)\n\ts_barrier" ::: "memory"); else asm volatile("s_waitcnt vmcnt(3)\n\ts_barrier" ::: "memory"); }
;         else asm volatile("s_waitcnt vmcnt(0)\n\ts_barrier" ::: "memory");
;         if (kt + 2 < nk) { const int nx = (cur == 0) ? 2 : cur - 1; RING_STAGE(nx, (kt + 2) * 32); }
;         const int so = cur * STAGEB;
;         bf16x8 bf[4], af[MI];
; #pragma unroll
;         for (int j = 0; j < 4; ++j) bf[j] = *(const bf16x8*)(brdb + so + j * 1024);
; #pragma unroll
;         for (int i = 0; i < MI; ++i) af[i] = *(const bf16x8*)(ardb + so + i * 1024);
;         if (blockIdx.x & 256) __builtin_amdgcn_s_setprio(2); else __builtin_amdgcn_s_setprio(1);
; #pragma unroll
;         for (int i = 0; i < MI; ++i) {
; #pragma unroll
;             for (int j = 0; j < 4; ++j) {
;                 if (SWAP) acc[i][j] = mfma16(bf[j], af[i], acc[i][j]);
;                 else acc[i][j] = mfma16(af[i], bf[j], acc[i][j]);
;             }
;         }
;         __builtin_amdgcn_s_setprio(0);
;         cur = (cur == 2) ? 0 : cur + 1;
;     }
	v_mfma_f32_16x16x32_bf16 v[56:59], v[128:131], v[156:159], v[56:59]
	v_mfma_f32_16x16x32_bf16 v[52:55], v[132:135], v[156:159], v[52:55]
	v_mfma_f32_16x16x32_bf16 v[48:51], v[136:139], v[156:159], v[48:51]
	v_mfma_f32_16x16x32_bf16 v[44:47], v[140:143], v[156:159], v[44:47]
	v_mfma_f32_16x16x32_bf16 v[40:43], v[128:131], v[152:155], v[40:43]
	v_mfma_f32_16x16x32_bf16 v[36:39], v[132:135], v[152:155], v[36:39]
	v_mfma_f32_16x16x32_bf16 v[32:35], v[136:139], v[152:155], v[32:35]
	v_mfma_f32_16x16x32_bf16 v[28:31], v[140:143], v[152:155], v[28:31]
	v_mfma_f32_16x16x32_bf16 v[24:27], v[128:131], v[148:151], v[24:27]
	v_mfma_f32_16x16x32_bf16 v[20:23], v[132:135], v[148:151], v[20:23]
	v_mfma_f32_16x16x32_bf16 v[16:19], v[136:139], v[148:151], v[16:19]
	v_mfma_f32_16x16x32_bf16 v[12:15], v[140:143], v[148:151], v[12:15]
	v_mfma_f32_16x16x32_bf16 v[8:11], v[128:131], v[144:147], v[8:11]
	v_mfma_f32_16x16x32_bf16 v[4:7], v[132:135], v[144:147], v[4:7]
	v_mfma_f32_16x16x32_bf16 v[0:3], v[136:139], v[144:147], v[0:3]
	v_mfma_f32_16x16x32_bf16 v[124:127], v[140:143], v[144:147], v[124:127]
	s_setprio 0
	s_add_u32 s6, s6, 64
	s_addc_u32 s7, s7, 0
	s_mov_b32 s8, 0xc000
	v_add_u32_e32 v140, s8, v223
	v_add_u32_e32 v144, s8, v222
	ds_read_b128 v[128:131], v140 offset:16384
	ds_read_b128 v[132:135], v140 offset:17408
	ds_read_b128 v[136:139], v140 offset:18432
	ds_read_b128 v[140:143], v140 offset:19456
	ds_read_b128 v[172:175], v144
	ds_read_b128 v[168:171], v144 offset:1024
	ds_read_b128 v[164:167], v144 offset:2048
	ds_read_b128 v[160:163], v144 offset:3072
	ds_read_b128 v[156:159], v144 offset:4096
	ds_read_b128 v[152:155], v144 offset:5120
	ds_read_b128 v[148:151], v144 offset:6144
	ds_read_b128 v[144:147], v144 offset:7168
	s_setprio 2
	s_waitcnt lgkmcnt(7)
	v_mfma_f32_16x16x32_bf16 v[120:123], v[128:131], v[172:175], v[120:123]
	v_mfma_f32_16x16x32_bf16 v[116:119], v[132:135], v[172:175], v[116:119]
	v_mfma_f32_16x16x32_bf16 v[112:115], v[136:139], v[172:175], v[112:115]
	v_mfma_f32_16x16x32_bf16 v[108:111], v[140:143], v[172:175], v[108:111]
	s_waitcnt lgkmcnt(6)
	v_mfma_f32_16x16x32_bf16 v[104:107], v[128:131], v[168:171], v[104:107]
	v_mfma_f32_16x16x32_bf16 v[100:103], v[132:135], v[168:171], v[100:103]
	v_mfma_f32_16x16x32_bf16 v[96:99], v[136:139], v[168:171], v[96:99]
	v_mfma_f32_16x16x32_bf16 v[92:95], v[140:143], v[168:171], v[92:95]
	s_waitcnt lgkmcnt(5)
	v_mfma_f32_16x16x32_bf16 v[88:91], v[128:131], v[164:167], v[88:91]
	v_mfma_f32_16x16x32_bf16 v[84:87], v[132:135], v[164:167], v[84:87]
	v_mfma_f32_16x16x32_bf16 v[80:83], v[136:139], v[164:167], v[80:83]
	v_mfma_f32_16x16x32_bf16 v[76:79], v[140:143], v[164:167], v[76:79]
	s_waitcnt lgkmcnt(4)
	v_mfma_f32_16x16x32_bf16 v[72:75], v[128:131], v[160:163], v[72:75]
	v_mfma_f32_16x16x32_bf16 v[68:71], v[132:135], v[160:163], v[68:71]
	v_mfma_f32_16x16x32_bf16 v[64:67], v[136:139], v[160:163], v[64:67]
	v_mfma_f32_16x16x32_bf16 v[60:63], v[140:143], v[160:163], v[60:63]
	s_waitcnt lgkmcnt(3)
	v_mfma_f32_16x16x32_bf16 v[56:59], v[128:131], v[156:159], v[56:59]
	v_mfma_f32_16x16x32_bf16 v[52:55], v[132:135], v[156:159], v[52:55]
	v_mfma_f32_16x16x32_bf16 v[48:51], v[136:139], v[156:159], v[48:51]
	v_mfma_f32_16x16x32_bf16 v[44:47], v[140:143], v[156:159], v[44:47]
	s_waitcnt lgkmcnt(2)
	v_mfma_f32_16x16x32_bf16 v[40:43], v[128:131], v[152:155], v[40:43]
	v_mfma_f32_16x16x32_bf16 v[36:39], v[132:135], v[152:155], v[36:39]
	v_mfma_f32_16x16x32_bf16 v[32:35], v[136:139], v[152:155], v[32:35]
	v_mfma_f32_16x16x32_bf16 v[28:31], v[140:143], v[152:155], v[28:31]
	s_waitcnt lgkmcnt(1)
	v_mfma_f32_16x16x32_bf16 v[24:27], v[128:131], v[148:151], v[24:27]
	v_mfma_f32_16x16x32_bf16 v[20:23], v[132:135], v[148:151], v[20:23]
	v_mfma_f32_16x16x32_bf16 v[16:19], v[136:139], v[148:151], v[16:19]
	v_mfma_f32_16x16x32_bf16 v[12:15], v[140:143], v[148:151], v[12:15]
	s_waitcnt lgkmcnt(0)
	v_mfma_f32_16x16x32_bf16 v[8:11], v[128:131], v[144:147], v[8:11]
	v_mfma_f32_16x16x32_bf16 v[4:7], v[132:135], v[144:147], v[4:7]
	v_mfma_f32_16x16x32_bf16 v[0:3], v[136:139], v[144:147], v[0:3]
	v_mfma_f32_16x16x32_bf16 v[124:127], v[140:143], v[144:147], v[124:127]
	s_setprio 0
	s_add_u32 s6, s6, 64
	s_addc_u32 s7, s7, 0
	s_mov_b32 s30, 0
	s_cmpk_eq_i32 s6, 0x1f40
	s_cbranch_scc1 .LBB0_2312
	s_mov_b32 s8, 0x0
	s_mov_b32 s9, 0xc000
	s_waitcnt vmcnt(0)
	s_barrier
	v_add_u32_e32 v140, s8, v223
	v_add_u32_e32 v144, s8, v222
	ds_read_b128 v[128:131], v140 offset:16384
	ds_read_b128 v[132:135], v140 offset:17408
	ds_read_b128 v[136:139], v140 offset:18432
	ds_read_b128 v[140:143], v140 offset:19456
	ds_read_b128 v[172:175], v144
	ds_read_b128 v[168:171], v144 offset:1024
	ds_read_b128 v[164:167], v144 offset:2048
	ds_read_b128 v[160:163], v144 offset:3072
	ds_read_b128 v[156:159], v144 offset:4096
	ds_read_b128 v[152:155], v144 offset:5120
	ds_read_b128 v[148:151], v144 offset:6144
	ds_read_b128 v[144:147], v144 offset:7168
	s_waitcnt lgkmcnt(0)
	s_barrier
; __device__ __forceinline__ f32x4 mfma16(bf16x8 a, bf16x8 b, f32x4 c) { return __builtin_amdgcn_mfma_f32_16x16x32_bf16(a, b, c, 0, 0, 0); }
; template <int MI, bool SWAP, class Epi> ...
;     ...
;     if (!prefetched) {
;         __syncthreads();
;         RING_STAGE(0, 0);
;         RING_STAGE(1, 32);
;     }
;     int cur = 0;
;     for (int kt = 0; kt < nk; ++kt) {
;         if (kt + 1 < nk && !(prefetched && kt == 0)) { if (MI == 8) asm volatile("s_waitcnt vmcnt(6)\n\ts_barrier" ::: "memory"); else if (MI == 4) asm volatile("s_waitcnt vmcnt(4)\n\ts_barrier" ::: "memory"); else asm volatile("s_waitcnt vmcnt(3)\n\ts_barrier" ::: "memory"); }
;         else asm volatile("s_waitcnt vmcnt(0)\n\ts_barrier" ::: "memory");
;         if (kt + 2 < nk) { const int nx = (cur == 0) ? 2 : cur - 1; RING_STAGE(nx, (kt + 2) * 32); }
;         const int so = cur * STAGEB;
;         bf16x8 bf[4], af[MI];
; #pragma unroll
;         for (int j = 0; j < 4; ++j) bf[j] = *(const bf16x8*)(brdb + so + j * 1024);
; #pragma unroll
;         for (int i = 0; i < MI; ++i) af[i] = *(const bf16x8*)(ardb + so + i * 1024);
;         if (blockIdx.x & 256) __builtin_amdgcn_s_setprio(2); else __builtin_amdgcn_s_setprio(1);
; #pragma unroll
;         for (int i = 0; i < MI; ++i) {
; #pragma unroll
;             for (int j = 0; j < 4; ++j) {
;                 if (SWAP) acc[i][j] = mfma16(bf[j], af[i], acc[i][j]);
;                 else acc[i][j] = mfma16(af[i], bf[j], acc[i][j]);
;             }
;         }
;         __builtin_amdgcn_s_setprio(0);
;         cur = (cur == 2) ? 0 : cur + 1;
;     }
	s_setprio 2
	s_sub_i32 vcc_lo, s8, s9
	v_mfma_f32_16x16x32_bf16 v[120:123], v[128:131], v[172:175], v[120:123]
	v_mfma_f32_16x16x32_bf16 v[116:119], v[132:135], v[172:175], v[116:119]
	v_mfma_f32_16x16x32_bf16 v[112:115], v[136:139], v[172:175], v[112:115]
	v_mfma_f32_16x16x32_bf16 v[108:111], v[140:143], v[172:175], v[108:111]
	v_mfma_f32_16x16x32_bf16 v[104:107], v[128:131], v[168:171], v[104:107]
	v_mfma_f32_16x16x32_bf16 v[100:103], v[132:135], v[168:171], v[100:103]
	v_mfma_f32_16x16x32_bf16 v[96:99], v[136:139], v[168:171], v[96:99]
	v_mfma_f32_16x16x32_bf16 v[92:95], v[140:143], v[168:171], v[92:95]
	v_mfma_f32_16x16x32_bf16 v[88:91], v[128:131], v[164:167], v[88:91]
	v_mfma_f32_16x16x32_bf16 v[84:87], v[132:135], v[164:167], v[84:87]
	v_mfma_f32_16x16x32_bf16 v[80:83], v[136:139], v[164:167], v[80:83]
	v_mfma_f32_16x16x32_bf16 v[76:79], v[140:143], v[164:167], v[76:79]
	v_lshl_add_u64 v[172:173], v[178:179], 0, s[6:7]
	s_add_i32 s31, s9, s26
	s_mov_b32 m0, s31
	v_lshl_add_u64 v[168:169], v[172:173], 0, 64
	global_load_lds_dwordx4 v[172:173], off
	s_add_i32 m0, s31, vcc_lo
	s_nop 0
	global_load_lds_dwordx4 v[168:169], off
	s_mov_b64 s[12:13], 0x20000
	v_lshl_add_u64 v[174:175], v[172:173], 0, s[12:13]
	s_add_i32 s34, s31, 0x400
	s_mov_b32 m0, s34
	v_lshl_add_u64 v[168:169], v[174:175], 0, 64
	global_load_lds_dwordx4 v[174:175], off
	s_add_i32 m0, s34, vcc_lo
	s_nop 0
	global_load_lds_dwordx4 v[168:169], off
	s_mov_b64 s[34:35], 0x40000
	v_lshl_add_u64 v[174:175], v[172:173], 0, s[34:35]
	s_add_i32 s34, s31, 0x800
	s_mov_b32 m0, s34
	v_lshl_add_u64 v[168:169], v[174:175], 0, 64
	global_load_lds_dwordx4 v[174:175], off
	s_add_i32 m0, s34, vcc_lo
	s_nop 0
	global_load_lds_dwordx4 v[168:169], off
	s_mov_b64 s[34:35], 0x60000
	v_lshl_add_u64 v[172:173], v[172:173], 0, s[34:35]
	s_addk_i32 s31, 0xc00
	s_mov_b32 m0, s31
	v_lshl_add_u64 v[168:169], v[172:173], 0, 64
	global_load_lds_dwordx4 v[172:173], off
	s_add_i32 m0, s31, vcc_lo
	s_nop 0
	global_load_lds_dwordx4 v[168:169], off
	v_lshl_add_u64 v[172:173], v[176:177], 0, s[6:7]
	s_add_i32 s9, s9, s27
	s_mov_b32 m0, s9
	v_lshl_add_u64 v[168:169], v[172:173], 0, 64
	global_load_lds_dwordx4 v[172:173], off
	s_add_i32 m0, s9, vcc_lo
	s_nop 0
	global_load_lds_dwordx4 v[168:169], off
	v_lshl_add_u64 v[172:173], v[172:173], 0, s[12:13]
	s_addk_i32 s9, 0x400
	s_mov_b32 m0, s9
	v_lshl_add_u64 v[168:169], v[172:173], 0, 64
	global_load_lds_dwordx4 v[172:173], off
	s_add_i32 m0, s9, vcc_lo
	s_nop 0
	global_load_lds_dwordx4 v[168:169], off
	v_mfma_f32_16x16x32_bf16 v[72:75], v[128:131], v[160:163], v[72:75]
	v_mfma_f32_16x16x32_bf16 v[68:71], v[132:135], v[160:163], v[68:71]
	v_mfma_f32_16x16x32_bf16 v[64:67], v[136:139], v[160:163], v[64:67]
	v_mfma_f32_16x16x32_bf16 v[60:63], v[140:143], v[160:163], v[60:63]
	v_mfma_f32_16x16x32_bf16 v[56:59], v[128:131], v[156:159], v[56:59]
	v_mfma_f32_16x16x32_bf16 v[52:55], v[132:135], v[156:159], v[52:55]
	v_mfma_f32_16x16x32_bf16 v[48:51], v[136:139], v[156:159], v[48:51]
	v_mfma_f32_16x16x32_bf16 v[44:47], v[140:143], v[156:159], v[44:47]
	v_mfma_f32_16x16x32_bf16 v[40:43], v[128:131], v[152:155], v[40:43]
	v_mfma_f32_16x16x32_bf16 v[36:39], v[132:135], v[152:155], v[36:39]
	v_mfma_f32_16x16x32_bf16 v[32:35], v[136:139], v[152:155], v[32:35]
	v_mfma_f32_16x16x32_bf16 v[28:31], v[140:143], v[152:155], v[28:31]
	v_mfma_f32_16x16x32_bf16 v[24:27], v[128:131], v[148:151], v[24:27]
	v_mfma_f32_16x16x32_bf16 v[20:23], v[132:135], v[148:151], v[20:23]
	v_mfma_f32_16x16x32_bf16 v[16:19], v[136:139], v[148:151], v[16:19]
	v_mfma_f32_16x16x32_bf16 v[12:15], v[140:143], v[148:151], v[12:15]
	v_mfma_f32_16x16x32_bf16 v[8:11], v[128:131], v[144:147], v[8:11]
	v_mfma_f32_16x16x32_bf16 v[4:7], v[132:135], v[144:147], v[4:7]
	v_mfma_f32_16x16x32_bf16 v[0:3], v[136:139], v[144:147], v[0:3]
	v_mfma_f32_16x16x32_bf16 v[124:127], v[140:143], v[144:147], v[124:127]
	s_setprio 0
	s_add_u32 s6, s6, 64
	s_addc_u32 s7, s7, 0
	s_mov_b32 s8, 0x6000
	v_add_u32_e32 v140, s8, v223
	v_add_u32_e32 v144, s8, v222
	ds_read_b128 v[128:131], v140 offset:16384
	ds_read_b128 v[132:135], v140 offset:17408
	ds_read_b128 v[136:139], v140 offset:18432
	ds_read_b128 v[140:143], v140 offset:19456
	ds_read_b128 v[172:175], v144
	ds_read_b128 v[168:171], v144 offset:1024
	ds_read_b128 v[164:167], v144 offset:2048
	ds_read_b128 v[160:163], v144 offset:3072
	ds_read_b128 v[156:159], v144 offset:4096
	ds_read_b128 v[152:155], v144 offset:5120
	ds_read_b128 v[148:151], v144 offset:6144
	ds_read_b128 v[144:147], v144 offset:7168
	s_setprio 2
	s_waitcnt lgkmcnt(7)
; __device__ __forceinline__ f32x4 mfma16(bf16x8 a, bf16x8 b, f32x4 c) { return __builtin_amdgcn_mfma_f32_16x16x32_bf16(a, b, c, 0, 0, 0); }
; template <int MI, bool SWAP, class Epi> ...
;     ...
;     for (int kt = 0; kt < nk; ++kt) {
;         if (kt + 1 < nk && !(prefetched && kt == 0)) { if (MI == 8) asm volatile("s_waitcnt vmcnt(6)\n\ts_barrier" ::: "memory"); else if (MI == 4) asm volatile("s_waitcnt vmcnt(4)\n\ts_barrier" ::: "memory"); else asm volatile("s_waitcnt vmcnt(3)\n\ts_barrier" ::: "memory"); }
;         else asm volatile("s_waitcnt vmcnt(0)\n\ts_barrier" ::: "memory");
;         if (kt + 2 < nk) { const int nx = (cur == 0) ? 2 : cur - 1; RING_STAGE(nx, (kt + 2) * 32); }
;         const int so = cur * STAGEB;
;         bf16x8 bf[4], af[MI];
; #pragma unroll
;         for (int j = 0; j < 4; ++j) bf[j] = *(const bf16x8*)(brdb + so + j * 1024);
; #pragma unroll
;         for (int i = 0; i < MI; ++i) af[i] = *(const bf16x8*)(ardb + so + i * 1024);
;         if (blockIdx.x & 256) __builtin_amdgcn_s_setprio(2); else __builtin_amdgcn_s_setprio(1);
; #pragma unroll
;         for (int i = 0; i < MI; ++i) {
; #pragma unroll
;             for (int j = 0; j < 4; ++j) {
;                 if (SWAP) acc[i][j] = mfma16(bf[j], af[i], acc[i][j]);
;                 else acc[i][j] = mfma16(af[i], bf[j], acc[i][j]);
;             }
;         }
;         __builtin_amdgcn_s_setprio(0);
;         cur = (cur == 2) ? 0 : cur + 1;
;     }
	v_mfma_f32_16x16x32_bf16 v[120:123], v[128:131], v[172:175], v[120:123]
	v_mfma_f32_16x16x32_bf16 v[116:119], v[132:135], v[172:175], v[116:119]
	v_mfma_f32_16x16x32_bf16 v[112:115], v[136:139], v[172:175], v[112:115]
	v_mfma_f32_16x16x32_bf16 v[108:111], v[140:143], v[172:175], v[108:111]
	s_waitcnt lgkmcnt(6)
	v_mfma_f32_16x16x32_bf16 v[104:107], v[128:131], v[168:171], v[104:107]
	v_mfma_f32_16x16x32_bf16 v[100:103], v[132:135], v[168:171], v[100:103]
	v_mfma_f32_16x16x32_bf16 v[96:99], v[136:139], v[168:171], v[96:99]
	v_mfma_f32_16x16x32_bf16 v[92:95], v[140:143], v[168:171], v[92:95]
	s_waitcnt lgkmcnt(5)
	v_mfma_f32_16x16x32_bf16 v[88:91], v[128:131], v[164:167], v[88:91]
	v_mfma_f32_16x16x32_bf16 v[84:87], v[132:135], v[164:167], v[84:87]
	v_mfma_f32_16x16x32_bf16 v[80:83], v[136:139], v[164:167], v[80:83]
	v_mfma_f32_16x16x32_bf16 v[76:79], v[140:143], v[164:167], v[76:79]
	s_waitcnt lgkmcnt(4)
	v_mfma_f32_16x16x32_bf16 v[72:75], v[128:131], v[160:163], v[72:75]
	v_mfma_f32_16x16x32_bf16 v[68:71], v[132:135], v[160:163], v[68:71]
	v_mfma_f32_16x16x32_bf16 v[64:67], v[136:139], v[160:163], v[64:67]
	v_mfma_f32_16x16x32_bf16 v[60:63], v[140:143], v[160:163], v[60:63]
	s_waitcnt lgkmcnt(3)
	v_mfma_f32_16x16x32_bf16 v[56:59], v[128:131], v[156:159], v[56:59]
	v_mfma_f32_16x16x32_bf16 v[52:55], v[132:135], v[156:159], v[52:55]
	v_mfma_f32_16x16x32_bf16 v[48:51], v[136:139], v[156:159], v[48:51]
	v_mfma_f32_16x16x32_bf16 v[44:47], v[140:143], v[156:159], v[44:47]
	s_waitcnt lgkmcnt(2)
	v_mfma_f32_16x16x32_bf16 v[40:43], v[128:131], v[152:155], v[40:43]
	v_mfma_f32_16x16x32_bf16 v[36:39], v[132:135], v[152:155], v[36:39]
	v_mfma_f32_16x16x32_bf16 v[32:35], v[136:139], v[152:155], v[32:35]
	v_mfma_f32_16x16x32_bf16 v[28:31], v[140:143], v[152:155], v[28:31]
	s_waitcnt lgkmcnt(1)
	v_mfma_f32_16x16x32_bf16 v[24:27], v[128:131], v[148:151], v[24:27]
	v_mfma_f32_16x16x32_bf16 v[20:23], v[132:135], v[148:151], v[20:23]
	v_mfma_f32_16x16x32_bf16 v[16:19], v[136:139], v[148:151], v[16:19]
	v_mfma_f32_16x16x32_bf16 v[12:15], v[140:143], v[148:151], v[12:15]
	s_waitcnt lgkmcnt(0)
	v_mfma_f32_16x16x32_bf16 v[8:11], v[128:131], v[144:147], v[8:11]
	v_mfma_f32_16x16x32_bf16 v[4:7], v[132:135], v[144:147], v[4:7]
	v_mfma_f32_16x16x32_bf16 v[0:3], v[136:139], v[144:147], v[0:3]
	v_mfma_f32_16x16x32_bf16 v[124:127], v[140:143], v[144:147], v[124:127]
	s_setprio 0
	s_add_u32 s6, s6, 64
	s_addc_u32 s7, s7, 0
	s_mov_b32 s30, 2
	s_cmpk_eq_i32 s6, 0x1f40
	s_cbranch_scc1 .LBB0_2312
	s_branch .Lru_loop_ff2
